# FFN epilogues: next tile's row sums of squares prefetched into a per-wave LDS slot by LDS-DMA during the current epilogue
# baseline (speedup 1.0000x reference)
.LBB0_358:
	s_mov_b64 s[14:15], 0x80
	s_lshl_b32 s1, s10, 5
	s_add_i32 m0, s44, 0x18000
	v_lshl_add_u64 v[6:7], v[6:7], 0, s[14:15]
	s_and_b32 s49, s1, 0x60
	s_waitcnt vmcnt(4)
	s_barrier
	global_load_lds_dwordx4 v[6:7], off
	v_lshl_add_u64 v[4:5], v[4:5], 0, s[14:15]
	s_add_i32 m0, s44, 0x1a000
	s_add_i32 s52, s44, 0x8000
	s_add_i32 s53, s44, 0xa000
	global_load_lds_dwordx4 v[4:5], off
	v_lshl_add_u64 v[2:3], v[2:3], 0, s[14:15]
	s_mov_b32 m0, s52
	s_add_u32 s10, s8, 0x1600080
	global_load_lds_dwordx4 v[2:3], off
	v_lshl_add_u64 v[0:1], v[0:1], 0, s[14:15]
	s_mov_b32 m0, s53
	s_addc_u32 s11, s9, 0
	global_load_lds_dwordx4 v[0:1], off
	s_add_i32 m0, s44, 0x1c000
	v_lshl_add_u64 v[0:1], s[10:11], 0, v[164:165]
	global_load_lds_dwordx4 v[0:1], off
	v_lshl_add_u64 v[0:1], s[10:11], 0, v[166:167]
	s_add_i32 m0, s44, 0x1e000
	s_ashr_i32 s54, s94, 31
	global_load_lds_dwordx4 v[0:1], off
	s_lshl_b32 s56, s5, 7
	s_lshl_b32 s57, s5, 2
	s_add_u32 s16, s82, 0xb000
	s_addc_u32 s17, s83, 0
	s_add_u32 s18, s82, 0x16000
	s_addc_u32 s19, s83, 0
	s_add_u32 s20, s82, 0x5800
	s_addc_u32 s21, s83, 0
	s_add_u32 s22, s82, 0x10800
	v_add3_u32 v0, v9, v221, v218
	s_addc_u32 s23, s83, 0
	v_lshl_or_b32 v0, v0, 12, v226
	s_sext_i32_i16 s1, s4
	v_lshl_or_b32 v2, s5, 13, v230
	s_add_u32 s24, s82, 0x1b800
	v_add_u32_e32 v0, v0, v224
	v_mov_b32_e32 v1, v165
	s_mov_b64 s[4:5], 0x40080
	s_addc_u32 s25, s83, 0
	v_add3_u32 v0, v8, v220, v218
	s_waitcnt vmcnt(6)
	s_add_u32 s26, s84, 0x5800
	v_lshl_or_b32 v0, v0, 12, v226
	s_addc_u32 s27, s85, 0
	v_add_u32_e32 v0, v0, v224
	s_add_i32 s58, 0, 0x10000
	s_add_i32 s59, 0, 0x14000
	s_mov_b32 s55, s94
	v_mov_b64_e32 v[176:177], 0xb00
	v_mov_b64_e32 v[178:179], 0xaff
	v_mov_b32_e32 v243, 0x3727c5ac
	s_mov_b32 s60, 0xb000
	s_movk_i32 s61, 0x2c00
	s_barrier
	s_mov_b32 s98, 0
	s_branch .LBB0_360

.LBB0_363:
	ds_read_b128 v[76:79], v231
	v_xor_b32_e32 v91, 64, v231
	ds_read_b128 v[80:83], v91
	ds_read_b128 v[84:87], v231 offset:2048
	ds_read_b128 v[88:91], v91 offset:2048
	s_add_u32 s8, s6, 0x100
	s_addc_u32 s9, s7, 0
	s_cmp_eq_u32 s65, 28
	s_cselect_b32 s39, s31, s9
	s_cselect_b32 s38, s33, s8
	s_cselect_b32 s11, s29, s64
	s_cselect_b32 s10, s62, s63
	v_lshl_add_u64 v[108:109], s[6:7], 0, v[172:173]
	s_add_i32 m0, s44, 0xc000
	ds_read_b128 v[92:95], v241
	v_xor_b32_e32 v195, 64, v241
	ds_read_b128 v[96:99], v195
	ds_read_b128 v[100:103], v241 offset:2048
	ds_read_b128 v[104:107], v195 offset:2048
	ds_read_b128 v[180:183], v241 offset:4096
	ds_read_b128 v[184:187], v195 offset:4096
	ds_read_b128 v[188:191], v241 offset:6144
	ds_read_b128 v[192:195], v195 offset:6144
	global_load_lds_dwordx4 v[108:109], off
	v_lshl_add_u64 v[108:109], s[6:7], 0, v[174:175]
	s_add_i32 m0, s44, 0xe000
	s_nop 0
	global_load_lds_dwordx4 v[108:109], off
	s_waitcnt lgkmcnt(8)
	s_barrier
	s_waitcnt lgkmcnt(0)
	s_setprio 1
	s_waitcnt lgkmcnt(0)
	v_mfma_f32_16x16x32_bf16 v[158:161], v[76:79], v[92:95], v[158:161]
	v_mfma_f32_16x16x32_bf16 v[158:161], v[80:83], v[96:99], v[158:161]
	v_mfma_f32_16x16x32_bf16 v[60:63], v[88:91], v[96:99], v[60:63]
	v_mfma_f32_16x16x32_bf16 v[60:63], v[84:87], v[92:95], v[60:63]
	v_mfma_f32_16x16x32_bf16 v[52:55], v[84:87], v[100:103], v[52:55]
	v_mfma_f32_16x16x32_bf16 v[52:55], v[88:91], v[104:107], v[52:55]
	v_mfma_f32_16x16x32_bf16 v[150:153], v[80:83], v[104:107], v[150:153]
	v_mfma_f32_16x16x32_bf16 v[150:153], v[76:79], v[100:103], v[150:153]
	v_mfma_f32_16x16x32_bf16 v[146:149], v[76:79], v[180:183], v[146:149]
	v_mfma_f32_16x16x32_bf16 v[146:149], v[80:83], v[184:187], v[146:149]
	v_mfma_f32_16x16x32_bf16 v[48:51], v[88:91], v[184:187], v[48:51]
	v_mfma_f32_16x16x32_bf16 v[48:51], v[84:87], v[180:183], v[48:51]
	v_mfma_f32_16x16x32_bf16 v[40:43], v[84:87], v[188:191], v[40:43]
	v_mfma_f32_16x16x32_bf16 v[40:43], v[88:91], v[192:195], v[40:43]
	v_mfma_f32_16x16x32_bf16 v[138:141], v[80:83], v[192:195], v[138:141]
	v_mfma_f32_16x16x32_bf16 v[138:141], v[76:79], v[188:191], v[138:141]
	s_setprio 0
	s_barrier
	s_add_i32 s6, s58, s42
	v_lshl_add_u64 v[216:217], s[10:11], 0, v[164:165]
	s_mov_b32 m0, s6
	ds_read_b128 v[196:199], v242
	v_xor_b32_e32 v211, 64, v242
	ds_read_b128 v[200:203], v211
	ds_read_b128 v[204:207], v242 offset:2048
	ds_read_b128 v[208:211], v211 offset:2048
	global_load_lds_dwordx4 v[216:217], off
	v_lshl_add_u64 v[244:245], s[10:11], 0, v[166:167]
	s_add_i32 m0, s6, 0x2000
	s_nop 0
	global_load_lds_dwordx4 v[244:245], off
	s_barrier
	s_waitcnt lgkmcnt(0)
	s_setprio 1
	s_waitcnt lgkmcnt(0)
	v_mfma_f32_16x16x32_bf16 v[154:157], v[196:199], v[92:95], v[154:157]
	v_mfma_f32_16x16x32_bf16 v[154:157], v[200:203], v[96:99], v[154:157]
	v_mfma_f32_16x16x32_bf16 v[56:59], v[208:211], v[96:99], v[56:59]
	v_mfma_f32_16x16x32_bf16 v[56:59], v[204:207], v[92:95], v[56:59]
	v_mfma_f32_16x16x32_bf16 v[44:47], v[204:207], v[100:103], v[44:47]
	v_mfma_f32_16x16x32_bf16 v[44:47], v[208:211], v[104:107], v[44:47]
	v_mfma_f32_16x16x32_bf16 v[36:39], v[208:211], v[184:187], v[36:39]
	v_mfma_f32_16x16x32_bf16 v[36:39], v[204:207], v[180:183], v[36:39]
	v_mfma_f32_16x16x32_bf16 v[32:35], v[204:207], v[188:191], v[32:35]
	v_mfma_f32_16x16x32_bf16 v[32:35], v[208:211], v[192:195], v[32:35]
	v_mfma_f32_16x16x32_bf16 v[92:95], v[196:199], v[100:103], v[142:145]
	v_mfma_f32_16x16x32_bf16 v[92:95], v[200:203], v[104:107], v[92:95]
	v_mfma_f32_16x16x32_bf16 v[96:99], v[200:203], v[184:187], v[134:137]
	v_mfma_f32_16x16x32_bf16 v[96:99], v[196:199], v[180:183], v[96:99]
	v_mfma_f32_16x16x32_bf16 v[100:103], v[196:199], v[188:191], v[130:133]
	v_mfma_f32_16x16x32_bf16 v[100:103], v[200:203], v[192:195], v[100:103]
	s_setprio 0
	s_mov_b32 m0, s44
	v_lshl_add_u64 v[246:247], s[38:39], 0, v[170:171]
	s_barrier
	ds_read_b128 v[104:107], v241 offset:16384
	v_xor_b32_e32 v195, 64, v241
	ds_read_b128 v[130:133], v195 offset:16384
	ds_read_b128 v[134:137], v241 offset:18432
	ds_read_b128 v[142:145], v195 offset:18432
	ds_read_b128 v[180:183], v241 offset:20480
	ds_read_b128 v[184:187], v195 offset:20480
	ds_read_b128 v[188:191], v241 offset:22528
	ds_read_b128 v[192:195], v195 offset:22528
	global_load_lds_dwordx4 v[246:247], off
	v_lshl_add_u64 v[248:249], s[38:39], 0, v[168:169]
	s_mov_b32 m0, s45
	s_nop 0
	global_load_lds_dwordx4 v[248:249], off
	s_barrier
	s_waitcnt lgkmcnt(0)
	s_setprio 1
	s_waitcnt lgkmcnt(0)
	v_mfma_f32_16x16x32_bf16 v[126:129], v[76:79], v[104:107], v[126:129]
	v_mfma_f32_16x16x32_bf16 v[126:129], v[80:83], v[130:133], v[126:129]
	v_mfma_f32_16x16x32_bf16 v[28:31], v[88:91], v[130:133], v[28:31]
	v_mfma_f32_16x16x32_bf16 v[28:31], v[84:87], v[104:107], v[28:31]
	v_mfma_f32_16x16x32_bf16 v[24:27], v[84:87], v[134:137], v[24:27]
	v_mfma_f32_16x16x32_bf16 v[24:27], v[88:91], v[142:145], v[24:27]
	v_mfma_f32_16x16x32_bf16 v[122:125], v[80:83], v[142:145], v[122:125]
	v_mfma_f32_16x16x32_bf16 v[122:125], v[76:79], v[134:137], v[122:125]
	v_mfma_f32_16x16x32_bf16 v[114:117], v[76:79], v[180:183], v[114:117]
	v_mfma_f32_16x16x32_bf16 v[114:117], v[80:83], v[184:187], v[114:117]
	v_mfma_f32_16x16x32_bf16 v[20:23], v[88:91], v[184:187], v[20:23]
	v_mfma_f32_16x16x32_bf16 v[20:23], v[84:87], v[180:183], v[20:23]
	v_mfma_f32_16x16x32_bf16 v[4:7], v[84:87], v[188:191], v[4:7]
	v_mfma_f32_16x16x32_bf16 v[4:7], v[88:91], v[192:195], v[4:7]
	v_mfma_f32_16x16x32_bf16 v[72:75], v[80:83], v[192:195], v[72:75]
	v_mfma_f32_16x16x32_bf16 v[72:75], v[76:79], v[188:191], v[72:75]
	s_setprio 0
	s_barrier
	s_add_u32 s6, s10, 0x1600000
	s_addc_u32 s7, s11, 0
	s_add_i32 s66, s59, s42
	v_lshl_add_u64 v[76:77], s[6:7], 0, v[164:165]
	s_mov_b32 m0, s66
	s_nop 0
	global_load_lds_dwordx4 v[76:77], off
	v_lshl_add_u64 v[76:77], s[6:7], 0, v[166:167]
	s_add_i32 m0, s66, 0x2000
	s_nop 0
	global_load_lds_dwordx4 v[76:77], off
	s_waitcnt vmcnt(6)
	s_barrier
	s_setprio 1
	v_mfma_f32_16x16x32_bf16 v[16:19], v[204:207], v[104:107], v[16:19]
	v_mfma_f32_16x16x32_bf16 v[16:19], v[208:211], v[130:133], v[16:19]
	v_mfma_f32_16x16x32_bf16 v[12:15], v[208:211], v[142:145], v[12:15]
	v_mfma_f32_16x16x32_bf16 v[12:15], v[204:207], v[134:137], v[12:15]
	v_mfma_f32_16x16x32_bf16 v[8:11], v[204:207], v[180:183], v[8:11]
	v_mfma_f32_16x16x32_bf16 v[8:11], v[208:211], v[184:187], v[8:11]
	v_mfma_f32_16x16x32_bf16 v[68:71], v[200:203], v[184:187], v[68:71]
	v_mfma_f32_16x16x32_bf16 v[68:71], v[196:199], v[180:183], v[68:71]
	v_mfma_f32_16x16x32_bf16 v[64:67], v[196:199], v[188:191], v[64:67]
	v_mfma_f32_16x16x32_bf16 v[64:67], v[200:203], v[192:195], v[64:67]
	v_mfma_f32_16x16x32_bf16 v[0:3], v[208:211], v[192:195], v[0:3]
	v_mfma_f32_16x16x32_bf16 v[0:3], v[204:207], v[188:191], v[0:3]
	v_mfma_f32_16x16x32_bf16 v[76:79], v[196:199], v[104:107], v[118:121]
	v_mfma_f32_16x16x32_bf16 v[76:79], v[200:203], v[130:133], v[76:79]
	v_mfma_f32_16x16x32_bf16 v[80:83], v[200:203], v[142:145], v[110:113]
	v_mfma_f32_16x16x32_bf16 v[80:83], v[196:199], v[134:137], v[80:83]
	s_setprio 0
	s_add_i32 s66, 0, 0x18000
	v_add_u32_e32 v108, s66, v229
	s_barrier
	ds_read_b128 v[84:87], v108
	v_xor_b32_e32 v111, 64, v108
	ds_read_b128 v[88:91], v111
	ds_read_b128 v[104:107], v108 offset:2048
	ds_read_b128 v[108:111], v111 offset:2048
	s_add_u32 s6, s38, 0x40000
	s_addc_u32 s7, s39, 0
	s_mov_b32 m0, s46
	v_lshl_add_u64 v[112:113], s[6:7], 0, v[170:171]
	ds_read_b128 v[118:121], v241 offset:32768
	v_xor_b32_e32 v199, 64, v241
	ds_read_b128 v[130:133], v199 offset:32768
	ds_read_b128 v[134:137], v241 offset:34816
	ds_read_b128 v[180:183], v199 offset:34816
	ds_read_b128 v[184:187], v241 offset:36864
	ds_read_b128 v[188:191], v199 offset:36864
	ds_read_b128 v[192:195], v241 offset:38912
	ds_read_b128 v[196:199], v199 offset:38912
	global_load_lds_dwordx4 v[112:113], off
	v_lshl_add_u64 v[112:113], s[6:7], 0, v[168:169]
	s_mov_b32 m0, s47
	s_nop 0
	global_load_lds_dwordx4 v[112:113], off
	s_waitcnt lgkmcnt(8)
	s_barrier
	s_waitcnt lgkmcnt(0)
	s_setprio 1
	s_waitcnt lgkmcnt(0)
	v_mfma_f32_16x16x32_bf16 v[142:145], v[84:87], v[118:121], v[158:161]
	v_mfma_f32_16x16x32_bf16 v[158:161], v[88:91], v[130:133], v[142:145]
	v_mfma_f32_16x16x32_bf16 v[60:63], v[108:111], v[130:133], v[60:63]
	v_mfma_f32_16x16x32_bf16 v[60:63], v[104:107], v[118:121], v[60:63]
	v_mfma_f32_16x16x32_bf16 v[52:55], v[104:107], v[134:137], v[52:55]
	v_mfma_f32_16x16x32_bf16 v[52:55], v[108:111], v[180:183], v[52:55]
	v_mfma_f32_16x16x32_bf16 v[48:51], v[108:111], v[188:191], v[48:51]
	v_mfma_f32_16x16x32_bf16 v[48:51], v[104:107], v[184:187], v[48:51]
	v_mfma_f32_16x16x32_bf16 v[40:43], v[104:107], v[192:195], v[40:43]
	v_mfma_f32_16x16x32_bf16 v[40:43], v[108:111], v[196:199], v[40:43]
	v_mfma_f32_16x16x32_bf16 v[138:141], v[88:91], v[196:199], v[138:141]
	v_mfma_f32_16x16x32_bf16 v[138:141], v[84:87], v[192:195], v[138:141]
	v_mfma_f32_16x16x32_bf16 v[142:145], v[84:87], v[134:137], v[150:153]
	v_mfma_f32_16x16x32_bf16 v[150:153], v[88:91], v[180:183], v[142:145]
	v_mfma_f32_16x16x32_bf16 v[142:145], v[84:87], v[184:187], v[146:149]
	v_mfma_f32_16x16x32_bf16 v[146:149], v[88:91], v[188:191], v[142:145]
	s_setprio 0
	s_barrier
	s_add_i32 s38, 0, 0x1c000
	v_add_u32_e32 v112, s38, v229
	s_add_i32 s6, s66, s42
	ds_read_b128 v[200:203], v112
	v_xor_b32_e32 v215, 64, v112
	ds_read_b128 v[204:207], v215
	ds_read_b128 v[208:211], v112 offset:2048
	ds_read_b128 v[212:215], v215 offset:2048
	v_lshl_add_u64 v[112:113], v[216:217], 0, s[14:15]
	s_mov_b32 m0, s6
	s_nop 0
	global_load_lds_dwordx4 v[112:113], off
	v_lshl_add_u64 v[112:113], v[244:245], 0, s[14:15]
	s_add_i32 m0, s6, 0x2000
	s_nop 0
	global_load_lds_dwordx4 v[112:113], off
	s_barrier
	s_waitcnt lgkmcnt(0)
	s_setprio 1
	s_waitcnt lgkmcnt(0)
	v_mfma_f32_16x16x32_bf16 v[142:145], v[200:203], v[118:121], v[154:157]
	v_mfma_f32_16x16x32_bf16 v[154:157], v[204:207], v[130:133], v[142:145]
	v_mfma_f32_16x16x32_bf16 v[56:59], v[212:215], v[130:133], v[56:59]
	v_mfma_f32_16x16x32_bf16 v[56:59], v[208:211], v[118:121], v[56:59]
	v_mfma_f32_16x16x32_bf16 v[44:47], v[208:211], v[134:137], v[44:47]
	v_mfma_f32_16x16x32_bf16 v[44:47], v[212:215], v[180:183], v[44:47]
	v_mfma_f32_16x16x32_bf16 v[36:39], v[212:215], v[188:191], v[36:39]
	v_mfma_f32_16x16x32_bf16 v[36:39], v[208:211], v[184:187], v[36:39]
	v_mfma_f32_16x16x32_bf16 v[32:35], v[208:211], v[192:195], v[32:35]
	v_mfma_f32_16x16x32_bf16 v[32:35], v[212:215], v[196:199], v[32:35]
	v_mfma_f32_16x16x32_bf16 v[92:95], v[200:203], v[134:137], v[92:95]
	v_mfma_f32_16x16x32_bf16 v[142:145], v[204:207], v[180:183], v[92:95]
	v_mfma_f32_16x16x32_bf16 v[92:95], v[200:203], v[184:187], v[96:99]
	v_mfma_f32_16x16x32_bf16 v[134:137], v[204:207], v[188:191], v[92:95]
	v_mfma_f32_16x16x32_bf16 v[92:95], v[200:203], v[192:195], v[100:103]
	v_mfma_f32_16x16x32_bf16 v[130:133], v[204:207], v[196:199], v[92:95]
	s_setprio 0
	s_mov_b32 m0, s52
	v_lshl_add_u64 v[112:113], v[246:247], 0, s[14:15]
	s_barrier
	ds_read_b128 v[92:95], v241 offset:49152
	v_xor_b32_e32 v199, 64, v241
	ds_read_b128 v[96:99], v199 offset:49152
	ds_read_b128 v[100:103], v241 offset:51200
	ds_read_b128 v[180:183], v199 offset:51200
	ds_read_b128 v[184:187], v241 offset:53248
	ds_read_b128 v[188:191], v199 offset:53248
	ds_read_b128 v[192:195], v241 offset:55296
	ds_read_b128 v[196:199], v199 offset:55296
	global_load_lds_dwordx4 v[112:113], off
	v_lshl_add_u64 v[112:113], v[248:249], 0, s[14:15]
	s_mov_b32 m0, s53
	s_nop 0
	global_load_lds_dwordx4 v[112:113], off
	s_barrier
	s_waitcnt lgkmcnt(0)
	s_setprio 1
	s_waitcnt lgkmcnt(0)
	v_mfma_f32_16x16x32_bf16 v[118:121], v[84:87], v[92:95], v[126:129]
	v_mfma_f32_16x16x32_bf16 v[126:129], v[88:91], v[96:99], v[118:121]
	v_mfma_f32_16x16x32_bf16 v[28:31], v[108:111], v[96:99], v[28:31]
	v_mfma_f32_16x16x32_bf16 v[28:31], v[104:107], v[92:95], v[28:31]
	v_mfma_f32_16x16x32_bf16 v[24:27], v[104:107], v[100:103], v[24:27]
	v_mfma_f32_16x16x32_bf16 v[24:27], v[108:111], v[180:183], v[24:27]
	v_mfma_f32_16x16x32_bf16 v[20:23], v[108:111], v[188:191], v[20:23]
	v_mfma_f32_16x16x32_bf16 v[20:23], v[104:107], v[184:187], v[20:23]
	v_mfma_f32_16x16x32_bf16 v[112:115], v[84:87], v[184:187], v[114:117]
	v_mfma_f32_16x16x32_bf16 v[114:117], v[88:91], v[188:191], v[112:115]
	v_mfma_f32_16x16x32_bf16 v[72:75], v[88:91], v[196:199], v[72:75]
	v_mfma_f32_16x16x32_bf16 v[72:75], v[84:87], v[192:195], v[72:75]
	v_mfma_f32_16x16x32_bf16 v[118:121], v[84:87], v[100:103], v[122:125]
	v_mfma_f32_16x16x32_bf16 v[122:125], v[88:91], v[180:183], v[118:121]
	v_mfma_f32_16x16x32_bf16 v[4:7], v[104:107], v[192:195], v[4:7]
	v_mfma_f32_16x16x32_bf16 v[4:7], v[108:111], v[196:199], v[4:7]
	s_setprio 0
	s_barrier
	s_add_u32 s6, s10, 0x1600080
	s_addc_u32 s7, s11, 0
	s_add_i32 s10, s38, s42
	v_lshl_add_u64 v[84:85], s[6:7], 0, v[164:165]
	s_mov_b32 m0, s10
	s_nop 0
	global_load_lds_dwordx4 v[84:85], off
	v_lshl_add_u64 v[84:85], s[6:7], 0, v[166:167]
	s_add_i32 m0, s10, 0x2000
	s_nop 0
	global_load_lds_dwordx4 v[84:85], off
	s_waitcnt vmcnt(6)
	s_barrier
	s_setprio 1
	v_mfma_f32_16x16x32_bf16 v[76:79], v[200:203], v[92:95], v[76:79]
	v_mfma_f32_16x16x32_bf16 v[118:121], v[204:207], v[96:99], v[76:79]
	v_mfma_f32_16x16x32_bf16 v[16:19], v[212:215], v[96:99], v[16:19]
	v_mfma_f32_16x16x32_bf16 v[16:19], v[208:211], v[92:95], v[16:19]
	v_mfma_f32_16x16x32_bf16 v[12:15], v[208:211], v[100:103], v[12:15]
	v_mfma_f32_16x16x32_bf16 v[12:15], v[212:215], v[180:183], v[12:15]
	v_mfma_f32_16x16x32_bf16 v[8:11], v[212:215], v[188:191], v[8:11]
	v_mfma_f32_16x16x32_bf16 v[8:11], v[208:211], v[184:187], v[8:11]
	v_mfma_f32_16x16x32_bf16 v[68:71], v[200:203], v[184:187], v[68:71]
	v_mfma_f32_16x16x32_bf16 v[68:71], v[204:207], v[188:191], v[68:71]
	v_mfma_f32_16x16x32_bf16 v[64:67], v[204:207], v[196:199], v[64:67]
	v_mfma_f32_16x16x32_bf16 v[64:67], v[200:203], v[192:195], v[64:67]
	v_mfma_f32_16x16x32_bf16 v[76:79], v[200:203], v[100:103], v[80:83]
	v_mfma_f32_16x16x32_bf16 v[110:113], v[204:207], v[180:183], v[76:79]
	v_mfma_f32_16x16x32_bf16 v[0:3], v[208:211], v[192:195], v[0:3]
	v_mfma_f32_16x16x32_bf16 v[0:3], v[212:215], v[196:199], v[0:3]
	s_setprio 0
	s_add_i32 s65, s65, 2
	s_add_u32 s63, s63, 0x100
	s_addc_u32 s64, s64, 0
	s_cmp_gt_u32 s65, 29
	s_mov_b64 s[6:7], s[8:9]
	s_barrier
	s_cbranch_scc0 .LBB0_363
	s_lshl_b32 s8, s0, 8
	s_add_i32 s8, s8, s56
	s_lshl_b32 s9, s1, 7
	s_add_i32 s9, s9, s49
	s_lshl_b32 s10, s0, 3
	s_lshr_b32 s11, s56, 5
	s_add_i32 s10, s10, s11
	v_add_u32_e32 v200, s8, v163
	v_lshlrev_b32_e32 v213, 2, v200
	s_cmp_eq_u32 s98, 0
	s_cbranch_scc1 .Lfs3_direct
	v_lshrrev_b32_e32 v212, 6, v222
	v_lshlrev_b32_e32 v212, 9, v212
	v_lshl_add_u32 v212, v163, 2, v212
	v_add_u32_e32 v212, 0x20040, v212
	ds_read_b32 v188, v212
	ds_read_b32 v189, v212 offset:64
	ds_read_b32 v190, v212 offset:128
	ds_read_b32 v191, v212 offset:192
	ds_read_b32 v192, v212 offset:256
	ds_read_b32 v193, v212 offset:320
	ds_read_b32 v194, v212 offset:384
	ds_read_b32 v195, v212 offset:448
	s_branch .Lfs3_join
.Lfs3_direct:
	global_load_dword v188, v213, s[12:13]
	global_load_dword v189, v213, s[12:13] offset:64
	global_load_dword v190, v213, s[12:13] offset:128
	global_load_dword v191, v213, s[12:13] offset:192
	global_load_dword v192, v213, s[12:13] offset:256
	global_load_dword v193, v213, s[12:13] offset:320
	global_load_dword v194, v213, s[12:13] offset:384
	global_load_dword v195, v213, s[12:13] offset:448
.Lfs3_join:
	v_lshl_add_u32 v201, v225, 3, s9
	v_lshlrev_b32_e32 v212, 2, v201
	global_load_dwordx4 v[76:79], v212, s[82:83]
	v_add_u32_e32 v213, 0xb000, v212
	global_load_dwordx4 v[80:83], v213, s[82:83]
	v_add_u32_e32 v213, 0x16000, v212
	global_load_dwordx4 v[84:87], v213, s[82:83]
	global_load_dwordx4 v[88:91], v212, s[84:85]
	v_add_u32_e32 v213, 0x5800, v212
	global_load_dwordx4 v[92:95], v213, s[82:83]
	v_add_u32_e32 v213, 0x10800, v212
	global_load_dwordx4 v[96:99], v213, s[82:83]
	v_add_u32_e32 v213, 0x1b800, v212
	global_load_dwordx4 v[100:103], v213, s[82:83]
	v_add_u32_e32 v213, 0x5800, v212
	global_load_dwordx4 v[104:107], v213, s[84:85]
	v_mul_u32_u24_e32 v215, 0x2c00, v200
	v_lshl_add_u32 v215, v201, 1, v215
	v_add_u32_e32 v213, s10, v163
	v_mul_u32_u24_e32 v217, 0xb000, v213
	v_add_u32_e32 v217, v217, v212
	v_cmp_gt_u32_e64 s[8:9], 2, v163
	v_cmp_lt_u32_e64 s[10:11], 13, v163
	v_cmp_lt_u32_e32 vcc, 1, v163
	v_mov_b32_e32 v214, 1.0
	v_mov_b32_e32 v216, 0xbfb8aa3b
	v_mov_b32_e32 v108, 0x3727c5ac
	s_waitcnt vmcnt(8)
	s_waitcnt lgkmcnt(0)
	v_fmamk_f32 v188, v188, 0x3a000000, v108
	v_fmamk_f32 v189, v189, 0x3a000000, v108
	v_fmamk_f32 v190, v190, 0x3a000000, v108
	v_fmamk_f32 v191, v191, 0x3a000000, v108
	v_fmamk_f32 v192, v192, 0x3a000000, v108
	v_fmamk_f32 v193, v193, 0x3a000000, v108
	v_fmamk_f32 v194, v194, 0x3a000000, v108
	v_fmamk_f32 v195, v195, 0x3a000000, v108
	v_rsq_f32_e32 v188, v188
	v_rsq_f32_e32 v189, v189
	v_rsq_f32_e32 v190, v190
	v_rsq_f32_e32 v191, v191
	v_rsq_f32_e32 v192, v192
	v_rsq_f32_e32 v193, v193
	v_rsq_f32_e32 v194, v194
	v_rsq_f32_e32 v195, v195
	v_pk_mul_f32 v[158:159], v[158:159], v[188:189] op_sel_hi:[1,0]
	v_pk_mul_f32 v[160:161], v[160:161], v[188:189] op_sel_hi:[1,0]
	v_pk_mul_f32 v[60:61], v[60:61], v[188:189] op_sel_hi:[1,0]
	v_pk_mul_f32 v[62:63], v[62:63], v[188:189] op_sel_hi:[1,0]
	v_pk_mul_f32 v[154:155], v[154:155], v[188:189] op_sel_hi:[1,0]
	v_pk_mul_f32 v[156:157], v[156:157], v[188:189] op_sel_hi:[1,0]
	v_pk_mul_f32 v[56:57], v[56:57], v[188:189] op_sel_hi:[1,0]
	v_pk_mul_f32 v[58:59], v[58:59], v[188:189] op_sel_hi:[1,0]
	v_pk_mul_f32 v[150:151], v[150:151], v[188:189] op_sel:[0,1] op_sel_hi:[1,1]
	v_pk_mul_f32 v[152:153], v[152:153], v[188:189] op_sel:[0,1] op_sel_hi:[1,1]
	v_pk_mul_f32 v[52:53], v[52:53], v[188:189] op_sel:[0,1] op_sel_hi:[1,1]
	v_pk_mul_f32 v[54:55], v[54:55], v[188:189] op_sel:[0,1] op_sel_hi:[1,1]
	v_pk_mul_f32 v[142:143], v[142:143], v[188:189] op_sel:[0,1] op_sel_hi:[1,1]
	v_pk_mul_f32 v[144:145], v[144:145], v[188:189] op_sel:[0,1] op_sel_hi:[1,1]
	v_pk_mul_f32 v[44:45], v[44:45], v[188:189] op_sel:[0,1] op_sel_hi:[1,1]
	v_pk_mul_f32 v[46:47], v[46:47], v[188:189] op_sel:[0,1] op_sel_hi:[1,1]
	v_pk_mul_f32 v[146:147], v[146:147], v[190:191] op_sel_hi:[1,0]
	v_pk_mul_f32 v[148:149], v[148:149], v[190:191] op_sel_hi:[1,0]
	v_pk_mul_f32 v[48:49], v[48:49], v[190:191] op_sel_hi:[1,0]
	v_pk_mul_f32 v[50:51], v[50:51], v[190:191] op_sel_hi:[1,0]
	v_pk_mul_f32 v[134:135], v[134:135], v[190:191] op_sel_hi:[1,0]
	v_pk_mul_f32 v[136:137], v[136:137], v[190:191] op_sel_hi:[1,0]
	v_pk_mul_f32 v[36:37], v[36:37], v[190:191] op_sel_hi:[1,0]
	v_pk_mul_f32 v[38:39], v[38:39], v[190:191] op_sel_hi:[1,0]
	v_pk_mul_f32 v[138:139], v[138:139], v[190:191] op_sel:[0,1] op_sel_hi:[1,1]
	v_pk_mul_f32 v[140:141], v[140:141], v[190:191] op_sel:[0,1] op_sel_hi:[1,1]
	v_pk_mul_f32 v[40:41], v[40:41], v[190:191] op_sel:[0,1] op_sel_hi:[1,1]
	v_pk_mul_f32 v[42:43], v[42:43], v[190:191] op_sel:[0,1] op_sel_hi:[1,1]
	v_pk_mul_f32 v[130:131], v[130:131], v[190:191] op_sel:[0,1] op_sel_hi:[1,1]
	v_pk_mul_f32 v[132:133], v[132:133], v[190:191] op_sel:[0,1] op_sel_hi:[1,1]
	v_pk_mul_f32 v[32:33], v[32:33], v[190:191] op_sel:[0,1] op_sel_hi:[1,1]
	v_pk_mul_f32 v[34:35], v[34:35], v[190:191] op_sel:[0,1] op_sel_hi:[1,1]
	v_pk_mul_f32 v[126:127], v[126:127], v[192:193] op_sel_hi:[1,0]
	v_pk_mul_f32 v[128:129], v[128:129], v[192:193] op_sel_hi:[1,0]
	v_pk_mul_f32 v[28:29], v[28:29], v[192:193] op_sel_hi:[1,0]
	v_pk_mul_f32 v[30:31], v[30:31], v[192:193] op_sel_hi:[1,0]
	v_pk_mul_f32 v[118:119], v[118:119], v[192:193] op_sel_hi:[1,0]
	v_pk_mul_f32 v[120:121], v[120:121], v[192:193] op_sel_hi:[1,0]
	v_pk_mul_f32 v[16:17], v[16:17], v[192:193] op_sel_hi:[1,0]
	v_pk_mul_f32 v[18:19], v[18:19], v[192:193] op_sel_hi:[1,0]
	v_pk_mul_f32 v[122:123], v[122:123], v[192:193] op_sel:[0,1] op_sel_hi:[1,1]
	v_pk_mul_f32 v[124:125], v[124:125], v[192:193] op_sel:[0,1] op_sel_hi:[1,1]
	v_pk_mul_f32 v[24:25], v[24:25], v[192:193] op_sel:[0,1] op_sel_hi:[1,1]
	v_pk_mul_f32 v[26:27], v[26:27], v[192:193] op_sel:[0,1] op_sel_hi:[1,1]
	v_pk_mul_f32 v[110:111], v[110:111], v[192:193] op_sel:[0,1] op_sel_hi:[1,1]
	v_pk_mul_f32 v[112:113], v[112:113], v[192:193] op_sel:[0,1] op_sel_hi:[1,1]
	v_pk_mul_f32 v[12:13], v[12:13], v[192:193] op_sel:[0,1] op_sel_hi:[1,1]
	v_pk_mul_f32 v[14:15], v[14:15], v[192:193] op_sel:[0,1] op_sel_hi:[1,1]
	v_pk_mul_f32 v[114:115], v[114:115], v[194:195] op_sel_hi:[1,0]
	v_pk_mul_f32 v[116:117], v[116:117], v[194:195] op_sel_hi:[1,0]
	v_pk_mul_f32 v[20:21], v[20:21], v[194:195] op_sel_hi:[1,0]
	v_pk_mul_f32 v[22:23], v[22:23], v[194:195] op_sel_hi:[1,0]
	v_pk_mul_f32 v[68:69], v[68:69], v[194:195] op_sel_hi:[1,0]
	v_pk_mul_f32 v[70:71], v[70:71], v[194:195] op_sel_hi:[1,0]
	v_pk_mul_f32 v[8:9], v[8:9], v[194:195] op_sel_hi:[1,0]
	v_pk_mul_f32 v[10:11], v[10:11], v[194:195] op_sel_hi:[1,0]
	v_pk_mul_f32 v[72:73], v[72:73], v[194:195] op_sel:[0,1] op_sel_hi:[1,1]
	v_pk_mul_f32 v[74:75], v[74:75], v[194:195] op_sel:[0,1] op_sel_hi:[1,1]
	v_pk_mul_f32 v[4:5], v[4:5], v[194:195] op_sel:[0,1] op_sel_hi:[1,1]
	v_pk_mul_f32 v[6:7], v[6:7], v[194:195] op_sel:[0,1] op_sel_hi:[1,1]
	v_pk_mul_f32 v[64:65], v[64:65], v[194:195] op_sel:[0,1] op_sel_hi:[1,1]
	v_pk_mul_f32 v[66:67], v[66:67], v[194:195] op_sel:[0,1] op_sel_hi:[1,1]
	v_pk_mul_f32 v[0:1], v[0:1], v[194:195] op_sel:[0,1] op_sel_hi:[1,1]
	v_pk_mul_f32 v[2:3], v[2:3], v[194:195] op_sel:[0,1] op_sel_hi:[1,1]
	s_nop 1
	s_mov_b64 exec, s[8:9]
	v_add_u32_e32 v213, 0x5800, v217
	global_store_dwordx4 v217, v[158:161], s[70:71]
	global_store_dwordx4 v213, v[154:157], s[70:71]
	global_store_dwordx4 v217, v[60:63], s[70:71] offset:16
	global_store_dwordx4 v213, v[56:59], s[70:71] offset:16
	s_mov_b64 exec, s[10:11]
	v_add_u32_e32 v213, 0xfff7c000, v217
	global_store_dwordx4 v213, v[72:75], s[70:71]
	global_store_dwordx4 v213, v[4:7], s[70:71] offset:16
	v_add_u32_e32 v213, 0xfff81800, v217
	global_store_dwordx4 v213, v[64:67], s[70:71]
	global_store_dwordx4 v213, v[0:3], s[70:71] offset:16
	s_mov_b64 exec, -1
	s_cmp_lg_u64 s[4:5], 0
	s_cselect_b32 s8, s0, s30
	v_lshrrev_b32_e32 v213, 6, v222
	s_lshl_b32 s8, s8, 8
	v_readfirstlane_b32 s9, v213
	s_add_i32 s8, s8, s56
	v_and_b32_e32 v213, 63, v222
	v_add_u32_e32 v213, s8, v213
	v_lshlrev_b32_e32 v213, 2, v213
	s_lshl_b32 s9, s9, 9
	s_add_i32 m0, s9, 0x20040
	s_nop 0
	global_load_lds_dword v213, s[12:13]
	v_add_u32_e32 v213, 0x100, v213
	s_add_i32 m0, s9, 0x20140
	s_nop 0
	global_load_lds_dword v213, s[12:13]
	v_add_u32_e32 v213, 0x1b800, v212
	global_load_dwordx4 v[204:207], v213, s[82:83] offset:16
	v_add_u32_e32 v213, 0x5800, v212
	global_load_dwordx4 v[208:211], v213, s[84:85] offset:16
	s_waitcnt vmcnt(12)
	v_pk_fma_f32 v[188:189], v[158:159], v[84:85], v[88:89]
	v_pk_fma_f32 v[190:191], v[160:161], v[86:87], v[90:91]
	v_pk_fma_f32 v[192:193], v[154:155], v[100:101], v[104:105]
	v_pk_fma_f32 v[194:195], v[156:157], v[102:103], v[106:107]
	v_fmac_f32_dpp v188, v158, v80 row_shr:1 row_mask:0xf bank_mask:0xf
	v_fmac_f32_dpp v189, v159, v81 row_shr:1 row_mask:0xf bank_mask:0xf
	v_fmac_f32_dpp v190, v160, v82 row_shr:1 row_mask:0xf bank_mask:0xf
	v_fmac_f32_dpp v191, v161, v83 row_shr:1 row_mask:0xf bank_mask:0xf
	v_fmac_f32_dpp v192, v154, v96 row_shr:1 row_mask:0xf bank_mask:0xf
	v_fmac_f32_dpp v193, v155, v97 row_shr:1 row_mask:0xf bank_mask:0xf
	v_fmac_f32_dpp v194, v156, v98 row_shr:1 row_mask:0xf bank_mask:0xf
	v_fmac_f32_dpp v195, v157, v99 row_shr:1 row_mask:0xf bank_mask:0xf
	v_fmac_f32_dpp v188, v158, v76 row_shr:2 row_mask:0xf bank_mask:0xf
	v_fmac_f32_dpp v189, v159, v77 row_shr:2 row_mask:0xf bank_mask:0xf
	v_fmac_f32_dpp v190, v160, v78 row_shr:2 row_mask:0xf bank_mask:0xf
	v_fmac_f32_dpp v191, v161, v79 row_shr:2 row_mask:0xf bank_mask:0xf
	v_fmac_f32_dpp v192, v154, v92 row_shr:2 row_mask:0xf bank_mask:0xf
	v_fmac_f32_dpp v193, v155, v93 row_shr:2 row_mask:0xf bank_mask:0xf
	v_fmac_f32_dpp v194, v156, v94 row_shr:2 row_mask:0xf bank_mask:0xf
	v_fmac_f32_dpp v195, v157, v95 row_shr:2 row_mask:0xf bank_mask:0xf
	v_pk_mul_f32 v[196:197], v[188:189], v[216:217] op_sel_hi:[1,0]
	v_pk_mul_f32 v[198:199], v[190:191], v[216:217] op_sel_hi:[1,0]
	v_exp_f32_e32 v196, v196
	v_exp_f32_e32 v197, v197
	v_exp_f32_e32 v198, v198
	v_exp_f32_e32 v199, v199
	v_pk_add_f32 v[196:197], v[196:197], v[214:215] op_sel_hi:[1,0]
	v_pk_add_f32 v[198:199], v[198:199], v[214:215] op_sel_hi:[1,0]
	v_rcp_f32_e32 v196, v196
	v_rcp_f32_e32 v197, v197
	v_rcp_f32_e32 v198, v198
	v_rcp_f32_e32 v199, v199
	v_pk_mul_f32 v[188:189], v[188:189], v[196:197]
	v_pk_mul_f32 v[190:191], v[190:191], v[198:199]
	v_pk_mul_f32 v[188:189], v[188:189], v[192:193]
	v_pk_mul_f32 v[190:191], v[190:191], v[194:195]
	v_cvt_pk_bf16_f32 v200, v188, v189
	v_cvt_pk_bf16_f32 v201, v190, v191
	v_pk_fma_f32 v[188:189], v[150:151], v[84:85], v[88:89]
	v_pk_fma_f32 v[190:191], v[152:153], v[86:87], v[90:91]
	v_pk_fma_f32 v[192:193], v[142:143], v[100:101], v[104:105]
	v_pk_fma_f32 v[194:195], v[144:145], v[102:103], v[106:107]
	v_fmac_f32_dpp v188, v150, v80 row_shr:1 row_mask:0xf bank_mask:0xf
	v_fmac_f32_dpp v189, v151, v81 row_shr:1 row_mask:0xf bank_mask:0xf
	v_fmac_f32_dpp v190, v152, v82 row_shr:1 row_mask:0xf bank_mask:0xf
	v_fmac_f32_dpp v191, v153, v83 row_shr:1 row_mask:0xf bank_mask:0xf
	v_fmac_f32_dpp v192, v142, v96 row_shr:1 row_mask:0xf bank_mask:0xf
	v_fmac_f32_dpp v193, v143, v97 row_shr:1 row_mask:0xf bank_mask:0xf
	v_fmac_f32_dpp v194, v144, v98 row_shr:1 row_mask:0xf bank_mask:0xf
	v_fmac_f32_dpp v195, v145, v99 row_shr:1 row_mask:0xf bank_mask:0xf
	v_fmac_f32_dpp v188, v150, v76 row_shr:2 row_mask:0xf bank_mask:0xf
	v_fmac_f32_dpp v189, v151, v77 row_shr:2 row_mask:0xf bank_mask:0xf
	v_fmac_f32_dpp v190, v152, v78 row_shr:2 row_mask:0xf bank_mask:0xf
	v_fmac_f32_dpp v191, v153, v79 row_shr:2 row_mask:0xf bank_mask:0xf
	v_fmac_f32_dpp v192, v142, v92 row_shr:2 row_mask:0xf bank_mask:0xf
	v_fmac_f32_dpp v193, v143, v93 row_shr:2 row_mask:0xf bank_mask:0xf
	v_fmac_f32_dpp v194, v144, v94 row_shr:2 row_mask:0xf bank_mask:0xf
	v_fmac_f32_dpp v195, v145, v95 row_shr:2 row_mask:0xf bank_mask:0xf
	v_fmac_f32_dpp v188, v158, v80 row_shl:15 row_mask:0xf bank_mask:0xf
	v_fmac_f32_dpp v189, v159, v81 row_shl:15 row_mask:0xf bank_mask:0xf
	v_fmac_f32_dpp v190, v160, v82 row_shl:15 row_mask:0xf bank_mask:0xf
	v_fmac_f32_dpp v191, v161, v83 row_shl:15 row_mask:0xf bank_mask:0xf
	v_fmac_f32_dpp v192, v154, v96 row_shl:15 row_mask:0xf bank_mask:0xf
	v_fmac_f32_dpp v193, v155, v97 row_shl:15 row_mask:0xf bank_mask:0xf
	v_fmac_f32_dpp v194, v156, v98 row_shl:15 row_mask:0xf bank_mask:0xf
	v_fmac_f32_dpp v195, v157, v99 row_shl:15 row_mask:0xf bank_mask:0xf
	v_fmac_f32_dpp v188, v158, v76 row_shl:14 row_mask:0xf bank_mask:0xf
	v_fmac_f32_dpp v189, v159, v77 row_shl:14 row_mask:0xf bank_mask:0xf
	v_fmac_f32_dpp v190, v160, v78 row_shl:14 row_mask:0xf bank_mask:0xf
	v_fmac_f32_dpp v191, v161, v79 row_shl:14 row_mask:0xf bank_mask:0xf
	v_fmac_f32_dpp v192, v154, v92 row_shl:14 row_mask:0xf bank_mask:0xf
	v_fmac_f32_dpp v193, v155, v93 row_shl:14 row_mask:0xf bank_mask:0xf
	v_fmac_f32_dpp v194, v156, v94 row_shl:14 row_mask:0xf bank_mask:0xf
	v_fmac_f32_dpp v195, v157, v95 row_shl:14 row_mask:0xf bank_mask:0xf
	v_pk_mul_f32 v[196:197], v[188:189], v[216:217] op_sel_hi:[1,0]
	v_pk_mul_f32 v[198:199], v[190:191], v[216:217] op_sel_hi:[1,0]
	v_exp_f32_e32 v196, v196
	v_exp_f32_e32 v197, v197
	v_exp_f32_e32 v198, v198
	v_exp_f32_e32 v199, v199
	v_pk_add_f32 v[196:197], v[196:197], v[214:215] op_sel_hi:[1,0]
	v_pk_add_f32 v[198:199], v[198:199], v[214:215] op_sel_hi:[1,0]
	v_rcp_f32_e32 v196, v196
	v_rcp_f32_e32 v197, v197
	v_rcp_f32_e32 v198, v198
	v_rcp_f32_e32 v199, v199
	v_pk_mul_f32 v[188:189], v[188:189], v[196:197]
	v_pk_mul_f32 v[190:191], v[190:191], v[198:199]
	v_pk_mul_f32 v[188:189], v[188:189], v[192:193]
	v_pk_mul_f32 v[190:191], v[190:191], v[194:195]
	v_cvt_pk_bf16_f32 v158, v188, v189
	v_cvt_pk_bf16_f32 v159, v190, v191
	global_load_dwordx4 v[154:157], v212, s[82:83] offset:16
	v_pk_fma_f32 v[188:189], v[146:147], v[84:85], v[88:89]
	v_pk_fma_f32 v[190:191], v[148:149], v[86:87], v[90:91]
	v_pk_fma_f32 v[192:193], v[134:135], v[100:101], v[104:105]
	v_pk_fma_f32 v[194:195], v[136:137], v[102:103], v[106:107]
	v_fmac_f32_dpp v188, v146, v80 row_shr:1 row_mask:0xf bank_mask:0xf
	v_fmac_f32_dpp v189, v147, v81 row_shr:1 row_mask:0xf bank_mask:0xf
	v_fmac_f32_dpp v190, v148, v82 row_shr:1 row_mask:0xf bank_mask:0xf
	v_fmac_f32_dpp v191, v149, v83 row_shr:1 row_mask:0xf bank_mask:0xf
	v_fmac_f32_dpp v192, v134, v96 row_shr:1 row_mask:0xf bank_mask:0xf
	v_fmac_f32_dpp v193, v135, v97 row_shr:1 row_mask:0xf bank_mask:0xf
	v_fmac_f32_dpp v194, v136, v98 row_shr:1 row_mask:0xf bank_mask:0xf
	v_fmac_f32_dpp v195, v137, v99 row_shr:1 row_mask:0xf bank_mask:0xf
	v_fmac_f32_dpp v188, v146, v76 row_shr:2 row_mask:0xf bank_mask:0xf
	v_fmac_f32_dpp v189, v147, v77 row_shr:2 row_mask:0xf bank_mask:0xf
	v_fmac_f32_dpp v190, v148, v78 row_shr:2 row_mask:0xf bank_mask:0xf
	v_fmac_f32_dpp v191, v149, v79 row_shr:2 row_mask:0xf bank_mask:0xf
	v_fmac_f32_dpp v192, v134, v92 row_shr:2 row_mask:0xf bank_mask:0xf
	v_fmac_f32_dpp v193, v135, v93 row_shr:2 row_mask:0xf bank_mask:0xf
	v_fmac_f32_dpp v194, v136, v94 row_shr:2 row_mask:0xf bank_mask:0xf
	v_fmac_f32_dpp v195, v137, v95 row_shr:2 row_mask:0xf bank_mask:0xf
	v_fmac_f32_dpp v188, v150, v80 row_shl:15 row_mask:0xf bank_mask:0xf
	v_fmac_f32_dpp v189, v151, v81 row_shl:15 row_mask:0xf bank_mask:0xf
	v_fmac_f32_dpp v190, v152, v82 row_shl:15 row_mask:0xf bank_mask:0xf
	v_fmac_f32_dpp v191, v153, v83 row_shl:15 row_mask:0xf bank_mask:0xf
	v_fmac_f32_dpp v192, v142, v96 row_shl:15 row_mask:0xf bank_mask:0xf
	v_fmac_f32_dpp v193, v143, v97 row_shl:15 row_mask:0xf bank_mask:0xf
	v_fmac_f32_dpp v194, v144, v98 row_shl:15 row_mask:0xf bank_mask:0xf
	v_fmac_f32_dpp v195, v145, v99 row_shl:15 row_mask:0xf bank_mask:0xf
	v_fmac_f32_dpp v188, v150, v76 row_shl:14 row_mask:0xf bank_mask:0xf
	v_fmac_f32_dpp v189, v151, v77 row_shl:14 row_mask:0xf bank_mask:0xf
	v_fmac_f32_dpp v190, v152, v78 row_shl:14 row_mask:0xf bank_mask:0xf
	v_fmac_f32_dpp v191, v153, v79 row_shl:14 row_mask:0xf bank_mask:0xf
	v_fmac_f32_dpp v192, v142, v92 row_shl:14 row_mask:0xf bank_mask:0xf
	v_fmac_f32_dpp v193, v143, v93 row_shl:14 row_mask:0xf bank_mask:0xf
	v_fmac_f32_dpp v194, v144, v94 row_shl:14 row_mask:0xf bank_mask:0xf
	v_fmac_f32_dpp v195, v145, v95 row_shl:14 row_mask:0xf bank_mask:0xf
	v_pk_mul_f32 v[196:197], v[188:189], v[216:217] op_sel_hi:[1,0]
	v_pk_mul_f32 v[198:199], v[190:191], v[216:217] op_sel_hi:[1,0]
	v_exp_f32_e32 v196, v196
	v_exp_f32_e32 v197, v197
	v_exp_f32_e32 v198, v198
	v_exp_f32_e32 v199, v199
	v_pk_add_f32 v[196:197], v[196:197], v[214:215] op_sel_hi:[1,0]
	v_pk_add_f32 v[198:199], v[198:199], v[214:215] op_sel_hi:[1,0]
	v_rcp_f32_e32 v196, v196
	v_rcp_f32_e32 v197, v197
	v_rcp_f32_e32 v198, v198
	v_rcp_f32_e32 v199, v199
	v_pk_mul_f32 v[188:189], v[188:189], v[196:197]
	v_pk_mul_f32 v[190:191], v[190:191], v[198:199]
	v_pk_mul_f32 v[188:189], v[188:189], v[192:193]
	v_pk_mul_f32 v[190:191], v[190:191], v[194:195]
	v_cvt_pk_bf16_f32 v150, v188, v189
	v_cvt_pk_bf16_f32 v151, v190, v191
	v_add_u32_e32 v213, 0xb000, v212
	global_load_dwordx4 v[142:145], v213, s[82:83] offset:16
	v_pk_fma_f32 v[188:189], v[138:139], v[84:85], v[88:89]
	v_pk_fma_f32 v[190:191], v[140:141], v[86:87], v[90:91]
	v_pk_fma_f32 v[192:193], v[130:131], v[100:101], v[104:105]
	v_pk_fma_f32 v[194:195], v[132:133], v[102:103], v[106:107]
	v_fmac_f32_dpp v188, v138, v80 row_shr:1 row_mask:0xf bank_mask:0xf
	v_fmac_f32_dpp v189, v139, v81 row_shr:1 row_mask:0xf bank_mask:0xf
	v_fmac_f32_dpp v190, v140, v82 row_shr:1 row_mask:0xf bank_mask:0xf
	v_fmac_f32_dpp v191, v141, v83 row_shr:1 row_mask:0xf bank_mask:0xf
	v_fmac_f32_dpp v192, v130, v96 row_shr:1 row_mask:0xf bank_mask:0xf
	v_fmac_f32_dpp v193, v131, v97 row_shr:1 row_mask:0xf bank_mask:0xf
	v_fmac_f32_dpp v194, v132, v98 row_shr:1 row_mask:0xf bank_mask:0xf
	v_fmac_f32_dpp v195, v133, v99 row_shr:1 row_mask:0xf bank_mask:0xf
	v_fmac_f32_dpp v188, v138, v76 row_shr:2 row_mask:0xf bank_mask:0xf
	v_fmac_f32_dpp v189, v139, v77 row_shr:2 row_mask:0xf bank_mask:0xf
	v_fmac_f32_dpp v190, v140, v78 row_shr:2 row_mask:0xf bank_mask:0xf
	v_fmac_f32_dpp v191, v141, v79 row_shr:2 row_mask:0xf bank_mask:0xf
	v_fmac_f32_dpp v192, v130, v92 row_shr:2 row_mask:0xf bank_mask:0xf
	v_fmac_f32_dpp v193, v131, v93 row_shr:2 row_mask:0xf bank_mask:0xf
	v_fmac_f32_dpp v194, v132, v94 row_shr:2 row_mask:0xf bank_mask:0xf
	v_fmac_f32_dpp v195, v133, v95 row_shr:2 row_mask:0xf bank_mask:0xf
	v_fmac_f32_dpp v188, v146, v80 row_shl:15 row_mask:0xf bank_mask:0xf
	v_fmac_f32_dpp v189, v147, v81 row_shl:15 row_mask:0xf bank_mask:0xf
	v_fmac_f32_dpp v190, v148, v82 row_shl:15 row_mask:0xf bank_mask:0xf
	v_fmac_f32_dpp v191, v149, v83 row_shl:15 row_mask:0xf bank_mask:0xf
	v_fmac_f32_dpp v192, v134, v96 row_shl:15 row_mask:0xf bank_mask:0xf
	v_fmac_f32_dpp v193, v135, v97 row_shl:15 row_mask:0xf bank_mask:0xf
	v_fmac_f32_dpp v194, v136, v98 row_shl:15 row_mask:0xf bank_mask:0xf
	v_fmac_f32_dpp v195, v137, v99 row_shl:15 row_mask:0xf bank_mask:0xf
	v_fmac_f32_dpp v188, v146, v76 row_shl:14 row_mask:0xf bank_mask:0xf
	v_fmac_f32_dpp v189, v147, v77 row_shl:14 row_mask:0xf bank_mask:0xf
	v_fmac_f32_dpp v190, v148, v78 row_shl:14 row_mask:0xf bank_mask:0xf
	v_fmac_f32_dpp v191, v149, v79 row_shl:14 row_mask:0xf bank_mask:0xf
	v_fmac_f32_dpp v192, v134, v92 row_shl:14 row_mask:0xf bank_mask:0xf
	v_fmac_f32_dpp v193, v135, v93 row_shl:14 row_mask:0xf bank_mask:0xf
	v_fmac_f32_dpp v194, v136, v94 row_shl:14 row_mask:0xf bank_mask:0xf
	v_fmac_f32_dpp v195, v137, v95 row_shl:14 row_mask:0xf bank_mask:0xf
	v_pk_mul_f32 v[196:197], v[188:189], v[216:217] op_sel_hi:[1,0]
	v_pk_mul_f32 v[198:199], v[190:191], v[216:217] op_sel_hi:[1,0]
	v_exp_f32_e32 v196, v196
	v_exp_f32_e32 v197, v197
	v_exp_f32_e32 v198, v198
	v_exp_f32_e32 v199, v199
	v_pk_add_f32 v[196:197], v[196:197], v[214:215] op_sel_hi:[1,0]
	v_pk_add_f32 v[198:199], v[198:199], v[214:215] op_sel_hi:[1,0]
	v_rcp_f32_e32 v196, v196
	v_rcp_f32_e32 v197, v197
	v_rcp_f32_e32 v198, v198
	v_rcp_f32_e32 v199, v199
	v_pk_mul_f32 v[188:189], v[188:189], v[196:197]
	v_pk_mul_f32 v[190:191], v[190:191], v[198:199]
	v_pk_mul_f32 v[188:189], v[188:189], v[192:193]
	v_pk_mul_f32 v[190:191], v[190:191], v[194:195]
	v_cvt_pk_bf16_f32 v146, v188, v189
	v_cvt_pk_bf16_f32 v147, v190, v191
	v_add_u32_e32 v213, 0x16000, v212
	global_load_dwordx4 v[134:137], v213, s[82:83] offset:16
	v_pk_fma_f32 v[188:189], v[126:127], v[84:85], v[88:89]
	v_pk_fma_f32 v[190:191], v[128:129], v[86:87], v[90:91]
	v_pk_fma_f32 v[192:193], v[118:119], v[100:101], v[104:105]
	v_pk_fma_f32 v[194:195], v[120:121], v[102:103], v[106:107]
	v_fmac_f32_dpp v188, v126, v80 row_shr:1 row_mask:0xf bank_mask:0xf
	v_fmac_f32_dpp v189, v127, v81 row_shr:1 row_mask:0xf bank_mask:0xf
	v_fmac_f32_dpp v190, v128, v82 row_shr:1 row_mask:0xf bank_mask:0xf
	v_fmac_f32_dpp v191, v129, v83 row_shr:1 row_mask:0xf bank_mask:0xf
	v_fmac_f32_dpp v192, v118, v96 row_shr:1 row_mask:0xf bank_mask:0xf
	v_fmac_f32_dpp v193, v119, v97 row_shr:1 row_mask:0xf bank_mask:0xf
	v_fmac_f32_dpp v194, v120, v98 row_shr:1 row_mask:0xf bank_mask:0xf
	v_fmac_f32_dpp v195, v121, v99 row_shr:1 row_mask:0xf bank_mask:0xf
	v_fmac_f32_dpp v188, v126, v76 row_shr:2 row_mask:0xf bank_mask:0xf
	v_fmac_f32_dpp v189, v127, v77 row_shr:2 row_mask:0xf bank_mask:0xf
	v_fmac_f32_dpp v190, v128, v78 row_shr:2 row_mask:0xf bank_mask:0xf
	v_fmac_f32_dpp v191, v129, v79 row_shr:2 row_mask:0xf bank_mask:0xf
	v_fmac_f32_dpp v192, v118, v92 row_shr:2 row_mask:0xf bank_mask:0xf
	v_fmac_f32_dpp v193, v119, v93 row_shr:2 row_mask:0xf bank_mask:0xf
	v_fmac_f32_dpp v194, v120, v94 row_shr:2 row_mask:0xf bank_mask:0xf
	v_fmac_f32_dpp v195, v121, v95 row_shr:2 row_mask:0xf bank_mask:0xf
	v_fmac_f32_dpp v188, v138, v80 row_shl:15 row_mask:0xf bank_mask:0xf
	v_fmac_f32_dpp v189, v139, v81 row_shl:15 row_mask:0xf bank_mask:0xf
	v_fmac_f32_dpp v190, v140, v82 row_shl:15 row_mask:0xf bank_mask:0xf
	v_fmac_f32_dpp v191, v141, v83 row_shl:15 row_mask:0xf bank_mask:0xf
	v_fmac_f32_dpp v192, v130, v96 row_shl:15 row_mask:0xf bank_mask:0xf
	v_fmac_f32_dpp v193, v131, v97 row_shl:15 row_mask:0xf bank_mask:0xf
	v_fmac_f32_dpp v194, v132, v98 row_shl:15 row_mask:0xf bank_mask:0xf
	v_fmac_f32_dpp v195, v133, v99 row_shl:15 row_mask:0xf bank_mask:0xf
	v_fmac_f32_dpp v188, v138, v76 row_shl:14 row_mask:0xf bank_mask:0xf
	v_fmac_f32_dpp v189, v139, v77 row_shl:14 row_mask:0xf bank_mask:0xf
	v_fmac_f32_dpp v190, v140, v78 row_shl:14 row_mask:0xf bank_mask:0xf
	v_fmac_f32_dpp v191, v141, v79 row_shl:14 row_mask:0xf bank_mask:0xf
	v_fmac_f32_dpp v192, v130, v92 row_shl:14 row_mask:0xf bank_mask:0xf
	v_fmac_f32_dpp v193, v131, v93 row_shl:14 row_mask:0xf bank_mask:0xf
	v_fmac_f32_dpp v194, v132, v94 row_shl:14 row_mask:0xf bank_mask:0xf
	v_fmac_f32_dpp v195, v133, v95 row_shl:14 row_mask:0xf bank_mask:0xf
	v_pk_mul_f32 v[196:197], v[188:189], v[216:217] op_sel_hi:[1,0]
	v_pk_mul_f32 v[198:199], v[190:191], v[216:217] op_sel_hi:[1,0]
	v_exp_f32_e32 v196, v196
	v_exp_f32_e32 v197, v197
	v_exp_f32_e32 v198, v198
	v_exp_f32_e32 v199, v199
	v_pk_add_f32 v[196:197], v[196:197], v[214:215] op_sel_hi:[1,0]
	v_pk_add_f32 v[198:199], v[198:199], v[214:215] op_sel_hi:[1,0]
	v_rcp_f32_e32 v196, v196
	v_rcp_f32_e32 v197, v197
	v_rcp_f32_e32 v198, v198
	v_rcp_f32_e32 v199, v199
	v_pk_mul_f32 v[188:189], v[188:189], v[196:197]
	v_pk_mul_f32 v[190:191], v[190:191], v[198:199]
	v_pk_mul_f32 v[188:189], v[188:189], v[192:193]
	v_pk_mul_f32 v[190:191], v[190:191], v[194:195]
	v_cvt_pk_bf16_f32 v138, v188, v189
	v_cvt_pk_bf16_f32 v139, v190, v191
	global_load_dwordx4 v[130:133], v212, s[84:85] offset:16
	v_pk_fma_f32 v[188:189], v[122:123], v[84:85], v[88:89]
	v_pk_fma_f32 v[190:191], v[124:125], v[86:87], v[90:91]
	v_pk_fma_f32 v[192:193], v[110:111], v[100:101], v[104:105]
	v_pk_fma_f32 v[194:195], v[112:113], v[102:103], v[106:107]
	v_fmac_f32_dpp v188, v122, v80 row_shr:1 row_mask:0xf bank_mask:0xf
	v_fmac_f32_dpp v189, v123, v81 row_shr:1 row_mask:0xf bank_mask:0xf
	v_fmac_f32_dpp v190, v124, v82 row_shr:1 row_mask:0xf bank_mask:0xf
	v_fmac_f32_dpp v191, v125, v83 row_shr:1 row_mask:0xf bank_mask:0xf
	v_fmac_f32_dpp v192, v110, v96 row_shr:1 row_mask:0xf bank_mask:0xf
	v_fmac_f32_dpp v193, v111, v97 row_shr:1 row_mask:0xf bank_mask:0xf
	v_fmac_f32_dpp v194, v112, v98 row_shr:1 row_mask:0xf bank_mask:0xf
	v_fmac_f32_dpp v195, v113, v99 row_shr:1 row_mask:0xf bank_mask:0xf
	v_fmac_f32_dpp v188, v122, v76 row_shr:2 row_mask:0xf bank_mask:0xf
	v_fmac_f32_dpp v189, v123, v77 row_shr:2 row_mask:0xf bank_mask:0xf
	v_fmac_f32_dpp v190, v124, v78 row_shr:2 row_mask:0xf bank_mask:0xf
	v_fmac_f32_dpp v191, v125, v79 row_shr:2 row_mask:0xf bank_mask:0xf
	v_fmac_f32_dpp v192, v110, v92 row_shr:2 row_mask:0xf bank_mask:0xf
	v_fmac_f32_dpp v193, v111, v93 row_shr:2 row_mask:0xf bank_mask:0xf
	v_fmac_f32_dpp v194, v112, v94 row_shr:2 row_mask:0xf bank_mask:0xf
	v_fmac_f32_dpp v195, v113, v95 row_shr:2 row_mask:0xf bank_mask:0xf
	v_fmac_f32_dpp v188, v126, v80 row_shl:15 row_mask:0xf bank_mask:0xf
	v_fmac_f32_dpp v189, v127, v81 row_shl:15 row_mask:0xf bank_mask:0xf
	v_fmac_f32_dpp v190, v128, v82 row_shl:15 row_mask:0xf bank_mask:0xf
	v_fmac_f32_dpp v191, v129, v83 row_shl:15 row_mask:0xf bank_mask:0xf
	v_fmac_f32_dpp v192, v118, v96 row_shl:15 row_mask:0xf bank_mask:0xf
	v_fmac_f32_dpp v193, v119, v97 row_shl:15 row_mask:0xf bank_mask:0xf
	v_fmac_f32_dpp v194, v120, v98 row_shl:15 row_mask:0xf bank_mask:0xf
	v_fmac_f32_dpp v195, v121, v99 row_shl:15 row_mask:0xf bank_mask:0xf
	v_fmac_f32_dpp v188, v126, v76 row_shl:14 row_mask:0xf bank_mask:0xf
	v_fmac_f32_dpp v189, v127, v77 row_shl:14 row_mask:0xf bank_mask:0xf
	v_fmac_f32_dpp v190, v128, v78 row_shl:14 row_mask:0xf bank_mask:0xf
	v_fmac_f32_dpp v191, v129, v79 row_shl:14 row_mask:0xf bank_mask:0xf
	v_fmac_f32_dpp v192, v118, v92 row_shl:14 row_mask:0xf bank_mask:0xf
	v_fmac_f32_dpp v193, v119, v93 row_shl:14 row_mask:0xf bank_mask:0xf
	v_fmac_f32_dpp v194, v120, v94 row_shl:14 row_mask:0xf bank_mask:0xf
	v_fmac_f32_dpp v195, v121, v95 row_shl:14 row_mask:0xf bank_mask:0xf
	v_pk_mul_f32 v[196:197], v[188:189], v[216:217] op_sel_hi:[1,0]
	v_pk_mul_f32 v[198:199], v[190:191], v[216:217] op_sel_hi:[1,0]
	v_exp_f32_e32 v196, v196
	v_exp_f32_e32 v197, v197
	v_exp_f32_e32 v198, v198
	v_exp_f32_e32 v199, v199
	v_pk_add_f32 v[196:197], v[196:197], v[214:215] op_sel_hi:[1,0]
	v_pk_add_f32 v[198:199], v[198:199], v[214:215] op_sel_hi:[1,0]
	v_rcp_f32_e32 v196, v196
	v_rcp_f32_e32 v197, v197
	v_rcp_f32_e32 v198, v198
	v_rcp_f32_e32 v199, v199
	v_pk_mul_f32 v[188:189], v[188:189], v[196:197]
	v_pk_mul_f32 v[190:191], v[190:191], v[198:199]
	v_pk_mul_f32 v[188:189], v[188:189], v[192:193]
	v_pk_mul_f32 v[190:191], v[190:191], v[194:195]
	v_cvt_pk_bf16_f32 v126, v188, v189
	v_cvt_pk_bf16_f32 v127, v190, v191
	v_add_u32_e32 v213, 0x5800, v212
	global_load_dwordx4 v[118:121], v213, s[82:83] offset:16
	v_pk_fma_f32 v[188:189], v[114:115], v[84:85], v[88:89]
	v_pk_fma_f32 v[190:191], v[116:117], v[86:87], v[90:91]
	v_pk_fma_f32 v[192:193], v[68:69], v[100:101], v[104:105]
	v_pk_fma_f32 v[194:195], v[70:71], v[102:103], v[106:107]
	v_fmac_f32_dpp v188, v114, v80 row_shr:1 row_mask:0xf bank_mask:0xf
	v_fmac_f32_dpp v189, v115, v81 row_shr:1 row_mask:0xf bank_mask:0xf
	v_fmac_f32_dpp v190, v116, v82 row_shr:1 row_mask:0xf bank_mask:0xf
	v_fmac_f32_dpp v191, v117, v83 row_shr:1 row_mask:0xf bank_mask:0xf
	v_fmac_f32_dpp v192, v68, v96 row_shr:1 row_mask:0xf bank_mask:0xf
	v_fmac_f32_dpp v193, v69, v97 row_shr:1 row_mask:0xf bank_mask:0xf
	v_fmac_f32_dpp v194, v70, v98 row_shr:1 row_mask:0xf bank_mask:0xf
	v_fmac_f32_dpp v195, v71, v99 row_shr:1 row_mask:0xf bank_mask:0xf
	v_fmac_f32_dpp v188, v114, v76 row_shr:2 row_mask:0xf bank_mask:0xf
	v_fmac_f32_dpp v189, v115, v77 row_shr:2 row_mask:0xf bank_mask:0xf
	v_fmac_f32_dpp v190, v116, v78 row_shr:2 row_mask:0xf bank_mask:0xf
	v_fmac_f32_dpp v191, v117, v79 row_shr:2 row_mask:0xf bank_mask:0xf
	v_fmac_f32_dpp v192, v68, v92 row_shr:2 row_mask:0xf bank_mask:0xf
	v_fmac_f32_dpp v193, v69, v93 row_shr:2 row_mask:0xf bank_mask:0xf
	v_fmac_f32_dpp v194, v70, v94 row_shr:2 row_mask:0xf bank_mask:0xf
	v_fmac_f32_dpp v195, v71, v95 row_shr:2 row_mask:0xf bank_mask:0xf
	v_fmac_f32_dpp v188, v122, v80 row_shl:15 row_mask:0xf bank_mask:0xf
	v_fmac_f32_dpp v189, v123, v81 row_shl:15 row_mask:0xf bank_mask:0xf
	v_fmac_f32_dpp v190, v124, v82 row_shl:15 row_mask:0xf bank_mask:0xf
	v_fmac_f32_dpp v191, v125, v83 row_shl:15 row_mask:0xf bank_mask:0xf
	v_fmac_f32_dpp v192, v110, v96 row_shl:15 row_mask:0xf bank_mask:0xf
	v_fmac_f32_dpp v193, v111, v97 row_shl:15 row_mask:0xf bank_mask:0xf
	v_fmac_f32_dpp v194, v112, v98 row_shl:15 row_mask:0xf bank_mask:0xf
	v_fmac_f32_dpp v195, v113, v99 row_shl:15 row_mask:0xf bank_mask:0xf
	v_fmac_f32_dpp v188, v122, v76 row_shl:14 row_mask:0xf bank_mask:0xf
	v_fmac_f32_dpp v189, v123, v77 row_shl:14 row_mask:0xf bank_mask:0xf
	v_fmac_f32_dpp v190, v124, v78 row_shl:14 row_mask:0xf bank_mask:0xf
	v_fmac_f32_dpp v191, v125, v79 row_shl:14 row_mask:0xf bank_mask:0xf
	v_fmac_f32_dpp v192, v110, v92 row_shl:14 row_mask:0xf bank_mask:0xf
	v_fmac_f32_dpp v193, v111, v93 row_shl:14 row_mask:0xf bank_mask:0xf
	v_fmac_f32_dpp v194, v112, v94 row_shl:14 row_mask:0xf bank_mask:0xf
	v_fmac_f32_dpp v195, v113, v95 row_shl:14 row_mask:0xf bank_mask:0xf
	v_pk_mul_f32 v[196:197], v[188:189], v[216:217] op_sel_hi:[1,0]
	v_pk_mul_f32 v[198:199], v[190:191], v[216:217] op_sel_hi:[1,0]
	v_exp_f32_e32 v196, v196
	v_exp_f32_e32 v197, v197
	v_exp_f32_e32 v198, v198
	v_exp_f32_e32 v199, v199
	v_pk_add_f32 v[196:197], v[196:197], v[214:215] op_sel_hi:[1,0]
	v_pk_add_f32 v[198:199], v[198:199], v[214:215] op_sel_hi:[1,0]
	v_rcp_f32_e32 v196, v196
	v_rcp_f32_e32 v197, v197
	v_rcp_f32_e32 v198, v198
	v_rcp_f32_e32 v199, v199
	v_pk_mul_f32 v[188:189], v[188:189], v[196:197]
	v_pk_mul_f32 v[190:191], v[190:191], v[198:199]
	v_pk_mul_f32 v[188:189], v[188:189], v[192:193]
	v_pk_mul_f32 v[190:191], v[190:191], v[194:195]
	v_cvt_pk_bf16_f32 v122, v188, v189
	v_cvt_pk_bf16_f32 v123, v190, v191
	v_add_u32_e32 v213, 0x10800, v212
	global_load_dwordx4 v[110:113], v213, s[82:83] offset:16
	v_pk_fma_f32 v[188:189], v[72:73], v[84:85], v[88:89]
	v_pk_fma_f32 v[190:191], v[74:75], v[86:87], v[90:91]
	v_pk_fma_f32 v[192:193], v[64:65], v[100:101], v[104:105]
	v_pk_fma_f32 v[194:195], v[66:67], v[102:103], v[106:107]
	v_fmac_f32_dpp v188, v72, v80 row_shr:1 row_mask:0xf bank_mask:0xf
	v_fmac_f32_dpp v189, v73, v81 row_shr:1 row_mask:0xf bank_mask:0xf
	v_fmac_f32_dpp v190, v74, v82 row_shr:1 row_mask:0xf bank_mask:0xf
	v_fmac_f32_dpp v191, v75, v83 row_shr:1 row_mask:0xf bank_mask:0xf
	v_fmac_f32_dpp v192, v64, v96 row_shr:1 row_mask:0xf bank_mask:0xf
	v_fmac_f32_dpp v193, v65, v97 row_shr:1 row_mask:0xf bank_mask:0xf
	v_fmac_f32_dpp v194, v66, v98 row_shr:1 row_mask:0xf bank_mask:0xf
	v_fmac_f32_dpp v195, v67, v99 row_shr:1 row_mask:0xf bank_mask:0xf
	v_fmac_f32_dpp v188, v72, v76 row_shr:2 row_mask:0xf bank_mask:0xf
	v_fmac_f32_dpp v189, v73, v77 row_shr:2 row_mask:0xf bank_mask:0xf
	v_fmac_f32_dpp v190, v74, v78 row_shr:2 row_mask:0xf bank_mask:0xf
	v_fmac_f32_dpp v191, v75, v79 row_shr:2 row_mask:0xf bank_mask:0xf
	v_fmac_f32_dpp v192, v64, v92 row_shr:2 row_mask:0xf bank_mask:0xf
	v_fmac_f32_dpp v193, v65, v93 row_shr:2 row_mask:0xf bank_mask:0xf
	v_fmac_f32_dpp v194, v66, v94 row_shr:2 row_mask:0xf bank_mask:0xf
	v_fmac_f32_dpp v195, v67, v95 row_shr:2 row_mask:0xf bank_mask:0xf
	v_fmac_f32_dpp v188, v114, v80 row_shl:15 row_mask:0xf bank_mask:0xf
	v_fmac_f32_dpp v189, v115, v81 row_shl:15 row_mask:0xf bank_mask:0xf
	v_fmac_f32_dpp v190, v116, v82 row_shl:15 row_mask:0xf bank_mask:0xf
	v_fmac_f32_dpp v191, v117, v83 row_shl:15 row_mask:0xf bank_mask:0xf
	v_fmac_f32_dpp v192, v68, v96 row_shl:15 row_mask:0xf bank_mask:0xf
	v_fmac_f32_dpp v193, v69, v97 row_shl:15 row_mask:0xf bank_mask:0xf
	v_fmac_f32_dpp v194, v70, v98 row_shl:15 row_mask:0xf bank_mask:0xf
	v_fmac_f32_dpp v195, v71, v99 row_shl:15 row_mask:0xf bank_mask:0xf
	v_fmac_f32_dpp v188, v114, v76 row_shl:14 row_mask:0xf bank_mask:0xf
	v_fmac_f32_dpp v189, v115, v77 row_shl:14 row_mask:0xf bank_mask:0xf
	v_fmac_f32_dpp v190, v116, v78 row_shl:14 row_mask:0xf bank_mask:0xf
	v_fmac_f32_dpp v191, v117, v79 row_shl:14 row_mask:0xf bank_mask:0xf
	v_fmac_f32_dpp v192, v68, v92 row_shl:14 row_mask:0xf bank_mask:0xf
	v_fmac_f32_dpp v193, v69, v93 row_shl:14 row_mask:0xf bank_mask:0xf
	v_fmac_f32_dpp v194, v70, v94 row_shl:14 row_mask:0xf bank_mask:0xf
	v_fmac_f32_dpp v195, v71, v95 row_shl:14 row_mask:0xf bank_mask:0xf
	v_pk_mul_f32 v[196:197], v[188:189], v[216:217] op_sel_hi:[1,0]
	v_pk_mul_f32 v[198:199], v[190:191], v[216:217] op_sel_hi:[1,0]
	v_exp_f32_e32 v196, v196
	v_exp_f32_e32 v197, v197
	v_exp_f32_e32 v198, v198
	v_exp_f32_e32 v199, v199
	v_pk_add_f32 v[196:197], v[196:197], v[214:215] op_sel_hi:[1,0]
	v_pk_add_f32 v[198:199], v[198:199], v[214:215] op_sel_hi:[1,0]
	v_rcp_f32_e32 v196, v196
	v_rcp_f32_e32 v197, v197
	v_rcp_f32_e32 v198, v198
	v_rcp_f32_e32 v199, v199
	v_pk_mul_f32 v[188:189], v[188:189], v[196:197]
	v_pk_mul_f32 v[190:191], v[190:191], v[198:199]
	v_pk_mul_f32 v[188:189], v[188:189], v[192:193]
	v_pk_mul_f32 v[190:191], v[190:191], v[194:195]
	v_cvt_pk_bf16_f32 v114, v188, v189
	v_cvt_pk_bf16_f32 v115, v190, v191
	s_waitcnt vmcnt(0)
	v_pk_fma_f32 v[188:189], v[60:61], v[134:135], v[130:131]
	v_pk_fma_f32 v[190:191], v[62:63], v[136:137], v[132:133]
	v_pk_fma_f32 v[192:193], v[56:57], v[204:205], v[208:209]
	v_pk_fma_f32 v[194:195], v[58:59], v[206:207], v[210:211]
	v_fmac_f32_dpp v188, v60, v142 row_shr:1 row_mask:0xf bank_mask:0xf
	v_fmac_f32_dpp v189, v61, v143 row_shr:1 row_mask:0xf bank_mask:0xf
	v_fmac_f32_dpp v190, v62, v144 row_shr:1 row_mask:0xf bank_mask:0xf
	v_fmac_f32_dpp v191, v63, v145 row_shr:1 row_mask:0xf bank_mask:0xf
	v_fmac_f32_dpp v192, v56, v110 row_shr:1 row_mask:0xf bank_mask:0xf
	v_fmac_f32_dpp v193, v57, v111 row_shr:1 row_mask:0xf bank_mask:0xf
	v_fmac_f32_dpp v194, v58, v112 row_shr:1 row_mask:0xf bank_mask:0xf
	v_fmac_f32_dpp v195, v59, v113 row_shr:1 row_mask:0xf bank_mask:0xf
	v_fmac_f32_dpp v188, v60, v154 row_shr:2 row_mask:0xf bank_mask:0xf
	v_fmac_f32_dpp v189, v61, v155 row_shr:2 row_mask:0xf bank_mask:0xf
	v_fmac_f32_dpp v190, v62, v156 row_shr:2 row_mask:0xf bank_mask:0xf
	v_fmac_f32_dpp v191, v63, v157 row_shr:2 row_mask:0xf bank_mask:0xf
	v_fmac_f32_dpp v192, v56, v118 row_shr:2 row_mask:0xf bank_mask:0xf
	v_fmac_f32_dpp v193, v57, v119 row_shr:2 row_mask:0xf bank_mask:0xf
	v_fmac_f32_dpp v194, v58, v120 row_shr:2 row_mask:0xf bank_mask:0xf
	v_fmac_f32_dpp v195, v59, v121 row_shr:2 row_mask:0xf bank_mask:0xf
	v_pk_mul_f32 v[196:197], v[188:189], v[216:217] op_sel_hi:[1,0]
	v_pk_mul_f32 v[198:199], v[190:191], v[216:217] op_sel_hi:[1,0]
	v_exp_f32_e32 v196, v196
	v_exp_f32_e32 v197, v197
	v_exp_f32_e32 v198, v198
	v_exp_f32_e32 v199, v199
	v_pk_add_f32 v[196:197], v[196:197], v[214:215] op_sel_hi:[1,0]
	v_pk_add_f32 v[198:199], v[198:199], v[214:215] op_sel_hi:[1,0]
	v_rcp_f32_e32 v196, v196
	v_rcp_f32_e32 v197, v197
	v_rcp_f32_e32 v198, v198
	v_rcp_f32_e32 v199, v199
	v_pk_mul_f32 v[188:189], v[188:189], v[196:197]
	v_pk_mul_f32 v[190:191], v[190:191], v[198:199]
	v_pk_mul_f32 v[188:189], v[188:189], v[192:193]
	v_pk_mul_f32 v[190:191], v[190:191], v[194:195]
	v_cvt_pk_bf16_f32 v202, v188, v189
	v_cvt_pk_bf16_f32 v203, v190, v191
	s_mov_b64 exec, vcc
	global_store_dwordx4 v215, v[200:203], s[96:97]
	s_mov_b64 exec, -1
	v_pk_fma_f32 v[188:189], v[52:53], v[134:135], v[130:131]
	v_pk_fma_f32 v[190:191], v[54:55], v[136:137], v[132:133]
	v_pk_fma_f32 v[192:193], v[44:45], v[204:205], v[208:209]
	v_pk_fma_f32 v[194:195], v[46:47], v[206:207], v[210:211]
	v_fmac_f32_dpp v188, v52, v142 row_shr:1 row_mask:0xf bank_mask:0xf
	v_fmac_f32_dpp v189, v53, v143 row_shr:1 row_mask:0xf bank_mask:0xf
	v_fmac_f32_dpp v190, v54, v144 row_shr:1 row_mask:0xf bank_mask:0xf
	v_fmac_f32_dpp v191, v55, v145 row_shr:1 row_mask:0xf bank_mask:0xf
	v_fmac_f32_dpp v192, v44, v110 row_shr:1 row_mask:0xf bank_mask:0xf
	v_fmac_f32_dpp v193, v45, v111 row_shr:1 row_mask:0xf bank_mask:0xf
	v_fmac_f32_dpp v194, v46, v112 row_shr:1 row_mask:0xf bank_mask:0xf
	v_fmac_f32_dpp v195, v47, v113 row_shr:1 row_mask:0xf bank_mask:0xf
	v_fmac_f32_dpp v188, v52, v154 row_shr:2 row_mask:0xf bank_mask:0xf
	v_fmac_f32_dpp v189, v53, v155 row_shr:2 row_mask:0xf bank_mask:0xf
	v_fmac_f32_dpp v190, v54, v156 row_shr:2 row_mask:0xf bank_mask:0xf
	v_fmac_f32_dpp v191, v55, v157 row_shr:2 row_mask:0xf bank_mask:0xf
	v_fmac_f32_dpp v192, v44, v118 row_shr:2 row_mask:0xf bank_mask:0xf
	v_fmac_f32_dpp v193, v45, v119 row_shr:2 row_mask:0xf bank_mask:0xf
	v_fmac_f32_dpp v194, v46, v120 row_shr:2 row_mask:0xf bank_mask:0xf
	v_fmac_f32_dpp v195, v47, v121 row_shr:2 row_mask:0xf bank_mask:0xf
	v_fmac_f32_dpp v188, v60, v142 row_shl:15 row_mask:0xf bank_mask:0xf
	v_fmac_f32_dpp v189, v61, v143 row_shl:15 row_mask:0xf bank_mask:0xf
	v_fmac_f32_dpp v190, v62, v144 row_shl:15 row_mask:0xf bank_mask:0xf
	v_fmac_f32_dpp v191, v63, v145 row_shl:15 row_mask:0xf bank_mask:0xf
	v_fmac_f32_dpp v192, v56, v110 row_shl:15 row_mask:0xf bank_mask:0xf
	v_fmac_f32_dpp v193, v57, v111 row_shl:15 row_mask:0xf bank_mask:0xf
	v_fmac_f32_dpp v194, v58, v112 row_shl:15 row_mask:0xf bank_mask:0xf
	v_fmac_f32_dpp v195, v59, v113 row_shl:15 row_mask:0xf bank_mask:0xf
	v_fmac_f32_dpp v188, v60, v154 row_shl:14 row_mask:0xf bank_mask:0xf
	v_fmac_f32_dpp v189, v61, v155 row_shl:14 row_mask:0xf bank_mask:0xf
	v_fmac_f32_dpp v190, v62, v156 row_shl:14 row_mask:0xf bank_mask:0xf
	v_fmac_f32_dpp v191, v63, v157 row_shl:14 row_mask:0xf bank_mask:0xf
	v_fmac_f32_dpp v192, v56, v118 row_shl:14 row_mask:0xf bank_mask:0xf
	v_fmac_f32_dpp v193, v57, v119 row_shl:14 row_mask:0xf bank_mask:0xf
	v_fmac_f32_dpp v194, v58, v120 row_shl:14 row_mask:0xf bank_mask:0xf
	v_fmac_f32_dpp v195, v59, v121 row_shl:14 row_mask:0xf bank_mask:0xf
	v_pk_mul_f32 v[196:197], v[188:189], v[216:217] op_sel_hi:[1,0]
	v_pk_mul_f32 v[198:199], v[190:191], v[216:217] op_sel_hi:[1,0]
	v_exp_f32_e32 v196, v196
	v_exp_f32_e32 v197, v197
	v_exp_f32_e32 v198, v198
	v_exp_f32_e32 v199, v199
	v_pk_add_f32 v[196:197], v[196:197], v[214:215] op_sel_hi:[1,0]
	v_pk_add_f32 v[198:199], v[198:199], v[214:215] op_sel_hi:[1,0]
	v_rcp_f32_e32 v196, v196
	v_rcp_f32_e32 v197, v197
	v_rcp_f32_e32 v198, v198
	v_rcp_f32_e32 v199, v199
	v_pk_mul_f32 v[188:189], v[188:189], v[196:197]
	v_pk_mul_f32 v[190:191], v[190:191], v[198:199]
	v_pk_mul_f32 v[188:189], v[188:189], v[192:193]
	v_pk_mul_f32 v[190:191], v[190:191], v[194:195]
	v_cvt_pk_bf16_f32 v160, v188, v189
	v_cvt_pk_bf16_f32 v161, v190, v191
	v_add_u32_e32 v213, 0x2c000, v215
	global_store_dwordx4 v213, v[158:161], s[96:97]
	v_pk_fma_f32 v[188:189], v[48:49], v[134:135], v[130:131]
	v_pk_fma_f32 v[190:191], v[50:51], v[136:137], v[132:133]
	v_pk_fma_f32 v[192:193], v[36:37], v[204:205], v[208:209]
	v_pk_fma_f32 v[194:195], v[38:39], v[206:207], v[210:211]
	v_fmac_f32_dpp v188, v48, v142 row_shr:1 row_mask:0xf bank_mask:0xf
	v_fmac_f32_dpp v189, v49, v143 row_shr:1 row_mask:0xf bank_mask:0xf
	v_fmac_f32_dpp v190, v50, v144 row_shr:1 row_mask:0xf bank_mask:0xf
	v_fmac_f32_dpp v191, v51, v145 row_shr:1 row_mask:0xf bank_mask:0xf
	v_fmac_f32_dpp v192, v36, v110 row_shr:1 row_mask:0xf bank_mask:0xf
	v_fmac_f32_dpp v193, v37, v111 row_shr:1 row_mask:0xf bank_mask:0xf
	v_fmac_f32_dpp v194, v38, v112 row_shr:1 row_mask:0xf bank_mask:0xf
	v_fmac_f32_dpp v195, v39, v113 row_shr:1 row_mask:0xf bank_mask:0xf
	v_fmac_f32_dpp v188, v48, v154 row_shr:2 row_mask:0xf bank_mask:0xf
	v_fmac_f32_dpp v189, v49, v155 row_shr:2 row_mask:0xf bank_mask:0xf
	v_fmac_f32_dpp v190, v50, v156 row_shr:2 row_mask:0xf bank_mask:0xf
	v_fmac_f32_dpp v191, v51, v157 row_shr:2 row_mask:0xf bank_mask:0xf
	v_fmac_f32_dpp v192, v36, v118 row_shr:2 row_mask:0xf bank_mask:0xf
	v_fmac_f32_dpp v193, v37, v119 row_shr:2 row_mask:0xf bank_mask:0xf
	v_fmac_f32_dpp v194, v38, v120 row_shr:2 row_mask:0xf bank_mask:0xf
	v_fmac_f32_dpp v195, v39, v121 row_shr:2 row_mask:0xf bank_mask:0xf
	v_fmac_f32_dpp v188, v52, v142 row_shl:15 row_mask:0xf bank_mask:0xf
	v_fmac_f32_dpp v189, v53, v143 row_shl:15 row_mask:0xf bank_mask:0xf
	v_fmac_f32_dpp v190, v54, v144 row_shl:15 row_mask:0xf bank_mask:0xf
	v_fmac_f32_dpp v191, v55, v145 row_shl:15 row_mask:0xf bank_mask:0xf
	v_fmac_f32_dpp v192, v44, v110 row_shl:15 row_mask:0xf bank_mask:0xf
	v_fmac_f32_dpp v193, v45, v111 row_shl:15 row_mask:0xf bank_mask:0xf
	v_fmac_f32_dpp v194, v46, v112 row_shl:15 row_mask:0xf bank_mask:0xf
	v_fmac_f32_dpp v195, v47, v113 row_shl:15 row_mask:0xf bank_mask:0xf
	v_fmac_f32_dpp v188, v52, v154 row_shl:14 row_mask:0xf bank_mask:0xf
	v_fmac_f32_dpp v189, v53, v155 row_shl:14 row_mask:0xf bank_mask:0xf
	v_fmac_f32_dpp v190, v54, v156 row_shl:14 row_mask:0xf bank_mask:0xf
	v_fmac_f32_dpp v191, v55, v157 row_shl:14 row_mask:0xf bank_mask:0xf
	v_fmac_f32_dpp v192, v44, v118 row_shl:14 row_mask:0xf bank_mask:0xf
	v_fmac_f32_dpp v193, v45, v119 row_shl:14 row_mask:0xf bank_mask:0xf
	v_fmac_f32_dpp v194, v46, v120 row_shl:14 row_mask:0xf bank_mask:0xf
	v_fmac_f32_dpp v195, v47, v121 row_shl:14 row_mask:0xf bank_mask:0xf
	v_pk_mul_f32 v[196:197], v[188:189], v[216:217] op_sel_hi:[1,0]
	v_pk_mul_f32 v[198:199], v[190:191], v[216:217] op_sel_hi:[1,0]
	v_exp_f32_e32 v196, v196
	v_exp_f32_e32 v197, v197
	v_exp_f32_e32 v198, v198
	v_exp_f32_e32 v199, v199
	v_pk_add_f32 v[196:197], v[196:197], v[214:215] op_sel_hi:[1,0]
	v_pk_add_f32 v[198:199], v[198:199], v[214:215] op_sel_hi:[1,0]
	v_rcp_f32_e32 v196, v196
	v_rcp_f32_e32 v197, v197
	v_rcp_f32_e32 v198, v198
	v_rcp_f32_e32 v199, v199
	v_pk_mul_f32 v[188:189], v[188:189], v[196:197]
	v_pk_mul_f32 v[190:191], v[190:191], v[198:199]
	v_pk_mul_f32 v[188:189], v[188:189], v[192:193]
	v_pk_mul_f32 v[190:191], v[190:191], v[194:195]
	v_cvt_pk_bf16_f32 v152, v188, v189
	v_cvt_pk_bf16_f32 v153, v190, v191
	v_add_u32_e32 v213, 0x58000, v215
	global_store_dwordx4 v213, v[150:153], s[96:97]
	v_pk_fma_f32 v[188:189], v[40:41], v[134:135], v[130:131]
	v_pk_fma_f32 v[190:191], v[42:43], v[136:137], v[132:133]
	v_pk_fma_f32 v[192:193], v[32:33], v[204:205], v[208:209]
	v_pk_fma_f32 v[194:195], v[34:35], v[206:207], v[210:211]
	v_fmac_f32_dpp v188, v40, v142 row_shr:1 row_mask:0xf bank_mask:0xf
	v_fmac_f32_dpp v189, v41, v143 row_shr:1 row_mask:0xf bank_mask:0xf
	v_fmac_f32_dpp v190, v42, v144 row_shr:1 row_mask:0xf bank_mask:0xf
	v_fmac_f32_dpp v191, v43, v145 row_shr:1 row_mask:0xf bank_mask:0xf
	v_fmac_f32_dpp v192, v32, v110 row_shr:1 row_mask:0xf bank_mask:0xf
	v_fmac_f32_dpp v193, v33, v111 row_shr:1 row_mask:0xf bank_mask:0xf
	v_fmac_f32_dpp v194, v34, v112 row_shr:1 row_mask:0xf bank_mask:0xf
	v_fmac_f32_dpp v195, v35, v113 row_shr:1 row_mask:0xf bank_mask:0xf
	v_fmac_f32_dpp v188, v40, v154 row_shr:2 row_mask:0xf bank_mask:0xf
	v_fmac_f32_dpp v189, v41, v155 row_shr:2 row_mask:0xf bank_mask:0xf
	v_fmac_f32_dpp v190, v42, v156 row_shr:2 row_mask:0xf bank_mask:0xf
	v_fmac_f32_dpp v191, v43, v157 row_shr:2 row_mask:0xf bank_mask:0xf
	v_fmac_f32_dpp v192, v32, v118 row_shr:2 row_mask:0xf bank_mask:0xf
	v_fmac_f32_dpp v193, v33, v119 row_shr:2 row_mask:0xf bank_mask:0xf
	v_fmac_f32_dpp v194, v34, v120 row_shr:2 row_mask:0xf bank_mask:0xf
	v_fmac_f32_dpp v195, v35, v121 row_shr:2 row_mask:0xf bank_mask:0xf
	v_fmac_f32_dpp v188, v48, v142 row_shl:15 row_mask:0xf bank_mask:0xf
	v_fmac_f32_dpp v189, v49, v143 row_shl:15 row_mask:0xf bank_mask:0xf
	v_fmac_f32_dpp v190, v50, v144 row_shl:15 row_mask:0xf bank_mask:0xf
	v_fmac_f32_dpp v191, v51, v145 row_shl:15 row_mask:0xf bank_mask:0xf
	v_fmac_f32_dpp v192, v36, v110 row_shl:15 row_mask:0xf bank_mask:0xf
	v_fmac_f32_dpp v193, v37, v111 row_shl:15 row_mask:0xf bank_mask:0xf
	v_fmac_f32_dpp v194, v38, v112 row_shl:15 row_mask:0xf bank_mask:0xf
	v_fmac_f32_dpp v195, v39, v113 row_shl:15 row_mask:0xf bank_mask:0xf
	v_fmac_f32_dpp v188, v48, v154 row_shl:14 row_mask:0xf bank_mask:0xf
	v_fmac_f32_dpp v189, v49, v155 row_shl:14 row_mask:0xf bank_mask:0xf
	v_fmac_f32_dpp v190, v50, v156 row_shl:14 row_mask:0xf bank_mask:0xf
	v_fmac_f32_dpp v191, v51, v157 row_shl:14 row_mask:0xf bank_mask:0xf
	v_fmac_f32_dpp v192, v36, v118 row_shl:14 row_mask:0xf bank_mask:0xf
	v_fmac_f32_dpp v193, v37, v119 row_shl:14 row_mask:0xf bank_mask:0xf
	v_fmac_f32_dpp v194, v38, v120 row_shl:14 row_mask:0xf bank_mask:0xf
	v_fmac_f32_dpp v195, v39, v121 row_shl:14 row_mask:0xf bank_mask:0xf
	v_pk_mul_f32 v[196:197], v[188:189], v[216:217] op_sel_hi:[1,0]
	v_pk_mul_f32 v[198:199], v[190:191], v[216:217] op_sel_hi:[1,0]
	v_exp_f32_e32 v196, v196
	v_exp_f32_e32 v197, v197
	v_exp_f32_e32 v198, v198
	v_exp_f32_e32 v199, v199
	v_pk_add_f32 v[196:197], v[196:197], v[214:215] op_sel_hi:[1,0]
	v_pk_add_f32 v[198:199], v[198:199], v[214:215] op_sel_hi:[1,0]
	v_rcp_f32_e32 v196, v196
	v_rcp_f32_e32 v197, v197
	v_rcp_f32_e32 v198, v198
	v_rcp_f32_e32 v199, v199
	v_pk_mul_f32 v[188:189], v[188:189], v[196:197]
	v_pk_mul_f32 v[190:191], v[190:191], v[198:199]
	v_pk_mul_f32 v[188:189], v[188:189], v[192:193]
	v_pk_mul_f32 v[190:191], v[190:191], v[194:195]
	v_cvt_pk_bf16_f32 v148, v188, v189
	v_cvt_pk_bf16_f32 v149, v190, v191
	v_add_u32_e32 v213, 0x84000, v215
	global_store_dwordx4 v213, v[146:149], s[96:97]
	v_pk_fma_f32 v[188:189], v[28:29], v[134:135], v[130:131]
	v_pk_fma_f32 v[190:191], v[30:31], v[136:137], v[132:133]
	v_pk_fma_f32 v[192:193], v[16:17], v[204:205], v[208:209]
	v_pk_fma_f32 v[194:195], v[18:19], v[206:207], v[210:211]
	v_fmac_f32_dpp v188, v28, v142 row_shr:1 row_mask:0xf bank_mask:0xf
	v_fmac_f32_dpp v189, v29, v143 row_shr:1 row_mask:0xf bank_mask:0xf
	v_fmac_f32_dpp v190, v30, v144 row_shr:1 row_mask:0xf bank_mask:0xf
	v_fmac_f32_dpp v191, v31, v145 row_shr:1 row_mask:0xf bank_mask:0xf
	v_fmac_f32_dpp v192, v16, v110 row_shr:1 row_mask:0xf bank_mask:0xf
	v_fmac_f32_dpp v193, v17, v111 row_shr:1 row_mask:0xf bank_mask:0xf
	v_fmac_f32_dpp v194, v18, v112 row_shr:1 row_mask:0xf bank_mask:0xf
	v_fmac_f32_dpp v195, v19, v113 row_shr:1 row_mask:0xf bank_mask:0xf
	v_fmac_f32_dpp v188, v28, v154 row_shr:2 row_mask:0xf bank_mask:0xf
	v_fmac_f32_dpp v189, v29, v155 row_shr:2 row_mask:0xf bank_mask:0xf
	v_fmac_f32_dpp v190, v30, v156 row_shr:2 row_mask:0xf bank_mask:0xf
	v_fmac_f32_dpp v191, v31, v157 row_shr:2 row_mask:0xf bank_mask:0xf
	v_fmac_f32_dpp v192, v16, v118 row_shr:2 row_mask:0xf bank_mask:0xf
	v_fmac_f32_dpp v193, v17, v119 row_shr:2 row_mask:0xf bank_mask:0xf
	v_fmac_f32_dpp v194, v18, v120 row_shr:2 row_mask:0xf bank_mask:0xf
	v_fmac_f32_dpp v195, v19, v121 row_shr:2 row_mask:0xf bank_mask:0xf
	v_fmac_f32_dpp v188, v40, v142 row_shl:15 row_mask:0xf bank_mask:0xf
	v_fmac_f32_dpp v189, v41, v143 row_shl:15 row_mask:0xf bank_mask:0xf
	v_fmac_f32_dpp v190, v42, v144 row_shl:15 row_mask:0xf bank_mask:0xf
	v_fmac_f32_dpp v191, v43, v145 row_shl:15 row_mask:0xf bank_mask:0xf
	v_fmac_f32_dpp v192, v32, v110 row_shl:15 row_mask:0xf bank_mask:0xf
	v_fmac_f32_dpp v193, v33, v111 row_shl:15 row_mask:0xf bank_mask:0xf
	v_fmac_f32_dpp v194, v34, v112 row_shl:15 row_mask:0xf bank_mask:0xf
	v_fmac_f32_dpp v195, v35, v113 row_shl:15 row_mask:0xf bank_mask:0xf
	v_fmac_f32_dpp v188, v40, v154 row_shl:14 row_mask:0xf bank_mask:0xf
	v_fmac_f32_dpp v189, v41, v155 row_shl:14 row_mask:0xf bank_mask:0xf
	v_fmac_f32_dpp v190, v42, v156 row_shl:14 row_mask:0xf bank_mask:0xf
	v_fmac_f32_dpp v191, v43, v157 row_shl:14 row_mask:0xf bank_mask:0xf
	v_fmac_f32_dpp v192, v32, v118 row_shl:14 row_mask:0xf bank_mask:0xf
	v_fmac_f32_dpp v193, v33, v119 row_shl:14 row_mask:0xf bank_mask:0xf
	v_fmac_f32_dpp v194, v34, v120 row_shl:14 row_mask:0xf bank_mask:0xf
	v_fmac_f32_dpp v195, v35, v121 row_shl:14 row_mask:0xf bank_mask:0xf
	v_pk_mul_f32 v[196:197], v[188:189], v[216:217] op_sel_hi:[1,0]
	v_pk_mul_f32 v[198:199], v[190:191], v[216:217] op_sel_hi:[1,0]
	v_exp_f32_e32 v196, v196
	v_exp_f32_e32 v197, v197
	v_exp_f32_e32 v198, v198
	v_exp_f32_e32 v199, v199
	v_pk_add_f32 v[196:197], v[196:197], v[214:215] op_sel_hi:[1,0]
	v_pk_add_f32 v[198:199], v[198:199], v[214:215] op_sel_hi:[1,0]
	v_rcp_f32_e32 v196, v196
	v_rcp_f32_e32 v197, v197
	v_rcp_f32_e32 v198, v198
	v_rcp_f32_e32 v199, v199
	v_pk_mul_f32 v[188:189], v[188:189], v[196:197]
	v_pk_mul_f32 v[190:191], v[190:191], v[198:199]
	v_pk_mul_f32 v[188:189], v[188:189], v[192:193]
	v_pk_mul_f32 v[190:191], v[190:191], v[194:195]
	v_cvt_pk_bf16_f32 v140, v188, v189
	v_cvt_pk_bf16_f32 v141, v190, v191
	v_add_u32_e32 v213, 0xb0000, v215
	global_store_dwordx4 v213, v[138:141], s[96:97]
	v_pk_fma_f32 v[188:189], v[24:25], v[134:135], v[130:131]
	v_pk_fma_f32 v[190:191], v[26:27], v[136:137], v[132:133]
	v_pk_fma_f32 v[192:193], v[12:13], v[204:205], v[208:209]
	v_pk_fma_f32 v[194:195], v[14:15], v[206:207], v[210:211]
	v_fmac_f32_dpp v188, v24, v142 row_shr:1 row_mask:0xf bank_mask:0xf
	v_fmac_f32_dpp v189, v25, v143 row_shr:1 row_mask:0xf bank_mask:0xf
	v_fmac_f32_dpp v190, v26, v144 row_shr:1 row_mask:0xf bank_mask:0xf
	v_fmac_f32_dpp v191, v27, v145 row_shr:1 row_mask:0xf bank_mask:0xf
	v_fmac_f32_dpp v192, v12, v110 row_shr:1 row_mask:0xf bank_mask:0xf
	v_fmac_f32_dpp v193, v13, v111 row_shr:1 row_mask:0xf bank_mask:0xf
	v_fmac_f32_dpp v194, v14, v112 row_shr:1 row_mask:0xf bank_mask:0xf
	v_fmac_f32_dpp v195, v15, v113 row_shr:1 row_mask:0xf bank_mask:0xf
	v_fmac_f32_dpp v188, v24, v154 row_shr:2 row_mask:0xf bank_mask:0xf
	v_fmac_f32_dpp v189, v25, v155 row_shr:2 row_mask:0xf bank_mask:0xf
	v_fmac_f32_dpp v190, v26, v156 row_shr:2 row_mask:0xf bank_mask:0xf
	v_fmac_f32_dpp v191, v27, v157 row_shr:2 row_mask:0xf bank_mask:0xf
	v_fmac_f32_dpp v192, v12, v118 row_shr:2 row_mask:0xf bank_mask:0xf
	v_fmac_f32_dpp v193, v13, v119 row_shr:2 row_mask:0xf bank_mask:0xf
	v_fmac_f32_dpp v194, v14, v120 row_shr:2 row_mask:0xf bank_mask:0xf
	v_fmac_f32_dpp v195, v15, v121 row_shr:2 row_mask:0xf bank_mask:0xf
	v_fmac_f32_dpp v188, v28, v142 row_shl:15 row_mask:0xf bank_mask:0xf
	v_fmac_f32_dpp v189, v29, v143 row_shl:15 row_mask:0xf bank_mask:0xf
	v_fmac_f32_dpp v190, v30, v144 row_shl:15 row_mask:0xf bank_mask:0xf
	v_fmac_f32_dpp v191, v31, v145 row_shl:15 row_mask:0xf bank_mask:0xf
	v_fmac_f32_dpp v192, v16, v110 row_shl:15 row_mask:0xf bank_mask:0xf
	v_fmac_f32_dpp v193, v17, v111 row_shl:15 row_mask:0xf bank_mask:0xf
	v_fmac_f32_dpp v194, v18, v112 row_shl:15 row_mask:0xf bank_mask:0xf
	v_fmac_f32_dpp v195, v19, v113 row_shl:15 row_mask:0xf bank_mask:0xf
	v_fmac_f32_dpp v188, v28, v154 row_shl:14 row_mask:0xf bank_mask:0xf
	v_fmac_f32_dpp v189, v29, v155 row_shl:14 row_mask:0xf bank_mask:0xf
	v_fmac_f32_dpp v190, v30, v156 row_shl:14 row_mask:0xf bank_mask:0xf
	v_fmac_f32_dpp v191, v31, v157 row_shl:14 row_mask:0xf bank_mask:0xf
	v_fmac_f32_dpp v192, v16, v118 row_shl:14 row_mask:0xf bank_mask:0xf
	v_fmac_f32_dpp v193, v17, v119 row_shl:14 row_mask:0xf bank_mask:0xf
	v_fmac_f32_dpp v194, v18, v120 row_shl:14 row_mask:0xf bank_mask:0xf
	v_fmac_f32_dpp v195, v19, v121 row_shl:14 row_mask:0xf bank_mask:0xf
	v_pk_mul_f32 v[196:197], v[188:189], v[216:217] op_sel_hi:[1,0]
	v_pk_mul_f32 v[198:199], v[190:191], v[216:217] op_sel_hi:[1,0]
	v_exp_f32_e32 v196, v196
	v_exp_f32_e32 v197, v197
	v_exp_f32_e32 v198, v198
	v_exp_f32_e32 v199, v199
	v_pk_add_f32 v[196:197], v[196:197], v[214:215] op_sel_hi:[1,0]
	v_pk_add_f32 v[198:199], v[198:199], v[214:215] op_sel_hi:[1,0]
	v_rcp_f32_e32 v196, v196
	v_rcp_f32_e32 v197, v197
	v_rcp_f32_e32 v198, v198
	v_rcp_f32_e32 v199, v199
	v_pk_mul_f32 v[188:189], v[188:189], v[196:197]
	v_pk_mul_f32 v[190:191], v[190:191], v[198:199]
	v_pk_mul_f32 v[188:189], v[188:189], v[192:193]
	v_pk_mul_f32 v[190:191], v[190:191], v[194:195]
	v_cvt_pk_bf16_f32 v128, v188, v189
	v_cvt_pk_bf16_f32 v129, v190, v191
	v_add_u32_e32 v213, 0xdc000, v215
	global_store_dwordx4 v213, v[126:129], s[96:97]
	v_pk_fma_f32 v[188:189], v[20:21], v[134:135], v[130:131]
	v_pk_fma_f32 v[190:191], v[22:23], v[136:137], v[132:133]
	v_pk_fma_f32 v[192:193], v[8:9], v[204:205], v[208:209]
	v_pk_fma_f32 v[194:195], v[10:11], v[206:207], v[210:211]
	v_fmac_f32_dpp v188, v20, v142 row_shr:1 row_mask:0xf bank_mask:0xf
	v_fmac_f32_dpp v189, v21, v143 row_shr:1 row_mask:0xf bank_mask:0xf
	v_fmac_f32_dpp v190, v22, v144 row_shr:1 row_mask:0xf bank_mask:0xf
	v_fmac_f32_dpp v191, v23, v145 row_shr:1 row_mask:0xf bank_mask:0xf
	v_fmac_f32_dpp v192, v8, v110 row_shr:1 row_mask:0xf bank_mask:0xf
	v_fmac_f32_dpp v193, v9, v111 row_shr:1 row_mask:0xf bank_mask:0xf
	v_fmac_f32_dpp v194, v10, v112 row_shr:1 row_mask:0xf bank_mask:0xf
	v_fmac_f32_dpp v195, v11, v113 row_shr:1 row_mask:0xf bank_mask:0xf
	v_fmac_f32_dpp v188, v20, v154 row_shr:2 row_mask:0xf bank_mask:0xf
	v_fmac_f32_dpp v189, v21, v155 row_shr:2 row_mask:0xf bank_mask:0xf
	v_fmac_f32_dpp v190, v22, v156 row_shr:2 row_mask:0xf bank_mask:0xf
	v_fmac_f32_dpp v191, v23, v157 row_shr:2 row_mask:0xf bank_mask:0xf
	v_fmac_f32_dpp v192, v8, v118 row_shr:2 row_mask:0xf bank_mask:0xf
	v_fmac_f32_dpp v193, v9, v119 row_shr:2 row_mask:0xf bank_mask:0xf
	v_fmac_f32_dpp v194, v10, v120 row_shr:2 row_mask:0xf bank_mask:0xf
	v_fmac_f32_dpp v195, v11, v121 row_shr:2 row_mask:0xf bank_mask:0xf
	v_fmac_f32_dpp v188, v24, v142 row_shl:15 row_mask:0xf bank_mask:0xf
	v_fmac_f32_dpp v189, v25, v143 row_shl:15 row_mask:0xf bank_mask:0xf
	v_fmac_f32_dpp v190, v26, v144 row_shl:15 row_mask:0xf bank_mask:0xf
	v_fmac_f32_dpp v191, v27, v145 row_shl:15 row_mask:0xf bank_mask:0xf
	v_fmac_f32_dpp v192, v12, v110 row_shl:15 row_mask:0xf bank_mask:0xf
	v_fmac_f32_dpp v193, v13, v111 row_shl:15 row_mask:0xf bank_mask:0xf
	v_fmac_f32_dpp v194, v14, v112 row_shl:15 row_mask:0xf bank_mask:0xf
	v_fmac_f32_dpp v195, v15, v113 row_shl:15 row_mask:0xf bank_mask:0xf
	v_fmac_f32_dpp v188, v24, v154 row_shl:14 row_mask:0xf bank_mask:0xf
	v_fmac_f32_dpp v189, v25, v155 row_shl:14 row_mask:0xf bank_mask:0xf
	v_fmac_f32_dpp v190, v26, v156 row_shl:14 row_mask:0xf bank_mask:0xf
	v_fmac_f32_dpp v191, v27, v157 row_shl:14 row_mask:0xf bank_mask:0xf
	v_fmac_f32_dpp v192, v12, v118 row_shl:14 row_mask:0xf bank_mask:0xf
	v_fmac_f32_dpp v193, v13, v119 row_shl:14 row_mask:0xf bank_mask:0xf
	v_fmac_f32_dpp v194, v14, v120 row_shl:14 row_mask:0xf bank_mask:0xf
	v_fmac_f32_dpp v195, v15, v121 row_shl:14 row_mask:0xf bank_mask:0xf
	v_pk_mul_f32 v[196:197], v[188:189], v[216:217] op_sel_hi:[1,0]
	v_pk_mul_f32 v[198:199], v[190:191], v[216:217] op_sel_hi:[1,0]
	v_exp_f32_e32 v196, v196
	v_exp_f32_e32 v197, v197
	v_exp_f32_e32 v198, v198
	v_exp_f32_e32 v199, v199
	v_pk_add_f32 v[196:197], v[196:197], v[214:215] op_sel_hi:[1,0]
	v_pk_add_f32 v[198:199], v[198:199], v[214:215] op_sel_hi:[1,0]
	v_rcp_f32_e32 v196, v196
	v_rcp_f32_e32 v197, v197
	v_rcp_f32_e32 v198, v198
	v_rcp_f32_e32 v199, v199
	v_pk_mul_f32 v[188:189], v[188:189], v[196:197]
	v_pk_mul_f32 v[190:191], v[190:191], v[198:199]
	v_pk_mul_f32 v[188:189], v[188:189], v[192:193]
	v_pk_mul_f32 v[190:191], v[190:191], v[194:195]
	v_cvt_pk_bf16_f32 v124, v188, v189
	v_cvt_pk_bf16_f32 v125, v190, v191
	v_add_u32_e32 v213, 0x108000, v215
	global_store_dwordx4 v213, v[122:125], s[96:97]
	v_pk_fma_f32 v[188:189], v[4:5], v[134:135], v[130:131]
	v_pk_fma_f32 v[190:191], v[6:7], v[136:137], v[132:133]
	v_pk_fma_f32 v[192:193], v[0:1], v[204:205], v[208:209]
	v_pk_fma_f32 v[194:195], v[2:3], v[206:207], v[210:211]
	v_fmac_f32_dpp v188, v4, v142 row_shr:1 row_mask:0xf bank_mask:0xf
	v_fmac_f32_dpp v189, v5, v143 row_shr:1 row_mask:0xf bank_mask:0xf
	v_fmac_f32_dpp v190, v6, v144 row_shr:1 row_mask:0xf bank_mask:0xf
	v_fmac_f32_dpp v191, v7, v145 row_shr:1 row_mask:0xf bank_mask:0xf
	v_fmac_f32_dpp v192, v0, v110 row_shr:1 row_mask:0xf bank_mask:0xf
	v_fmac_f32_dpp v193, v1, v111 row_shr:1 row_mask:0xf bank_mask:0xf
	v_fmac_f32_dpp v194, v2, v112 row_shr:1 row_mask:0xf bank_mask:0xf
	v_fmac_f32_dpp v195, v3, v113 row_shr:1 row_mask:0xf bank_mask:0xf
	v_fmac_f32_dpp v188, v4, v154 row_shr:2 row_mask:0xf bank_mask:0xf
	v_fmac_f32_dpp v189, v5, v155 row_shr:2 row_mask:0xf bank_mask:0xf
	v_fmac_f32_dpp v190, v6, v156 row_shr:2 row_mask:0xf bank_mask:0xf
	v_fmac_f32_dpp v191, v7, v157 row_shr:2 row_mask:0xf bank_mask:0xf
	v_fmac_f32_dpp v192, v0, v118 row_shr:2 row_mask:0xf bank_mask:0xf
	v_fmac_f32_dpp v193, v1, v119 row_shr:2 row_mask:0xf bank_mask:0xf
	v_fmac_f32_dpp v194, v2, v120 row_shr:2 row_mask:0xf bank_mask:0xf
	v_fmac_f32_dpp v195, v3, v121 row_shr:2 row_mask:0xf bank_mask:0xf
	v_fmac_f32_dpp v188, v20, v142 row_shl:15 row_mask:0xf bank_mask:0xf
	v_fmac_f32_dpp v189, v21, v143 row_shl:15 row_mask:0xf bank_mask:0xf
	v_fmac_f32_dpp v190, v22, v144 row_shl:15 row_mask:0xf bank_mask:0xf
	v_fmac_f32_dpp v191, v23, v145 row_shl:15 row_mask:0xf bank_mask:0xf
	v_fmac_f32_dpp v192, v8, v110 row_shl:15 row_mask:0xf bank_mask:0xf
	v_fmac_f32_dpp v193, v9, v111 row_shl:15 row_mask:0xf bank_mask:0xf
	v_fmac_f32_dpp v194, v10, v112 row_shl:15 row_mask:0xf bank_mask:0xf
	v_fmac_f32_dpp v195, v11, v113 row_shl:15 row_mask:0xf bank_mask:0xf
	v_fmac_f32_dpp v188, v20, v154 row_shl:14 row_mask:0xf bank_mask:0xf
	v_fmac_f32_dpp v189, v21, v155 row_shl:14 row_mask:0xf bank_mask:0xf
	v_fmac_f32_dpp v190, v22, v156 row_shl:14 row_mask:0xf bank_mask:0xf
	v_fmac_f32_dpp v191, v23, v157 row_shl:14 row_mask:0xf bank_mask:0xf
	v_fmac_f32_dpp v192, v8, v118 row_shl:14 row_mask:0xf bank_mask:0xf
	v_fmac_f32_dpp v193, v9, v119 row_shl:14 row_mask:0xf bank_mask:0xf
	v_fmac_f32_dpp v194, v10, v120 row_shl:14 row_mask:0xf bank_mask:0xf
	v_fmac_f32_dpp v195, v11, v121 row_shl:14 row_mask:0xf bank_mask:0xf
	v_pk_mul_f32 v[196:197], v[188:189], v[216:217] op_sel_hi:[1,0]
	v_pk_mul_f32 v[198:199], v[190:191], v[216:217] op_sel_hi:[1,0]
	v_exp_f32_e32 v196, v196
	v_exp_f32_e32 v197, v197
	v_exp_f32_e32 v198, v198
	v_exp_f32_e32 v199, v199
	v_pk_add_f32 v[196:197], v[196:197], v[214:215] op_sel_hi:[1,0]
	v_pk_add_f32 v[198:199], v[198:199], v[214:215] op_sel_hi:[1,0]
	v_rcp_f32_e32 v196, v196
	v_rcp_f32_e32 v197, v197
	v_rcp_f32_e32 v198, v198
	v_rcp_f32_e32 v199, v199
	v_pk_mul_f32 v[188:189], v[188:189], v[196:197]
	v_pk_mul_f32 v[190:191], v[190:191], v[198:199]
	v_pk_mul_f32 v[188:189], v[188:189], v[192:193]
	v_pk_mul_f32 v[190:191], v[190:191], v[194:195]
	v_cvt_pk_bf16_f32 v116, v188, v189
	v_cvt_pk_bf16_f32 v117, v190, v191
	v_add_u32_e32 v213, 0x134000, v215
	global_store_dwordx4 v213, v[114:117], s[96:97]
	s_add_i32 s98, s98, 1
	s_branch .LBB0_359

.LBB0_835:
	s_mov_b64 s[18:19], 0x80
	s_lshl_b32 s1, s12, 5
	s_add_i32 m0, s48, 0x18000
	v_lshl_add_u64 v[6:7], v[6:7], 0, s[18:19]
	s_and_b32 s53, s1, 0x60
	s_waitcnt vmcnt(4)
	s_barrier
	global_load_lds_dwordx4 v[6:7], off
	v_lshl_add_u64 v[4:5], v[4:5], 0, s[18:19]
	s_add_i32 m0, s48, 0x1a000
	s_add_i32 s54, s48, 0x8000
	s_add_i32 s55, s48, 0xa000
	global_load_lds_dwordx4 v[4:5], off
	v_lshl_add_u64 v[2:3], v[2:3], 0, s[18:19]
	s_mov_b32 m0, s54
	s_add_u32 s12, s10, 0x1600080
	global_load_lds_dwordx4 v[2:3], off
	v_lshl_add_u64 v[0:1], v[0:1], 0, s[18:19]
	s_mov_b32 m0, s55
	s_addc_u32 s13, s11, 0
	global_load_lds_dwordx4 v[0:1], off
	s_add_i32 m0, s48, 0x1c000
	v_lshl_add_u64 v[0:1], s[12:13], 0, v[164:165]
	global_load_lds_dwordx4 v[0:1], off
	v_lshl_add_u64 v[0:1], s[12:13], 0, v[166:167]
	s_add_i32 m0, s48, 0x1e000
	s_ashr_i32 s56, s94, 31
	global_load_lds_dwordx4 v[0:1], off
	s_lshl_b32 s58, s7, 7
	s_lshl_b32 s59, s7, 2
	s_add_u32 s20, s82, 0x2c000
	s_addc_u32 s21, s83, 0
	s_add_u32 s22, s82, 0x37000
	s_addc_u32 s23, s83, 0
	s_add_u32 s24, s82, 0x26800
	s_addc_u32 s25, s83, 0
	s_add_u32 s26, s82, 0x31800
	v_add3_u32 v0, v9, v221, v218
	s_addc_u32 s27, s83, 0
	v_lshl_or_b32 v0, v0, 12, v226
	s_sext_i32_i16 s1, s6
	v_lshl_or_b32 v2, s7, 13, v230
	s_add_u32 s28, s82, 0x3c800
	v_add_u32_e32 v0, v0, v224
	v_mov_b32_e32 v1, v165
	s_mov_b64 s[6:7], 0x40080
	s_addc_u32 s29, s83, 0
	v_add3_u32 v0, v8, v220, v218
	s_waitcnt vmcnt(6)
	s_add_u32 s30, s84, 0x10800
	v_lshl_or_b32 v0, v0, 12, v226
	s_addc_u32 s31, s85, 0
	v_add_u32_e32 v0, v0, v224
	s_add_i32 s60, 0, 0x10000
	s_add_i32 s61, 0, 0x14000
	s_mov_b32 s57, s94
	v_mov_b64_e32 v[184:185], 0xb00
	v_mov_b64_e32 v[186:187], 0xaff
	v_mov_b32_e32 v230, 0x3727c5ac
	s_mov_b32 s62, 0xb000
	s_movk_i32 s63, 0x2c00
	s_barrier
	s_mov_b32 s98, 0
	s_branch .LBB0_837

.LBB0_840:
	ds_read_b128 v[76:79], v171
	v_xor_b32_e32 v91, 64, v171
	ds_read_b128 v[80:83], v91
	ds_read_b128 v[84:87], v171 offset:2048
	ds_read_b128 v[88:91], v91 offset:2048
	s_add_u32 s10, s8, 0x100
	s_addc_u32 s11, s9, 0
	s_cmp_eq_u32 s67, 28
	s_cselect_b32 s43, s33, s11
	s_cselect_b32 s42, s37, s10
	s_cselect_b32 s13, s35, s66
	s_cselect_b32 s12, s64, s65
	v_lshl_add_u64 v[108:109], s[8:9], 0, v[180:181]
	s_add_i32 m0, s48, 0xc000
	ds_read_b128 v[92:95], v173
	v_xor_b32_e32 v203, 64, v173
	ds_read_b128 v[96:99], v203
	ds_read_b128 v[100:103], v173 offset:2048
	ds_read_b128 v[104:107], v203 offset:2048
	ds_read_b128 v[188:191], v173 offset:4096
	ds_read_b128 v[192:195], v203 offset:4096
	ds_read_b128 v[196:199], v173 offset:6144
	ds_read_b128 v[200:203], v203 offset:6144
	global_load_lds_dwordx4 v[108:109], off
	v_lshl_add_u64 v[108:109], s[8:9], 0, v[182:183]
	s_add_i32 m0, s48, 0xe000
	s_nop 0
	global_load_lds_dwordx4 v[108:109], off
	s_waitcnt lgkmcnt(8)
	s_barrier
	s_waitcnt lgkmcnt(0)
	s_setprio 1
	s_waitcnt lgkmcnt(0)
	v_mfma_f32_16x16x32_bf16 v[158:161], v[76:79], v[92:95], v[158:161]
	v_mfma_f32_16x16x32_bf16 v[158:161], v[80:83], v[96:99], v[158:161]
	v_mfma_f32_16x16x32_bf16 v[60:63], v[88:91], v[96:99], v[60:63]
	v_mfma_f32_16x16x32_bf16 v[60:63], v[84:87], v[92:95], v[60:63]
	v_mfma_f32_16x16x32_bf16 v[52:55], v[84:87], v[100:103], v[52:55]
	v_mfma_f32_16x16x32_bf16 v[52:55], v[88:91], v[104:107], v[52:55]
	v_mfma_f32_16x16x32_bf16 v[150:153], v[80:83], v[104:107], v[150:153]
	v_mfma_f32_16x16x32_bf16 v[150:153], v[76:79], v[100:103], v[150:153]
	v_mfma_f32_16x16x32_bf16 v[146:149], v[76:79], v[188:191], v[146:149]
	v_mfma_f32_16x16x32_bf16 v[146:149], v[80:83], v[192:195], v[146:149]
	v_mfma_f32_16x16x32_bf16 v[48:51], v[88:91], v[192:195], v[48:51]
	v_mfma_f32_16x16x32_bf16 v[48:51], v[84:87], v[188:191], v[48:51]
	v_mfma_f32_16x16x32_bf16 v[40:43], v[84:87], v[196:199], v[40:43]
	v_mfma_f32_16x16x32_bf16 v[40:43], v[88:91], v[200:203], v[40:43]
	v_mfma_f32_16x16x32_bf16 v[138:141], v[80:83], v[200:203], v[138:141]
	v_mfma_f32_16x16x32_bf16 v[138:141], v[76:79], v[196:199], v[138:141]
	s_setprio 0
	s_barrier
	s_add_i32 s8, s60, s46
	v_lshl_add_u64 v[220:221], s[12:13], 0, v[164:165]
	s_mov_b32 m0, s8
	ds_read_b128 v[204:207], v175
	v_xor_b32_e32 v219, 64, v175
	ds_read_b128 v[208:211], v219
	ds_read_b128 v[212:215], v175 offset:2048
	ds_read_b128 v[216:219], v219 offset:2048
	global_load_lds_dwordx4 v[220:221], off
	v_lshl_add_u64 v[238:239], s[12:13], 0, v[166:167]
	s_add_i32 m0, s8, 0x2000
	s_nop 0
	global_load_lds_dwordx4 v[238:239], off
	s_barrier
	s_waitcnt lgkmcnt(0)
	s_setprio 1
	s_waitcnt lgkmcnt(0)
	v_mfma_f32_16x16x32_bf16 v[154:157], v[204:207], v[92:95], v[154:157]
	v_mfma_f32_16x16x32_bf16 v[154:157], v[208:211], v[96:99], v[154:157]
	v_mfma_f32_16x16x32_bf16 v[56:59], v[216:219], v[96:99], v[56:59]
	v_mfma_f32_16x16x32_bf16 v[56:59], v[212:215], v[92:95], v[56:59]
	v_mfma_f32_16x16x32_bf16 v[44:47], v[212:215], v[100:103], v[44:47]
	v_mfma_f32_16x16x32_bf16 v[44:47], v[216:219], v[104:107], v[44:47]
	v_mfma_f32_16x16x32_bf16 v[36:39], v[216:219], v[192:195], v[36:39]
	v_mfma_f32_16x16x32_bf16 v[36:39], v[212:215], v[188:191], v[36:39]
	v_mfma_f32_16x16x32_bf16 v[32:35], v[212:215], v[196:199], v[32:35]
	v_mfma_f32_16x16x32_bf16 v[32:35], v[216:219], v[200:203], v[32:35]
	v_mfma_f32_16x16x32_bf16 v[92:95], v[204:207], v[100:103], v[142:145]
	v_mfma_f32_16x16x32_bf16 v[92:95], v[208:211], v[104:107], v[92:95]
	v_mfma_f32_16x16x32_bf16 v[96:99], v[208:211], v[192:195], v[134:137]
	v_mfma_f32_16x16x32_bf16 v[96:99], v[204:207], v[188:191], v[96:99]
	v_mfma_f32_16x16x32_bf16 v[100:103], v[204:207], v[196:199], v[130:133]
	v_mfma_f32_16x16x32_bf16 v[100:103], v[208:211], v[200:203], v[100:103]
	s_setprio 0
	s_mov_b32 m0, s48
	v_lshl_add_u64 v[240:241], s[42:43], 0, v[178:179]
	s_barrier
	ds_read_b128 v[104:107], v173 offset:16384
	v_xor_b32_e32 v203, 64, v173
	ds_read_b128 v[130:133], v203 offset:16384
	ds_read_b128 v[134:137], v173 offset:18432
	ds_read_b128 v[142:145], v203 offset:18432
	ds_read_b128 v[188:191], v173 offset:20480
	ds_read_b128 v[192:195], v203 offset:20480
	ds_read_b128 v[196:199], v173 offset:22528
	ds_read_b128 v[200:203], v203 offset:22528
	global_load_lds_dwordx4 v[240:241], off
	v_lshl_add_u64 v[242:243], s[42:43], 0, v[176:177]
	s_mov_b32 m0, s49
	s_nop 0
	global_load_lds_dwordx4 v[242:243], off
	s_barrier
	s_waitcnt lgkmcnt(0)
	s_setprio 1
	s_waitcnt lgkmcnt(0)
	v_mfma_f32_16x16x32_bf16 v[126:129], v[76:79], v[104:107], v[126:129]
	v_mfma_f32_16x16x32_bf16 v[126:129], v[80:83], v[130:133], v[126:129]
	v_mfma_f32_16x16x32_bf16 v[28:31], v[88:91], v[130:133], v[28:31]
	v_mfma_f32_16x16x32_bf16 v[28:31], v[84:87], v[104:107], v[28:31]
	v_mfma_f32_16x16x32_bf16 v[24:27], v[84:87], v[134:137], v[24:27]
	v_mfma_f32_16x16x32_bf16 v[24:27], v[88:91], v[142:145], v[24:27]
	v_mfma_f32_16x16x32_bf16 v[122:125], v[80:83], v[142:145], v[122:125]
	v_mfma_f32_16x16x32_bf16 v[122:125], v[76:79], v[134:137], v[122:125]
	v_mfma_f32_16x16x32_bf16 v[114:117], v[76:79], v[188:191], v[114:117]
	v_mfma_f32_16x16x32_bf16 v[114:117], v[80:83], v[192:195], v[114:117]
	v_mfma_f32_16x16x32_bf16 v[20:23], v[88:91], v[192:195], v[20:23]
	v_mfma_f32_16x16x32_bf16 v[20:23], v[84:87], v[188:191], v[20:23]
	v_mfma_f32_16x16x32_bf16 v[4:7], v[84:87], v[196:199], v[4:7]
	v_mfma_f32_16x16x32_bf16 v[4:7], v[88:91], v[200:203], v[4:7]
	v_mfma_f32_16x16x32_bf16 v[72:75], v[80:83], v[200:203], v[72:75]
	v_mfma_f32_16x16x32_bf16 v[72:75], v[76:79], v[196:199], v[72:75]
	s_setprio 0
	s_barrier
	s_add_u32 s8, s12, 0x1600000
	s_addc_u32 s9, s13, 0
	s_add_i32 s68, s61, s46
	v_lshl_add_u64 v[76:77], s[8:9], 0, v[164:165]
	s_mov_b32 m0, s68
	s_nop 0
	global_load_lds_dwordx4 v[76:77], off
	v_lshl_add_u64 v[76:77], s[8:9], 0, v[166:167]
	s_add_i32 m0, s68, 0x2000
	s_nop 0
	global_load_lds_dwordx4 v[76:77], off
	s_waitcnt vmcnt(6)
	s_barrier
	s_setprio 1
	v_mfma_f32_16x16x32_bf16 v[16:19], v[212:215], v[104:107], v[16:19]
	v_mfma_f32_16x16x32_bf16 v[16:19], v[216:219], v[130:133], v[16:19]
	v_mfma_f32_16x16x32_bf16 v[12:15], v[216:219], v[142:145], v[12:15]
	v_mfma_f32_16x16x32_bf16 v[12:15], v[212:215], v[134:137], v[12:15]
	v_mfma_f32_16x16x32_bf16 v[8:11], v[212:215], v[188:191], v[8:11]
	v_mfma_f32_16x16x32_bf16 v[8:11], v[216:219], v[192:195], v[8:11]
	v_mfma_f32_16x16x32_bf16 v[68:71], v[208:211], v[192:195], v[68:71]
	v_mfma_f32_16x16x32_bf16 v[68:71], v[204:207], v[188:191], v[68:71]
	v_mfma_f32_16x16x32_bf16 v[64:67], v[204:207], v[196:199], v[64:67]
	v_mfma_f32_16x16x32_bf16 v[64:67], v[208:211], v[200:203], v[64:67]
	v_mfma_f32_16x16x32_bf16 v[0:3], v[216:219], v[200:203], v[0:3]
	v_mfma_f32_16x16x32_bf16 v[0:3], v[212:215], v[196:199], v[0:3]
	v_mfma_f32_16x16x32_bf16 v[76:79], v[204:207], v[104:107], v[118:121]
	v_mfma_f32_16x16x32_bf16 v[76:79], v[208:211], v[130:133], v[76:79]
	v_mfma_f32_16x16x32_bf16 v[80:83], v[208:211], v[142:145], v[110:113]
	v_mfma_f32_16x16x32_bf16 v[80:83], v[204:207], v[134:137], v[80:83]
	s_setprio 0
	s_add_i32 s68, 0, 0x18000
	v_add_u32_e32 v108, s68, v169
	s_barrier
	ds_read_b128 v[84:87], v108
	v_xor_b32_e32 v111, 64, v108
	ds_read_b128 v[88:91], v111
	ds_read_b128 v[104:107], v108 offset:2048
	ds_read_b128 v[108:111], v111 offset:2048
	s_add_u32 s8, s42, 0x40000
	s_addc_u32 s9, s43, 0
	s_mov_b32 m0, s50
	v_lshl_add_u64 v[112:113], s[8:9], 0, v[178:179]
	ds_read_b128 v[118:121], v173 offset:32768
	v_xor_b32_e32 v207, 64, v173
	ds_read_b128 v[130:133], v207 offset:32768
	ds_read_b128 v[134:137], v173 offset:34816
	ds_read_b128 v[188:191], v207 offset:34816
	ds_read_b128 v[192:195], v173 offset:36864
	ds_read_b128 v[196:199], v207 offset:36864
	ds_read_b128 v[200:203], v173 offset:38912
	ds_read_b128 v[204:207], v207 offset:38912
	global_load_lds_dwordx4 v[112:113], off
	v_lshl_add_u64 v[112:113], s[8:9], 0, v[176:177]
	s_mov_b32 m0, s51
	s_nop 0
	global_load_lds_dwordx4 v[112:113], off
	s_waitcnt lgkmcnt(8)
	s_barrier
	s_waitcnt lgkmcnt(0)
	s_setprio 1
	s_waitcnt lgkmcnt(0)
	v_mfma_f32_16x16x32_bf16 v[142:145], v[84:87], v[118:121], v[158:161]
	v_mfma_f32_16x16x32_bf16 v[158:161], v[88:91], v[130:133], v[142:145]
	v_mfma_f32_16x16x32_bf16 v[60:63], v[108:111], v[130:133], v[60:63]
	v_mfma_f32_16x16x32_bf16 v[60:63], v[104:107], v[118:121], v[60:63]
	v_mfma_f32_16x16x32_bf16 v[52:55], v[104:107], v[134:137], v[52:55]
	v_mfma_f32_16x16x32_bf16 v[52:55], v[108:111], v[188:191], v[52:55]
	v_mfma_f32_16x16x32_bf16 v[48:51], v[108:111], v[196:199], v[48:51]
	v_mfma_f32_16x16x32_bf16 v[48:51], v[104:107], v[192:195], v[48:51]
	v_mfma_f32_16x16x32_bf16 v[40:43], v[104:107], v[200:203], v[40:43]
	v_mfma_f32_16x16x32_bf16 v[40:43], v[108:111], v[204:207], v[40:43]
	v_mfma_f32_16x16x32_bf16 v[138:141], v[88:91], v[204:207], v[138:141]
	v_mfma_f32_16x16x32_bf16 v[138:141], v[84:87], v[200:203], v[138:141]
	v_mfma_f32_16x16x32_bf16 v[142:145], v[84:87], v[134:137], v[150:153]
	v_mfma_f32_16x16x32_bf16 v[150:153], v[88:91], v[188:191], v[142:145]
	v_mfma_f32_16x16x32_bf16 v[142:145], v[84:87], v[192:195], v[146:149]
	v_mfma_f32_16x16x32_bf16 v[146:149], v[88:91], v[196:199], v[142:145]
	s_setprio 0
	s_barrier
	s_add_i32 s42, 0, 0x1c000
	v_add_u32_e32 v112, s42, v169
	s_add_i32 s8, s68, s46
	ds_read_b128 v[208:211], v112
	v_xor_b32_e32 v237, 64, v112
	ds_read_b128 v[212:215], v237
	ds_read_b128 v[216:219], v112 offset:2048
	ds_read_b128 v[234:237], v237 offset:2048
	v_lshl_add_u64 v[112:113], v[220:221], 0, s[18:19]
	s_mov_b32 m0, s8
	s_nop 0
	global_load_lds_dwordx4 v[112:113], off
	v_lshl_add_u64 v[112:113], v[238:239], 0, s[18:19]
	s_add_i32 m0, s8, 0x2000
	s_nop 0
	global_load_lds_dwordx4 v[112:113], off
	s_barrier
	s_waitcnt lgkmcnt(0)
	s_setprio 1
	s_waitcnt lgkmcnt(0)
	v_mfma_f32_16x16x32_bf16 v[142:145], v[208:211], v[118:121], v[154:157]
	v_mfma_f32_16x16x32_bf16 v[154:157], v[212:215], v[130:133], v[142:145]
	v_mfma_f32_16x16x32_bf16 v[56:59], v[234:237], v[130:133], v[56:59]
	v_mfma_f32_16x16x32_bf16 v[56:59], v[216:219], v[118:121], v[56:59]
	v_mfma_f32_16x16x32_bf16 v[44:47], v[216:219], v[134:137], v[44:47]
	v_mfma_f32_16x16x32_bf16 v[44:47], v[234:237], v[188:191], v[44:47]
	v_mfma_f32_16x16x32_bf16 v[36:39], v[234:237], v[196:199], v[36:39]
	v_mfma_f32_16x16x32_bf16 v[36:39], v[216:219], v[192:195], v[36:39]
	v_mfma_f32_16x16x32_bf16 v[32:35], v[216:219], v[200:203], v[32:35]
	v_mfma_f32_16x16x32_bf16 v[32:35], v[234:237], v[204:207], v[32:35]
	v_mfma_f32_16x16x32_bf16 v[92:95], v[208:211], v[134:137], v[92:95]
	v_mfma_f32_16x16x32_bf16 v[142:145], v[212:215], v[188:191], v[92:95]
	v_mfma_f32_16x16x32_bf16 v[92:95], v[208:211], v[192:195], v[96:99]
	v_mfma_f32_16x16x32_bf16 v[134:137], v[212:215], v[196:199], v[92:95]
	v_mfma_f32_16x16x32_bf16 v[92:95], v[208:211], v[200:203], v[100:103]
	v_mfma_f32_16x16x32_bf16 v[130:133], v[212:215], v[204:207], v[92:95]
	s_setprio 0
	s_mov_b32 m0, s54
	v_lshl_add_u64 v[112:113], v[240:241], 0, s[18:19]
	s_barrier
	ds_read_b128 v[92:95], v173 offset:49152
	v_xor_b32_e32 v207, 64, v173
	ds_read_b128 v[96:99], v207 offset:49152
	ds_read_b128 v[100:103], v173 offset:51200
	ds_read_b128 v[188:191], v207 offset:51200
	ds_read_b128 v[192:195], v173 offset:53248
	ds_read_b128 v[196:199], v207 offset:53248
	ds_read_b128 v[200:203], v173 offset:55296
	ds_read_b128 v[204:207], v207 offset:55296
	global_load_lds_dwordx4 v[112:113], off
	v_lshl_add_u64 v[112:113], v[242:243], 0, s[18:19]
	s_mov_b32 m0, s55
	s_nop 0
	global_load_lds_dwordx4 v[112:113], off
	s_barrier
	s_waitcnt lgkmcnt(0)
	s_setprio 1
	s_waitcnt lgkmcnt(0)
	v_mfma_f32_16x16x32_bf16 v[118:121], v[84:87], v[92:95], v[126:129]
	v_mfma_f32_16x16x32_bf16 v[126:129], v[88:91], v[96:99], v[118:121]
	v_mfma_f32_16x16x32_bf16 v[28:31], v[108:111], v[96:99], v[28:31]
	v_mfma_f32_16x16x32_bf16 v[28:31], v[104:107], v[92:95], v[28:31]
	v_mfma_f32_16x16x32_bf16 v[24:27], v[104:107], v[100:103], v[24:27]
	v_mfma_f32_16x16x32_bf16 v[24:27], v[108:111], v[188:191], v[24:27]
	v_mfma_f32_16x16x32_bf16 v[20:23], v[108:111], v[196:199], v[20:23]
	v_mfma_f32_16x16x32_bf16 v[20:23], v[104:107], v[192:195], v[20:23]
	v_mfma_f32_16x16x32_bf16 v[112:115], v[84:87], v[192:195], v[114:117]
	v_mfma_f32_16x16x32_bf16 v[114:117], v[88:91], v[196:199], v[112:115]
	v_mfma_f32_16x16x32_bf16 v[72:75], v[88:91], v[204:207], v[72:75]
	v_mfma_f32_16x16x32_bf16 v[72:75], v[84:87], v[200:203], v[72:75]
	v_mfma_f32_16x16x32_bf16 v[118:121], v[84:87], v[100:103], v[122:125]
	v_mfma_f32_16x16x32_bf16 v[122:125], v[88:91], v[188:191], v[118:121]
	v_mfma_f32_16x16x32_bf16 v[4:7], v[104:107], v[200:203], v[4:7]
	v_mfma_f32_16x16x32_bf16 v[4:7], v[108:111], v[204:207], v[4:7]
	s_setprio 0
	s_barrier
	s_add_u32 s8, s12, 0x1600080
	s_addc_u32 s9, s13, 0
	s_add_i32 s12, s42, s46
	v_lshl_add_u64 v[84:85], s[8:9], 0, v[164:165]
	s_mov_b32 m0, s12
	s_nop 0
	global_load_lds_dwordx4 v[84:85], off
	v_lshl_add_u64 v[84:85], s[8:9], 0, v[166:167]
	s_add_i32 m0, s12, 0x2000
	s_nop 0
	global_load_lds_dwordx4 v[84:85], off
	s_waitcnt vmcnt(6)
	s_barrier
	s_setprio 1
	v_mfma_f32_16x16x32_bf16 v[76:79], v[208:211], v[92:95], v[76:79]
	v_mfma_f32_16x16x32_bf16 v[118:121], v[212:215], v[96:99], v[76:79]
	v_mfma_f32_16x16x32_bf16 v[16:19], v[234:237], v[96:99], v[16:19]
	v_mfma_f32_16x16x32_bf16 v[16:19], v[216:219], v[92:95], v[16:19]
	v_mfma_f32_16x16x32_bf16 v[12:15], v[216:219], v[100:103], v[12:15]
	v_mfma_f32_16x16x32_bf16 v[12:15], v[234:237], v[188:191], v[12:15]
	v_mfma_f32_16x16x32_bf16 v[8:11], v[234:237], v[196:199], v[8:11]
	v_mfma_f32_16x16x32_bf16 v[8:11], v[216:219], v[192:195], v[8:11]
	v_mfma_f32_16x16x32_bf16 v[68:71], v[208:211], v[192:195], v[68:71]
	v_mfma_f32_16x16x32_bf16 v[68:71], v[212:215], v[196:199], v[68:71]
	v_mfma_f32_16x16x32_bf16 v[64:67], v[212:215], v[204:207], v[64:67]
	v_mfma_f32_16x16x32_bf16 v[64:67], v[208:211], v[200:203], v[64:67]
	v_mfma_f32_16x16x32_bf16 v[76:79], v[208:211], v[100:103], v[80:83]
	v_mfma_f32_16x16x32_bf16 v[110:113], v[212:215], v[188:191], v[76:79]
	v_mfma_f32_16x16x32_bf16 v[0:3], v[216:219], v[200:203], v[0:3]
	v_mfma_f32_16x16x32_bf16 v[0:3], v[234:237], v[204:207], v[0:3]
	s_setprio 0
	s_add_i32 s67, s67, 2
	s_add_u32 s65, s65, 0x100
	s_addc_u32 s66, s66, 0
	s_cmp_gt_u32 s67, 29
	s_mov_b64 s[8:9], s[10:11]
	s_barrier
	s_cbranch_scc0 .LBB0_840
	s_lshl_b32 s8, s0, 8
	s_add_i32 s8, s8, s58
	s_lshl_b32 s9, s1, 7
	s_add_i32 s9, s9, s53
	s_lshl_b32 s10, s0, 3
	s_lshr_b32 s11, s58, 5
	s_add_i32 s10, s10, s11
	v_add_u32_e32 v200, s8, v163
	v_lshlrev_b32_e32 v213, 2, v200
	s_cmp_eq_u32 s98, 0
	s_cbranch_scc1 .Lfs8_direct
	v_lshrrev_b32_e32 v212, 6, v222
	v_lshlrev_b32_e32 v212, 9, v212
	v_lshl_add_u32 v212, v163, 2, v212
	v_add_u32_e32 v212, 0x20040, v212
	ds_read_b32 v188, v212
	ds_read_b32 v189, v212 offset:64
	ds_read_b32 v190, v212 offset:128
	ds_read_b32 v191, v212 offset:192
	ds_read_b32 v192, v212 offset:256
	ds_read_b32 v193, v212 offset:320
	ds_read_b32 v194, v212 offset:384
	ds_read_b32 v195, v212 offset:448
	s_branch .Lfs8_join
.Lfs8_direct:
	global_load_dword v188, v213, s[4:5]
	global_load_dword v189, v213, s[4:5] offset:64
	global_load_dword v190, v213, s[4:5] offset:128
	global_load_dword v191, v213, s[4:5] offset:192
	global_load_dword v192, v213, s[4:5] offset:256
	global_load_dword v193, v213, s[4:5] offset:320
	global_load_dword v194, v213, s[4:5] offset:384
	global_load_dword v195, v213, s[4:5] offset:448
.Lfs8_join:
	v_lshl_add_u32 v201, v225, 3, s9
	v_lshlrev_b32_e32 v212, 2, v201
	v_add_u32_e32 v213, 0x21000, v212
	global_load_dwordx4 v[76:79], v213, s[82:83]
	v_add_u32_e32 v213, 0x2c000, v212
	global_load_dwordx4 v[80:83], v213, s[82:83]
	v_add_u32_e32 v213, 0x37000, v212
	global_load_dwordx4 v[84:87], v213, s[82:83]
	v_add_u32_e32 v213, 0xb000, v212
	global_load_dwordx4 v[88:91], v213, s[84:85]
	v_add_u32_e32 v213, 0x26800, v212
	global_load_dwordx4 v[92:95], v213, s[82:83]
	v_add_u32_e32 v213, 0x31800, v212
	global_load_dwordx4 v[96:99], v213, s[82:83]
	v_add_u32_e32 v213, 0x3c800, v212
	global_load_dwordx4 v[100:103], v213, s[82:83]
	v_add_u32_e32 v213, 0x10800, v212
	global_load_dwordx4 v[104:107], v213, s[84:85]
	v_mul_u32_u24_e32 v215, 0x2c00, v200
	v_lshl_add_u32 v215, v201, 1, v215
	v_add_u32_e32 v213, s10, v163
	v_mul_u32_u24_e32 v217, 0xb000, v213
	v_add_u32_e32 v217, v217, v212
	v_cmp_gt_u32_e64 s[8:9], 2, v163
	v_cmp_lt_u32_e64 s[10:11], 13, v163
	v_cmp_lt_u32_e32 vcc, 1, v163
	v_mov_b32_e32 v214, 1.0
	v_mov_b32_e32 v216, 0xbfb8aa3b
	v_mov_b32_e32 v108, 0x3727c5ac
	s_waitcnt vmcnt(8)
	s_waitcnt lgkmcnt(0)
	v_fmamk_f32 v188, v188, 0x3a000000, v108
	v_fmamk_f32 v189, v189, 0x3a000000, v108
	v_fmamk_f32 v190, v190, 0x3a000000, v108
	v_fmamk_f32 v191, v191, 0x3a000000, v108
	v_fmamk_f32 v192, v192, 0x3a000000, v108
	v_fmamk_f32 v193, v193, 0x3a000000, v108
	v_fmamk_f32 v194, v194, 0x3a000000, v108
	v_fmamk_f32 v195, v195, 0x3a000000, v108
	v_rsq_f32_e32 v188, v188
	v_rsq_f32_e32 v189, v189
	v_rsq_f32_e32 v190, v190
	v_rsq_f32_e32 v191, v191
	v_rsq_f32_e32 v192, v192
	v_rsq_f32_e32 v193, v193
	v_rsq_f32_e32 v194, v194
	v_rsq_f32_e32 v195, v195
	v_pk_mul_f32 v[158:159], v[158:159], v[188:189] op_sel_hi:[1,0]
	v_pk_mul_f32 v[160:161], v[160:161], v[188:189] op_sel_hi:[1,0]
	v_pk_mul_f32 v[60:61], v[60:61], v[188:189] op_sel_hi:[1,0]
	v_pk_mul_f32 v[62:63], v[62:63], v[188:189] op_sel_hi:[1,0]
	v_pk_mul_f32 v[154:155], v[154:155], v[188:189] op_sel_hi:[1,0]
	v_pk_mul_f32 v[156:157], v[156:157], v[188:189] op_sel_hi:[1,0]
	v_pk_mul_f32 v[56:57], v[56:57], v[188:189] op_sel_hi:[1,0]
	v_pk_mul_f32 v[58:59], v[58:59], v[188:189] op_sel_hi:[1,0]
	v_pk_mul_f32 v[150:151], v[150:151], v[188:189] op_sel:[0,1] op_sel_hi:[1,1]
	v_pk_mul_f32 v[152:153], v[152:153], v[188:189] op_sel:[0,1] op_sel_hi:[1,1]
	v_pk_mul_f32 v[52:53], v[52:53], v[188:189] op_sel:[0,1] op_sel_hi:[1,1]
	v_pk_mul_f32 v[54:55], v[54:55], v[188:189] op_sel:[0,1] op_sel_hi:[1,1]
	v_pk_mul_f32 v[142:143], v[142:143], v[188:189] op_sel:[0,1] op_sel_hi:[1,1]
	v_pk_mul_f32 v[144:145], v[144:145], v[188:189] op_sel:[0,1] op_sel_hi:[1,1]
	v_pk_mul_f32 v[44:45], v[44:45], v[188:189] op_sel:[0,1] op_sel_hi:[1,1]
	v_pk_mul_f32 v[46:47], v[46:47], v[188:189] op_sel:[0,1] op_sel_hi:[1,1]
	v_pk_mul_f32 v[146:147], v[146:147], v[190:191] op_sel_hi:[1,0]
	v_pk_mul_f32 v[148:149], v[148:149], v[190:191] op_sel_hi:[1,0]
	v_pk_mul_f32 v[48:49], v[48:49], v[190:191] op_sel_hi:[1,0]
	v_pk_mul_f32 v[50:51], v[50:51], v[190:191] op_sel_hi:[1,0]
	v_pk_mul_f32 v[134:135], v[134:135], v[190:191] op_sel_hi:[1,0]
	v_pk_mul_f32 v[136:137], v[136:137], v[190:191] op_sel_hi:[1,0]
	v_pk_mul_f32 v[36:37], v[36:37], v[190:191] op_sel_hi:[1,0]
	v_pk_mul_f32 v[38:39], v[38:39], v[190:191] op_sel_hi:[1,0]
	v_pk_mul_f32 v[138:139], v[138:139], v[190:191] op_sel:[0,1] op_sel_hi:[1,1]
	v_pk_mul_f32 v[140:141], v[140:141], v[190:191] op_sel:[0,1] op_sel_hi:[1,1]
	v_pk_mul_f32 v[40:41], v[40:41], v[190:191] op_sel:[0,1] op_sel_hi:[1,1]
	v_pk_mul_f32 v[42:43], v[42:43], v[190:191] op_sel:[0,1] op_sel_hi:[1,1]
	v_pk_mul_f32 v[130:131], v[130:131], v[190:191] op_sel:[0,1] op_sel_hi:[1,1]
	v_pk_mul_f32 v[132:133], v[132:133], v[190:191] op_sel:[0,1] op_sel_hi:[1,1]
	v_pk_mul_f32 v[32:33], v[32:33], v[190:191] op_sel:[0,1] op_sel_hi:[1,1]
	v_pk_mul_f32 v[34:35], v[34:35], v[190:191] op_sel:[0,1] op_sel_hi:[1,1]
	v_pk_mul_f32 v[126:127], v[126:127], v[192:193] op_sel_hi:[1,0]
	v_pk_mul_f32 v[128:129], v[128:129], v[192:193] op_sel_hi:[1,0]
	v_pk_mul_f32 v[28:29], v[28:29], v[192:193] op_sel_hi:[1,0]
	v_pk_mul_f32 v[30:31], v[30:31], v[192:193] op_sel_hi:[1,0]
	v_pk_mul_f32 v[118:119], v[118:119], v[192:193] op_sel_hi:[1,0]
	v_pk_mul_f32 v[120:121], v[120:121], v[192:193] op_sel_hi:[1,0]
	v_pk_mul_f32 v[16:17], v[16:17], v[192:193] op_sel_hi:[1,0]
	v_pk_mul_f32 v[18:19], v[18:19], v[192:193] op_sel_hi:[1,0]
	v_pk_mul_f32 v[122:123], v[122:123], v[192:193] op_sel:[0,1] op_sel_hi:[1,1]
	v_pk_mul_f32 v[124:125], v[124:125], v[192:193] op_sel:[0,1] op_sel_hi:[1,1]
	v_pk_mul_f32 v[24:25], v[24:25], v[192:193] op_sel:[0,1] op_sel_hi:[1,1]
	v_pk_mul_f32 v[26:27], v[26:27], v[192:193] op_sel:[0,1] op_sel_hi:[1,1]
	v_pk_mul_f32 v[110:111], v[110:111], v[192:193] op_sel:[0,1] op_sel_hi:[1,1]
	v_pk_mul_f32 v[112:113], v[112:113], v[192:193] op_sel:[0,1] op_sel_hi:[1,1]
	v_pk_mul_f32 v[12:13], v[12:13], v[192:193] op_sel:[0,1] op_sel_hi:[1,1]
	v_pk_mul_f32 v[14:15], v[14:15], v[192:193] op_sel:[0,1] op_sel_hi:[1,1]
	v_pk_mul_f32 v[114:115], v[114:115], v[194:195] op_sel_hi:[1,0]
	v_pk_mul_f32 v[116:117], v[116:117], v[194:195] op_sel_hi:[1,0]
	v_pk_mul_f32 v[20:21], v[20:21], v[194:195] op_sel_hi:[1,0]
	v_pk_mul_f32 v[22:23], v[22:23], v[194:195] op_sel_hi:[1,0]
	v_pk_mul_f32 v[68:69], v[68:69], v[194:195] op_sel_hi:[1,0]
	v_pk_mul_f32 v[70:71], v[70:71], v[194:195] op_sel_hi:[1,0]
	v_pk_mul_f32 v[8:9], v[8:9], v[194:195] op_sel_hi:[1,0]
	v_pk_mul_f32 v[10:11], v[10:11], v[194:195] op_sel_hi:[1,0]
	v_pk_mul_f32 v[72:73], v[72:73], v[194:195] op_sel:[0,1] op_sel_hi:[1,1]
	v_pk_mul_f32 v[74:75], v[74:75], v[194:195] op_sel:[0,1] op_sel_hi:[1,1]
	v_pk_mul_f32 v[4:5], v[4:5], v[194:195] op_sel:[0,1] op_sel_hi:[1,1]
	v_pk_mul_f32 v[6:7], v[6:7], v[194:195] op_sel:[0,1] op_sel_hi:[1,1]
	v_pk_mul_f32 v[64:65], v[64:65], v[194:195] op_sel:[0,1] op_sel_hi:[1,1]
	v_pk_mul_f32 v[66:67], v[66:67], v[194:195] op_sel:[0,1] op_sel_hi:[1,1]
	v_pk_mul_f32 v[0:1], v[0:1], v[194:195] op_sel:[0,1] op_sel_hi:[1,1]
	v_pk_mul_f32 v[2:3], v[2:3], v[194:195] op_sel:[0,1] op_sel_hi:[1,1]
	s_nop 1
	s_mov_b64 exec, s[8:9]
	v_add_u32_e32 v213, 0x5800, v217
	global_store_dwordx4 v217, v[158:161], s[70:71]
	global_store_dwordx4 v213, v[154:157], s[70:71]
	global_store_dwordx4 v217, v[60:63], s[70:71] offset:16
	global_store_dwordx4 v213, v[56:59], s[70:71] offset:16
	s_mov_b64 exec, s[10:11]
	v_add_u32_e32 v213, 0xfff7c000, v217
	global_store_dwordx4 v213, v[72:75], s[70:71]
	global_store_dwordx4 v213, v[4:7], s[70:71] offset:16
	v_add_u32_e32 v213, 0xfff81800, v217
	global_store_dwordx4 v213, v[64:67], s[70:71]
	global_store_dwordx4 v213, v[0:3], s[70:71] offset:16
	s_mov_b64 exec, -1
	s_cmp_lg_u64 s[6:7], 0
	s_cselect_b32 s8, s0, s36
	v_lshrrev_b32_e32 v213, 6, v222
	s_lshl_b32 s8, s8, 8
	v_readfirstlane_b32 s9, v213
	s_add_i32 s8, s8, s58
	v_and_b32_e32 v213, 63, v222
	v_add_u32_e32 v213, s8, v213
	v_lshlrev_b32_e32 v213, 2, v213
	s_lshl_b32 s9, s9, 9
	s_add_i32 m0, s9, 0x20040
	s_nop 0
	global_load_lds_dword v213, s[4:5]
	v_add_u32_e32 v213, 0x100, v213
	s_add_i32 m0, s9, 0x20140
	s_nop 0
	global_load_lds_dword v213, s[4:5]
	v_add_u32_e32 v213, 0x3c800, v212
	global_load_dwordx4 v[204:207], v213, s[82:83] offset:16
	v_add_u32_e32 v213, 0x10800, v212
	global_load_dwordx4 v[208:211], v213, s[84:85] offset:16
	s_waitcnt vmcnt(12)
	v_pk_fma_f32 v[188:189], v[158:159], v[84:85], v[88:89]
	v_pk_fma_f32 v[190:191], v[160:161], v[86:87], v[90:91]
	v_pk_fma_f32 v[192:193], v[154:155], v[100:101], v[104:105]
	v_pk_fma_f32 v[194:195], v[156:157], v[102:103], v[106:107]
	v_fmac_f32_dpp v188, v158, v80 row_shr:1 row_mask:0xf bank_mask:0xf
	v_fmac_f32_dpp v189, v159, v81 row_shr:1 row_mask:0xf bank_mask:0xf
	v_fmac_f32_dpp v190, v160, v82 row_shr:1 row_mask:0xf bank_mask:0xf
	v_fmac_f32_dpp v191, v161, v83 row_shr:1 row_mask:0xf bank_mask:0xf
	v_fmac_f32_dpp v192, v154, v96 row_shr:1 row_mask:0xf bank_mask:0xf
	v_fmac_f32_dpp v193, v155, v97 row_shr:1 row_mask:0xf bank_mask:0xf
	v_fmac_f32_dpp v194, v156, v98 row_shr:1 row_mask:0xf bank_mask:0xf
	v_fmac_f32_dpp v195, v157, v99 row_shr:1 row_mask:0xf bank_mask:0xf
	v_fmac_f32_dpp v188, v158, v76 row_shr:2 row_mask:0xf bank_mask:0xf
	v_fmac_f32_dpp v189, v159, v77 row_shr:2 row_mask:0xf bank_mask:0xf
	v_fmac_f32_dpp v190, v160, v78 row_shr:2 row_mask:0xf bank_mask:0xf
	v_fmac_f32_dpp v191, v161, v79 row_shr:2 row_mask:0xf bank_mask:0xf
	v_fmac_f32_dpp v192, v154, v92 row_shr:2 row_mask:0xf bank_mask:0xf
	v_fmac_f32_dpp v193, v155, v93 row_shr:2 row_mask:0xf bank_mask:0xf
	v_fmac_f32_dpp v194, v156, v94 row_shr:2 row_mask:0xf bank_mask:0xf
	v_fmac_f32_dpp v195, v157, v95 row_shr:2 row_mask:0xf bank_mask:0xf
	v_pk_mul_f32 v[196:197], v[188:189], v[216:217] op_sel_hi:[1,0]
	v_pk_mul_f32 v[198:199], v[190:191], v[216:217] op_sel_hi:[1,0]
	v_exp_f32_e32 v196, v196
	v_exp_f32_e32 v197, v197
	v_exp_f32_e32 v198, v198
	v_exp_f32_e32 v199, v199
	v_pk_add_f32 v[196:197], v[196:197], v[214:215] op_sel_hi:[1,0]
	v_pk_add_f32 v[198:199], v[198:199], v[214:215] op_sel_hi:[1,0]
	v_rcp_f32_e32 v196, v196
	v_rcp_f32_e32 v197, v197
	v_rcp_f32_e32 v198, v198
	v_rcp_f32_e32 v199, v199
	v_pk_mul_f32 v[188:189], v[188:189], v[196:197]
	v_pk_mul_f32 v[190:191], v[190:191], v[198:199]
	v_pk_mul_f32 v[188:189], v[188:189], v[192:193]
	v_pk_mul_f32 v[190:191], v[190:191], v[194:195]
	v_cvt_pk_bf16_f32 v200, v188, v189
	v_cvt_pk_bf16_f32 v201, v190, v191
	v_pk_fma_f32 v[188:189], v[150:151], v[84:85], v[88:89]
	v_pk_fma_f32 v[190:191], v[152:153], v[86:87], v[90:91]
	v_pk_fma_f32 v[192:193], v[142:143], v[100:101], v[104:105]
	v_pk_fma_f32 v[194:195], v[144:145], v[102:103], v[106:107]
	v_fmac_f32_dpp v188, v150, v80 row_shr:1 row_mask:0xf bank_mask:0xf
	v_fmac_f32_dpp v189, v151, v81 row_shr:1 row_mask:0xf bank_mask:0xf
	v_fmac_f32_dpp v190, v152, v82 row_shr:1 row_mask:0xf bank_mask:0xf
	v_fmac_f32_dpp v191, v153, v83 row_shr:1 row_mask:0xf bank_mask:0xf
	v_fmac_f32_dpp v192, v142, v96 row_shr:1 row_mask:0xf bank_mask:0xf
	v_fmac_f32_dpp v193, v143, v97 row_shr:1 row_mask:0xf bank_mask:0xf
	v_fmac_f32_dpp v194, v144, v98 row_shr:1 row_mask:0xf bank_mask:0xf
	v_fmac_f32_dpp v195, v145, v99 row_shr:1 row_mask:0xf bank_mask:0xf
	v_fmac_f32_dpp v188, v150, v76 row_shr:2 row_mask:0xf bank_mask:0xf
	v_fmac_f32_dpp v189, v151, v77 row_shr:2 row_mask:0xf bank_mask:0xf
	v_fmac_f32_dpp v190, v152, v78 row_shr:2 row_mask:0xf bank_mask:0xf
	v_fmac_f32_dpp v191, v153, v79 row_shr:2 row_mask:0xf bank_mask:0xf
	v_fmac_f32_dpp v192, v142, v92 row_shr:2 row_mask:0xf bank_mask:0xf
	v_fmac_f32_dpp v193, v143, v93 row_shr:2 row_mask:0xf bank_mask:0xf
	v_fmac_f32_dpp v194, v144, v94 row_shr:2 row_mask:0xf bank_mask:0xf
	v_fmac_f32_dpp v195, v145, v95 row_shr:2 row_mask:0xf bank_mask:0xf
	v_fmac_f32_dpp v188, v158, v80 row_shl:15 row_mask:0xf bank_mask:0xf
	v_fmac_f32_dpp v189, v159, v81 row_shl:15 row_mask:0xf bank_mask:0xf
	v_fmac_f32_dpp v190, v160, v82 row_shl:15 row_mask:0xf bank_mask:0xf
	v_fmac_f32_dpp v191, v161, v83 row_shl:15 row_mask:0xf bank_mask:0xf
	v_fmac_f32_dpp v192, v154, v96 row_shl:15 row_mask:0xf bank_mask:0xf
	v_fmac_f32_dpp v193, v155, v97 row_shl:15 row_mask:0xf bank_mask:0xf
	v_fmac_f32_dpp v194, v156, v98 row_shl:15 row_mask:0xf bank_mask:0xf
	v_fmac_f32_dpp v195, v157, v99 row_shl:15 row_mask:0xf bank_mask:0xf
	v_fmac_f32_dpp v188, v158, v76 row_shl:14 row_mask:0xf bank_mask:0xf
	v_fmac_f32_dpp v189, v159, v77 row_shl:14 row_mask:0xf bank_mask:0xf
	v_fmac_f32_dpp v190, v160, v78 row_shl:14 row_mask:0xf bank_mask:0xf
	v_fmac_f32_dpp v191, v161, v79 row_shl:14 row_mask:0xf bank_mask:0xf
	v_fmac_f32_dpp v192, v154, v92 row_shl:14 row_mask:0xf bank_mask:0xf
	v_fmac_f32_dpp v193, v155, v93 row_shl:14 row_mask:0xf bank_mask:0xf
	v_fmac_f32_dpp v194, v156, v94 row_shl:14 row_mask:0xf bank_mask:0xf
	v_fmac_f32_dpp v195, v157, v95 row_shl:14 row_mask:0xf bank_mask:0xf
	v_pk_mul_f32 v[196:197], v[188:189], v[216:217] op_sel_hi:[1,0]
	v_pk_mul_f32 v[198:199], v[190:191], v[216:217] op_sel_hi:[1,0]
	v_exp_f32_e32 v196, v196
	v_exp_f32_e32 v197, v197
	v_exp_f32_e32 v198, v198
	v_exp_f32_e32 v199, v199
	v_pk_add_f32 v[196:197], v[196:197], v[214:215] op_sel_hi:[1,0]
	v_pk_add_f32 v[198:199], v[198:199], v[214:215] op_sel_hi:[1,0]
	v_rcp_f32_e32 v196, v196
	v_rcp_f32_e32 v197, v197
	v_rcp_f32_e32 v198, v198
	v_rcp_f32_e32 v199, v199
	v_pk_mul_f32 v[188:189], v[188:189], v[196:197]
	v_pk_mul_f32 v[190:191], v[190:191], v[198:199]
	v_pk_mul_f32 v[188:189], v[188:189], v[192:193]
	v_pk_mul_f32 v[190:191], v[190:191], v[194:195]
	v_cvt_pk_bf16_f32 v158, v188, v189
	v_cvt_pk_bf16_f32 v159, v190, v191
	v_add_u32_e32 v213, 0x21000, v212
	global_load_dwordx4 v[154:157], v213, s[82:83] offset:16
	v_pk_fma_f32 v[188:189], v[146:147], v[84:85], v[88:89]
	v_pk_fma_f32 v[190:191], v[148:149], v[86:87], v[90:91]
	v_pk_fma_f32 v[192:193], v[134:135], v[100:101], v[104:105]
	v_pk_fma_f32 v[194:195], v[136:137], v[102:103], v[106:107]
	v_fmac_f32_dpp v188, v146, v80 row_shr:1 row_mask:0xf bank_mask:0xf
	v_fmac_f32_dpp v189, v147, v81 row_shr:1 row_mask:0xf bank_mask:0xf
	v_fmac_f32_dpp v190, v148, v82 row_shr:1 row_mask:0xf bank_mask:0xf
	v_fmac_f32_dpp v191, v149, v83 row_shr:1 row_mask:0xf bank_mask:0xf
	v_fmac_f32_dpp v192, v134, v96 row_shr:1 row_mask:0xf bank_mask:0xf
	v_fmac_f32_dpp v193, v135, v97 row_shr:1 row_mask:0xf bank_mask:0xf
	v_fmac_f32_dpp v194, v136, v98 row_shr:1 row_mask:0xf bank_mask:0xf
	v_fmac_f32_dpp v195, v137, v99 row_shr:1 row_mask:0xf bank_mask:0xf
	v_fmac_f32_dpp v188, v146, v76 row_shr:2 row_mask:0xf bank_mask:0xf
	v_fmac_f32_dpp v189, v147, v77 row_shr:2 row_mask:0xf bank_mask:0xf
	v_fmac_f32_dpp v190, v148, v78 row_shr:2 row_mask:0xf bank_mask:0xf
	v_fmac_f32_dpp v191, v149, v79 row_shr:2 row_mask:0xf bank_mask:0xf
	v_fmac_f32_dpp v192, v134, v92 row_shr:2 row_mask:0xf bank_mask:0xf
	v_fmac_f32_dpp v193, v135, v93 row_shr:2 row_mask:0xf bank_mask:0xf
	v_fmac_f32_dpp v194, v136, v94 row_shr:2 row_mask:0xf bank_mask:0xf
	v_fmac_f32_dpp v195, v137, v95 row_shr:2 row_mask:0xf bank_mask:0xf
	v_fmac_f32_dpp v188, v150, v80 row_shl:15 row_mask:0xf bank_mask:0xf
	v_fmac_f32_dpp v189, v151, v81 row_shl:15 row_mask:0xf bank_mask:0xf
	v_fmac_f32_dpp v190, v152, v82 row_shl:15 row_mask:0xf bank_mask:0xf
	v_fmac_f32_dpp v191, v153, v83 row_shl:15 row_mask:0xf bank_mask:0xf
	v_fmac_f32_dpp v192, v142, v96 row_shl:15 row_mask:0xf bank_mask:0xf
	v_fmac_f32_dpp v193, v143, v97 row_shl:15 row_mask:0xf bank_mask:0xf
	v_fmac_f32_dpp v194, v144, v98 row_shl:15 row_mask:0xf bank_mask:0xf
	v_fmac_f32_dpp v195, v145, v99 row_shl:15 row_mask:0xf bank_mask:0xf
	v_fmac_f32_dpp v188, v150, v76 row_shl:14 row_mask:0xf bank_mask:0xf
	v_fmac_f32_dpp v189, v151, v77 row_shl:14 row_mask:0xf bank_mask:0xf
	v_fmac_f32_dpp v190, v152, v78 row_shl:14 row_mask:0xf bank_mask:0xf
	v_fmac_f32_dpp v191, v153, v79 row_shl:14 row_mask:0xf bank_mask:0xf
	v_fmac_f32_dpp v192, v142, v92 row_shl:14 row_mask:0xf bank_mask:0xf
	v_fmac_f32_dpp v193, v143, v93 row_shl:14 row_mask:0xf bank_mask:0xf
	v_fmac_f32_dpp v194, v144, v94 row_shl:14 row_mask:0xf bank_mask:0xf
	v_fmac_f32_dpp v195, v145, v95 row_shl:14 row_mask:0xf bank_mask:0xf
	v_pk_mul_f32 v[196:197], v[188:189], v[216:217] op_sel_hi:[1,0]
	v_pk_mul_f32 v[198:199], v[190:191], v[216:217] op_sel_hi:[1,0]
	v_exp_f32_e32 v196, v196
	v_exp_f32_e32 v197, v197
	v_exp_f32_e32 v198, v198
	v_exp_f32_e32 v199, v199
	v_pk_add_f32 v[196:197], v[196:197], v[214:215] op_sel_hi:[1,0]
	v_pk_add_f32 v[198:199], v[198:199], v[214:215] op_sel_hi:[1,0]
	v_rcp_f32_e32 v196, v196
	v_rcp_f32_e32 v197, v197
	v_rcp_f32_e32 v198, v198
	v_rcp_f32_e32 v199, v199
	v_pk_mul_f32 v[188:189], v[188:189], v[196:197]
	v_pk_mul_f32 v[190:191], v[190:191], v[198:199]
	v_pk_mul_f32 v[188:189], v[188:189], v[192:193]
	v_pk_mul_f32 v[190:191], v[190:191], v[194:195]
	v_cvt_pk_bf16_f32 v150, v188, v189
	v_cvt_pk_bf16_f32 v151, v190, v191
	v_add_u32_e32 v213, 0x2c000, v212
	global_load_dwordx4 v[142:145], v213, s[82:83] offset:16
	v_pk_fma_f32 v[188:189], v[138:139], v[84:85], v[88:89]
	v_pk_fma_f32 v[190:191], v[140:141], v[86:87], v[90:91]
	v_pk_fma_f32 v[192:193], v[130:131], v[100:101], v[104:105]
	v_pk_fma_f32 v[194:195], v[132:133], v[102:103], v[106:107]
	v_fmac_f32_dpp v188, v138, v80 row_shr:1 row_mask:0xf bank_mask:0xf
	v_fmac_f32_dpp v189, v139, v81 row_shr:1 row_mask:0xf bank_mask:0xf
	v_fmac_f32_dpp v190, v140, v82 row_shr:1 row_mask:0xf bank_mask:0xf
	v_fmac_f32_dpp v191, v141, v83 row_shr:1 row_mask:0xf bank_mask:0xf
	v_fmac_f32_dpp v192, v130, v96 row_shr:1 row_mask:0xf bank_mask:0xf
	v_fmac_f32_dpp v193, v131, v97 row_shr:1 row_mask:0xf bank_mask:0xf
	v_fmac_f32_dpp v194, v132, v98 row_shr:1 row_mask:0xf bank_mask:0xf
	v_fmac_f32_dpp v195, v133, v99 row_shr:1 row_mask:0xf bank_mask:0xf
	v_fmac_f32_dpp v188, v138, v76 row_shr:2 row_mask:0xf bank_mask:0xf
	v_fmac_f32_dpp v189, v139, v77 row_shr:2 row_mask:0xf bank_mask:0xf
	v_fmac_f32_dpp v190, v140, v78 row_shr:2 row_mask:0xf bank_mask:0xf
	v_fmac_f32_dpp v191, v141, v79 row_shr:2 row_mask:0xf bank_mask:0xf
	v_fmac_f32_dpp v192, v130, v92 row_shr:2 row_mask:0xf bank_mask:0xf
	v_fmac_f32_dpp v193, v131, v93 row_shr:2 row_mask:0xf bank_mask:0xf
	v_fmac_f32_dpp v194, v132, v94 row_shr:2 row_mask:0xf bank_mask:0xf
	v_fmac_f32_dpp v195, v133, v95 row_shr:2 row_mask:0xf bank_mask:0xf
	v_fmac_f32_dpp v188, v146, v80 row_shl:15 row_mask:0xf bank_mask:0xf
	v_fmac_f32_dpp v189, v147, v81 row_shl:15 row_mask:0xf bank_mask:0xf
	v_fmac_f32_dpp v190, v148, v82 row_shl:15 row_mask:0xf bank_mask:0xf
	v_fmac_f32_dpp v191, v149, v83 row_shl:15 row_mask:0xf bank_mask:0xf
	v_fmac_f32_dpp v192, v134, v96 row_shl:15 row_mask:0xf bank_mask:0xf
	v_fmac_f32_dpp v193, v135, v97 row_shl:15 row_mask:0xf bank_mask:0xf
	v_fmac_f32_dpp v194, v136, v98 row_shl:15 row_mask:0xf bank_mask:0xf
	v_fmac_f32_dpp v195, v137, v99 row_shl:15 row_mask:0xf bank_mask:0xf
	v_fmac_f32_dpp v188, v146, v76 row_shl:14 row_mask:0xf bank_mask:0xf
	v_fmac_f32_dpp v189, v147, v77 row_shl:14 row_mask:0xf bank_mask:0xf
	v_fmac_f32_dpp v190, v148, v78 row_shl:14 row_mask:0xf bank_mask:0xf
	v_fmac_f32_dpp v191, v149, v79 row_shl:14 row_mask:0xf bank_mask:0xf
	v_fmac_f32_dpp v192, v134, v92 row_shl:14 row_mask:0xf bank_mask:0xf
	v_fmac_f32_dpp v193, v135, v93 row_shl:14 row_mask:0xf bank_mask:0xf
	v_fmac_f32_dpp v194, v136, v94 row_shl:14 row_mask:0xf bank_mask:0xf
	v_fmac_f32_dpp v195, v137, v95 row_shl:14 row_mask:0xf bank_mask:0xf
	v_pk_mul_f32 v[196:197], v[188:189], v[216:217] op_sel_hi:[1,0]
	v_pk_mul_f32 v[198:199], v[190:191], v[216:217] op_sel_hi:[1,0]
	v_exp_f32_e32 v196, v196
	v_exp_f32_e32 v197, v197
	v_exp_f32_e32 v198, v198
	v_exp_f32_e32 v199, v199
	v_pk_add_f32 v[196:197], v[196:197], v[214:215] op_sel_hi:[1,0]
	v_pk_add_f32 v[198:199], v[198:199], v[214:215] op_sel_hi:[1,0]
	v_rcp_f32_e32 v196, v196
	v_rcp_f32_e32 v197, v197
	v_rcp_f32_e32 v198, v198
	v_rcp_f32_e32 v199, v199
	v_pk_mul_f32 v[188:189], v[188:189], v[196:197]
	v_pk_mul_f32 v[190:191], v[190:191], v[198:199]
	v_pk_mul_f32 v[188:189], v[188:189], v[192:193]
	v_pk_mul_f32 v[190:191], v[190:191], v[194:195]
	v_cvt_pk_bf16_f32 v146, v188, v189
	v_cvt_pk_bf16_f32 v147, v190, v191
	v_add_u32_e32 v213, 0x37000, v212
	global_load_dwordx4 v[134:137], v213, s[82:83] offset:16
	v_pk_fma_f32 v[188:189], v[126:127], v[84:85], v[88:89]
	v_pk_fma_f32 v[190:191], v[128:129], v[86:87], v[90:91]
	v_pk_fma_f32 v[192:193], v[118:119], v[100:101], v[104:105]
	v_pk_fma_f32 v[194:195], v[120:121], v[102:103], v[106:107]
	v_fmac_f32_dpp v188, v126, v80 row_shr:1 row_mask:0xf bank_mask:0xf
	v_fmac_f32_dpp v189, v127, v81 row_shr:1 row_mask:0xf bank_mask:0xf
	v_fmac_f32_dpp v190, v128, v82 row_shr:1 row_mask:0xf bank_mask:0xf
	v_fmac_f32_dpp v191, v129, v83 row_shr:1 row_mask:0xf bank_mask:0xf
	v_fmac_f32_dpp v192, v118, v96 row_shr:1 row_mask:0xf bank_mask:0xf
	v_fmac_f32_dpp v193, v119, v97 row_shr:1 row_mask:0xf bank_mask:0xf
	v_fmac_f32_dpp v194, v120, v98 row_shr:1 row_mask:0xf bank_mask:0xf
	v_fmac_f32_dpp v195, v121, v99 row_shr:1 row_mask:0xf bank_mask:0xf
	v_fmac_f32_dpp v188, v126, v76 row_shr:2 row_mask:0xf bank_mask:0xf
	v_fmac_f32_dpp v189, v127, v77 row_shr:2 row_mask:0xf bank_mask:0xf
	v_fmac_f32_dpp v190, v128, v78 row_shr:2 row_mask:0xf bank_mask:0xf
	v_fmac_f32_dpp v191, v129, v79 row_shr:2 row_mask:0xf bank_mask:0xf
	v_fmac_f32_dpp v192, v118, v92 row_shr:2 row_mask:0xf bank_mask:0xf
	v_fmac_f32_dpp v193, v119, v93 row_shr:2 row_mask:0xf bank_mask:0xf
	v_fmac_f32_dpp v194, v120, v94 row_shr:2 row_mask:0xf bank_mask:0xf
	v_fmac_f32_dpp v195, v121, v95 row_shr:2 row_mask:0xf bank_mask:0xf
	v_fmac_f32_dpp v188, v138, v80 row_shl:15 row_mask:0xf bank_mask:0xf
	v_fmac_f32_dpp v189, v139, v81 row_shl:15 row_mask:0xf bank_mask:0xf
	v_fmac_f32_dpp v190, v140, v82 row_shl:15 row_mask:0xf bank_mask:0xf
	v_fmac_f32_dpp v191, v141, v83 row_shl:15 row_mask:0xf bank_mask:0xf
	v_fmac_f32_dpp v192, v130, v96 row_shl:15 row_mask:0xf bank_mask:0xf
	v_fmac_f32_dpp v193, v131, v97 row_shl:15 row_mask:0xf bank_mask:0xf
	v_fmac_f32_dpp v194, v132, v98 row_shl:15 row_mask:0xf bank_mask:0xf
	v_fmac_f32_dpp v195, v133, v99 row_shl:15 row_mask:0xf bank_mask:0xf
	v_fmac_f32_dpp v188, v138, v76 row_shl:14 row_mask:0xf bank_mask:0xf
	v_fmac_f32_dpp v189, v139, v77 row_shl:14 row_mask:0xf bank_mask:0xf
	v_fmac_f32_dpp v190, v140, v78 row_shl:14 row_mask:0xf bank_mask:0xf
	v_fmac_f32_dpp v191, v141, v79 row_shl:14 row_mask:0xf bank_mask:0xf
	v_fmac_f32_dpp v192, v130, v92 row_shl:14 row_mask:0xf bank_mask:0xf
	v_fmac_f32_dpp v193, v131, v93 row_shl:14 row_mask:0xf bank_mask:0xf
	v_fmac_f32_dpp v194, v132, v94 row_shl:14 row_mask:0xf bank_mask:0xf
	v_fmac_f32_dpp v195, v133, v95 row_shl:14 row_mask:0xf bank_mask:0xf
	v_pk_mul_f32 v[196:197], v[188:189], v[216:217] op_sel_hi:[1,0]
	v_pk_mul_f32 v[198:199], v[190:191], v[216:217] op_sel_hi:[1,0]
	v_exp_f32_e32 v196, v196
	v_exp_f32_e32 v197, v197
	v_exp_f32_e32 v198, v198
	v_exp_f32_e32 v199, v199
	v_pk_add_f32 v[196:197], v[196:197], v[214:215] op_sel_hi:[1,0]
	v_pk_add_f32 v[198:199], v[198:199], v[214:215] op_sel_hi:[1,0]
	v_rcp_f32_e32 v196, v196
	v_rcp_f32_e32 v197, v197
	v_rcp_f32_e32 v198, v198
	v_rcp_f32_e32 v199, v199
	v_pk_mul_f32 v[188:189], v[188:189], v[196:197]
	v_pk_mul_f32 v[190:191], v[190:191], v[198:199]
	v_pk_mul_f32 v[188:189], v[188:189], v[192:193]
	v_pk_mul_f32 v[190:191], v[190:191], v[194:195]
	v_cvt_pk_bf16_f32 v138, v188, v189
	v_cvt_pk_bf16_f32 v139, v190, v191
	v_add_u32_e32 v213, 0xb000, v212
	global_load_dwordx4 v[130:133], v213, s[84:85] offset:16
	v_pk_fma_f32 v[188:189], v[122:123], v[84:85], v[88:89]
	v_pk_fma_f32 v[190:191], v[124:125], v[86:87], v[90:91]
	v_pk_fma_f32 v[192:193], v[110:111], v[100:101], v[104:105]
	v_pk_fma_f32 v[194:195], v[112:113], v[102:103], v[106:107]
	v_fmac_f32_dpp v188, v122, v80 row_shr:1 row_mask:0xf bank_mask:0xf
	v_fmac_f32_dpp v189, v123, v81 row_shr:1 row_mask:0xf bank_mask:0xf
	v_fmac_f32_dpp v190, v124, v82 row_shr:1 row_mask:0xf bank_mask:0xf
	v_fmac_f32_dpp v191, v125, v83 row_shr:1 row_mask:0xf bank_mask:0xf
	v_fmac_f32_dpp v192, v110, v96 row_shr:1 row_mask:0xf bank_mask:0xf
	v_fmac_f32_dpp v193, v111, v97 row_shr:1 row_mask:0xf bank_mask:0xf
	v_fmac_f32_dpp v194, v112, v98 row_shr:1 row_mask:0xf bank_mask:0xf
	v_fmac_f32_dpp v195, v113, v99 row_shr:1 row_mask:0xf bank_mask:0xf
	v_fmac_f32_dpp v188, v122, v76 row_shr:2 row_mask:0xf bank_mask:0xf
	v_fmac_f32_dpp v189, v123, v77 row_shr:2 row_mask:0xf bank_mask:0xf
	v_fmac_f32_dpp v190, v124, v78 row_shr:2 row_mask:0xf bank_mask:0xf
	v_fmac_f32_dpp v191, v125, v79 row_shr:2 row_mask:0xf bank_mask:0xf
	v_fmac_f32_dpp v192, v110, v92 row_shr:2 row_mask:0xf bank_mask:0xf
	v_fmac_f32_dpp v193, v111, v93 row_shr:2 row_mask:0xf bank_mask:0xf
	v_fmac_f32_dpp v194, v112, v94 row_shr:2 row_mask:0xf bank_mask:0xf
	v_fmac_f32_dpp v195, v113, v95 row_shr:2 row_mask:0xf bank_mask:0xf
	v_fmac_f32_dpp v188, v126, v80 row_shl:15 row_mask:0xf bank_mask:0xf
	v_fmac_f32_dpp v189, v127, v81 row_shl:15 row_mask:0xf bank_mask:0xf
	v_fmac_f32_dpp v190, v128, v82 row_shl:15 row_mask:0xf bank_mask:0xf
	v_fmac_f32_dpp v191, v129, v83 row_shl:15 row_mask:0xf bank_mask:0xf
	v_fmac_f32_dpp v192, v118, v96 row_shl:15 row_mask:0xf bank_mask:0xf
	v_fmac_f32_dpp v193, v119, v97 row_shl:15 row_mask:0xf bank_mask:0xf
	v_fmac_f32_dpp v194, v120, v98 row_shl:15 row_mask:0xf bank_mask:0xf
	v_fmac_f32_dpp v195, v121, v99 row_shl:15 row_mask:0xf bank_mask:0xf
	v_fmac_f32_dpp v188, v126, v76 row_shl:14 row_mask:0xf bank_mask:0xf
	v_fmac_f32_dpp v189, v127, v77 row_shl:14 row_mask:0xf bank_mask:0xf
	v_fmac_f32_dpp v190, v128, v78 row_shl:14 row_mask:0xf bank_mask:0xf
	v_fmac_f32_dpp v191, v129, v79 row_shl:14 row_mask:0xf bank_mask:0xf
	v_fmac_f32_dpp v192, v118, v92 row_shl:14 row_mask:0xf bank_mask:0xf
	v_fmac_f32_dpp v193, v119, v93 row_shl:14 row_mask:0xf bank_mask:0xf
	v_fmac_f32_dpp v194, v120, v94 row_shl:14 row_mask:0xf bank_mask:0xf
	v_fmac_f32_dpp v195, v121, v95 row_shl:14 row_mask:0xf bank_mask:0xf
	v_pk_mul_f32 v[196:197], v[188:189], v[216:217] op_sel_hi:[1,0]
	v_pk_mul_f32 v[198:199], v[190:191], v[216:217] op_sel_hi:[1,0]
	v_exp_f32_e32 v196, v196
	v_exp_f32_e32 v197, v197
	v_exp_f32_e32 v198, v198
	v_exp_f32_e32 v199, v199
	v_pk_add_f32 v[196:197], v[196:197], v[214:215] op_sel_hi:[1,0]
	v_pk_add_f32 v[198:199], v[198:199], v[214:215] op_sel_hi:[1,0]
	v_rcp_f32_e32 v196, v196
	v_rcp_f32_e32 v197, v197
	v_rcp_f32_e32 v198, v198
	v_rcp_f32_e32 v199, v199
	v_pk_mul_f32 v[188:189], v[188:189], v[196:197]
	v_pk_mul_f32 v[190:191], v[190:191], v[198:199]
	v_pk_mul_f32 v[188:189], v[188:189], v[192:193]
	v_pk_mul_f32 v[190:191], v[190:191], v[194:195]
	v_cvt_pk_bf16_f32 v126, v188, v189
	v_cvt_pk_bf16_f32 v127, v190, v191
	v_add_u32_e32 v213, 0x26800, v212
	global_load_dwordx4 v[118:121], v213, s[82:83] offset:16
	v_pk_fma_f32 v[188:189], v[114:115], v[84:85], v[88:89]
	v_pk_fma_f32 v[190:191], v[116:117], v[86:87], v[90:91]
	v_pk_fma_f32 v[192:193], v[68:69], v[100:101], v[104:105]
	v_pk_fma_f32 v[194:195], v[70:71], v[102:103], v[106:107]
	v_fmac_f32_dpp v188, v114, v80 row_shr:1 row_mask:0xf bank_mask:0xf
	v_fmac_f32_dpp v189, v115, v81 row_shr:1 row_mask:0xf bank_mask:0xf
	v_fmac_f32_dpp v190, v116, v82 row_shr:1 row_mask:0xf bank_mask:0xf
	v_fmac_f32_dpp v191, v117, v83 row_shr:1 row_mask:0xf bank_mask:0xf
	v_fmac_f32_dpp v192, v68, v96 row_shr:1 row_mask:0xf bank_mask:0xf
	v_fmac_f32_dpp v193, v69, v97 row_shr:1 row_mask:0xf bank_mask:0xf
	v_fmac_f32_dpp v194, v70, v98 row_shr:1 row_mask:0xf bank_mask:0xf
	v_fmac_f32_dpp v195, v71, v99 row_shr:1 row_mask:0xf bank_mask:0xf
	v_fmac_f32_dpp v188, v114, v76 row_shr:2 row_mask:0xf bank_mask:0xf
	v_fmac_f32_dpp v189, v115, v77 row_shr:2 row_mask:0xf bank_mask:0xf
	v_fmac_f32_dpp v190, v116, v78 row_shr:2 row_mask:0xf bank_mask:0xf
	v_fmac_f32_dpp v191, v117, v79 row_shr:2 row_mask:0xf bank_mask:0xf
	v_fmac_f32_dpp v192, v68, v92 row_shr:2 row_mask:0xf bank_mask:0xf
	v_fmac_f32_dpp v193, v69, v93 row_shr:2 row_mask:0xf bank_mask:0xf
	v_fmac_f32_dpp v194, v70, v94 row_shr:2 row_mask:0xf bank_mask:0xf
	v_fmac_f32_dpp v195, v71, v95 row_shr:2 row_mask:0xf bank_mask:0xf
	v_fmac_f32_dpp v188, v122, v80 row_shl:15 row_mask:0xf bank_mask:0xf
	v_fmac_f32_dpp v189, v123, v81 row_shl:15 row_mask:0xf bank_mask:0xf
	v_fmac_f32_dpp v190, v124, v82 row_shl:15 row_mask:0xf bank_mask:0xf
	v_fmac_f32_dpp v191, v125, v83 row_shl:15 row_mask:0xf bank_mask:0xf
	v_fmac_f32_dpp v192, v110, v96 row_shl:15 row_mask:0xf bank_mask:0xf
	v_fmac_f32_dpp v193, v111, v97 row_shl:15 row_mask:0xf bank_mask:0xf
	v_fmac_f32_dpp v194, v112, v98 row_shl:15 row_mask:0xf bank_mask:0xf
	v_fmac_f32_dpp v195, v113, v99 row_shl:15 row_mask:0xf bank_mask:0xf
	v_fmac_f32_dpp v188, v122, v76 row_shl:14 row_mask:0xf bank_mask:0xf
	v_fmac_f32_dpp v189, v123, v77 row_shl:14 row_mask:0xf bank_mask:0xf
	v_fmac_f32_dpp v190, v124, v78 row_shl:14 row_mask:0xf bank_mask:0xf
	v_fmac_f32_dpp v191, v125, v79 row_shl:14 row_mask:0xf bank_mask:0xf
	v_fmac_f32_dpp v192, v110, v92 row_shl:14 row_mask:0xf bank_mask:0xf
	v_fmac_f32_dpp v193, v111, v93 row_shl:14 row_mask:0xf bank_mask:0xf
	v_fmac_f32_dpp v194, v112, v94 row_shl:14 row_mask:0xf bank_mask:0xf
	v_fmac_f32_dpp v195, v113, v95 row_shl:14 row_mask:0xf bank_mask:0xf
	v_pk_mul_f32 v[196:197], v[188:189], v[216:217] op_sel_hi:[1,0]
	v_pk_mul_f32 v[198:199], v[190:191], v[216:217] op_sel_hi:[1,0]
	v_exp_f32_e32 v196, v196
	v_exp_f32_e32 v197, v197
	v_exp_f32_e32 v198, v198
	v_exp_f32_e32 v199, v199
	v_pk_add_f32 v[196:197], v[196:197], v[214:215] op_sel_hi:[1,0]
	v_pk_add_f32 v[198:199], v[198:199], v[214:215] op_sel_hi:[1,0]
	v_rcp_f32_e32 v196, v196
	v_rcp_f32_e32 v197, v197
	v_rcp_f32_e32 v198, v198
	v_rcp_f32_e32 v199, v199
	v_pk_mul_f32 v[188:189], v[188:189], v[196:197]
	v_pk_mul_f32 v[190:191], v[190:191], v[198:199]
	v_pk_mul_f32 v[188:189], v[188:189], v[192:193]
	v_pk_mul_f32 v[190:191], v[190:191], v[194:195]
	v_cvt_pk_bf16_f32 v122, v188, v189
	v_cvt_pk_bf16_f32 v123, v190, v191
	v_add_u32_e32 v213, 0x31800, v212
	global_load_dwordx4 v[110:113], v213, s[82:83] offset:16
	v_pk_fma_f32 v[188:189], v[72:73], v[84:85], v[88:89]
	v_pk_fma_f32 v[190:191], v[74:75], v[86:87], v[90:91]
	v_pk_fma_f32 v[192:193], v[64:65], v[100:101], v[104:105]
	v_pk_fma_f32 v[194:195], v[66:67], v[102:103], v[106:107]
	v_fmac_f32_dpp v188, v72, v80 row_shr:1 row_mask:0xf bank_mask:0xf
	v_fmac_f32_dpp v189, v73, v81 row_shr:1 row_mask:0xf bank_mask:0xf
	v_fmac_f32_dpp v190, v74, v82 row_shr:1 row_mask:0xf bank_mask:0xf
	v_fmac_f32_dpp v191, v75, v83 row_shr:1 row_mask:0xf bank_mask:0xf
	v_fmac_f32_dpp v192, v64, v96 row_shr:1 row_mask:0xf bank_mask:0xf
	v_fmac_f32_dpp v193, v65, v97 row_shr:1 row_mask:0xf bank_mask:0xf
	v_fmac_f32_dpp v194, v66, v98 row_shr:1 row_mask:0xf bank_mask:0xf
	v_fmac_f32_dpp v195, v67, v99 row_shr:1 row_mask:0xf bank_mask:0xf
	v_fmac_f32_dpp v188, v72, v76 row_shr:2 row_mask:0xf bank_mask:0xf
	v_fmac_f32_dpp v189, v73, v77 row_shr:2 row_mask:0xf bank_mask:0xf
	v_fmac_f32_dpp v190, v74, v78 row_shr:2 row_mask:0xf bank_mask:0xf
	v_fmac_f32_dpp v191, v75, v79 row_shr:2 row_mask:0xf bank_mask:0xf
	v_fmac_f32_dpp v192, v64, v92 row_shr:2 row_mask:0xf bank_mask:0xf
	v_fmac_f32_dpp v193, v65, v93 row_shr:2 row_mask:0xf bank_mask:0xf
	v_fmac_f32_dpp v194, v66, v94 row_shr:2 row_mask:0xf bank_mask:0xf
	v_fmac_f32_dpp v195, v67, v95 row_shr:2 row_mask:0xf bank_mask:0xf
	v_fmac_f32_dpp v188, v114, v80 row_shl:15 row_mask:0xf bank_mask:0xf
	v_fmac_f32_dpp v189, v115, v81 row_shl:15 row_mask:0xf bank_mask:0xf
	v_fmac_f32_dpp v190, v116, v82 row_shl:15 row_mask:0xf bank_mask:0xf
	v_fmac_f32_dpp v191, v117, v83 row_shl:15 row_mask:0xf bank_mask:0xf
	v_fmac_f32_dpp v192, v68, v96 row_shl:15 row_mask:0xf bank_mask:0xf
	v_fmac_f32_dpp v193, v69, v97 row_shl:15 row_mask:0xf bank_mask:0xf
	v_fmac_f32_dpp v194, v70, v98 row_shl:15 row_mask:0xf bank_mask:0xf
	v_fmac_f32_dpp v195, v71, v99 row_shl:15 row_mask:0xf bank_mask:0xf
	v_fmac_f32_dpp v188, v114, v76 row_shl:14 row_mask:0xf bank_mask:0xf
	v_fmac_f32_dpp v189, v115, v77 row_shl:14 row_mask:0xf bank_mask:0xf
	v_fmac_f32_dpp v190, v116, v78 row_shl:14 row_mask:0xf bank_mask:0xf
	v_fmac_f32_dpp v191, v117, v79 row_shl:14 row_mask:0xf bank_mask:0xf
	v_fmac_f32_dpp v192, v68, v92 row_shl:14 row_mask:0xf bank_mask:0xf
	v_fmac_f32_dpp v193, v69, v93 row_shl:14 row_mask:0xf bank_mask:0xf
	v_fmac_f32_dpp v194, v70, v94 row_shl:14 row_mask:0xf bank_mask:0xf
	v_fmac_f32_dpp v195, v71, v95 row_shl:14 row_mask:0xf bank_mask:0xf
	v_pk_mul_f32 v[196:197], v[188:189], v[216:217] op_sel_hi:[1,0]
	v_pk_mul_f32 v[198:199], v[190:191], v[216:217] op_sel_hi:[1,0]
	v_exp_f32_e32 v196, v196
	v_exp_f32_e32 v197, v197
	v_exp_f32_e32 v198, v198
	v_exp_f32_e32 v199, v199
	v_pk_add_f32 v[196:197], v[196:197], v[214:215] op_sel_hi:[1,0]
	v_pk_add_f32 v[198:199], v[198:199], v[214:215] op_sel_hi:[1,0]
	v_rcp_f32_e32 v196, v196
	v_rcp_f32_e32 v197, v197
	v_rcp_f32_e32 v198, v198
	v_rcp_f32_e32 v199, v199
	v_pk_mul_f32 v[188:189], v[188:189], v[196:197]
	v_pk_mul_f32 v[190:191], v[190:191], v[198:199]
	v_pk_mul_f32 v[188:189], v[188:189], v[192:193]
	v_pk_mul_f32 v[190:191], v[190:191], v[194:195]
	v_cvt_pk_bf16_f32 v114, v188, v189
	v_cvt_pk_bf16_f32 v115, v190, v191
	s_waitcnt vmcnt(0)
	v_pk_fma_f32 v[188:189], v[60:61], v[134:135], v[130:131]
	v_pk_fma_f32 v[190:191], v[62:63], v[136:137], v[132:133]
	v_pk_fma_f32 v[192:193], v[56:57], v[204:205], v[208:209]
	v_pk_fma_f32 v[194:195], v[58:59], v[206:207], v[210:211]
	v_fmac_f32_dpp v188, v60, v142 row_shr:1 row_mask:0xf bank_mask:0xf
	v_fmac_f32_dpp v189, v61, v143 row_shr:1 row_mask:0xf bank_mask:0xf
	v_fmac_f32_dpp v190, v62, v144 row_shr:1 row_mask:0xf bank_mask:0xf
	v_fmac_f32_dpp v191, v63, v145 row_shr:1 row_mask:0xf bank_mask:0xf
	v_fmac_f32_dpp v192, v56, v110 row_shr:1 row_mask:0xf bank_mask:0xf
	v_fmac_f32_dpp v193, v57, v111 row_shr:1 row_mask:0xf bank_mask:0xf
	v_fmac_f32_dpp v194, v58, v112 row_shr:1 row_mask:0xf bank_mask:0xf
	v_fmac_f32_dpp v195, v59, v113 row_shr:1 row_mask:0xf bank_mask:0xf
	v_fmac_f32_dpp v188, v60, v154 row_shr:2 row_mask:0xf bank_mask:0xf
	v_fmac_f32_dpp v189, v61, v155 row_shr:2 row_mask:0xf bank_mask:0xf
	v_fmac_f32_dpp v190, v62, v156 row_shr:2 row_mask:0xf bank_mask:0xf
	v_fmac_f32_dpp v191, v63, v157 row_shr:2 row_mask:0xf bank_mask:0xf
	v_fmac_f32_dpp v192, v56, v118 row_shr:2 row_mask:0xf bank_mask:0xf
	v_fmac_f32_dpp v193, v57, v119 row_shr:2 row_mask:0xf bank_mask:0xf
	v_fmac_f32_dpp v194, v58, v120 row_shr:2 row_mask:0xf bank_mask:0xf
	v_fmac_f32_dpp v195, v59, v121 row_shr:2 row_mask:0xf bank_mask:0xf
	v_pk_mul_f32 v[196:197], v[188:189], v[216:217] op_sel_hi:[1,0]
	v_pk_mul_f32 v[198:199], v[190:191], v[216:217] op_sel_hi:[1,0]
	v_exp_f32_e32 v196, v196
	v_exp_f32_e32 v197, v197
	v_exp_f32_e32 v198, v198
	v_exp_f32_e32 v199, v199
	v_pk_add_f32 v[196:197], v[196:197], v[214:215] op_sel_hi:[1,0]
	v_pk_add_f32 v[198:199], v[198:199], v[214:215] op_sel_hi:[1,0]
	v_rcp_f32_e32 v196, v196
	v_rcp_f32_e32 v197, v197
	v_rcp_f32_e32 v198, v198
	v_rcp_f32_e32 v199, v199
	v_pk_mul_f32 v[188:189], v[188:189], v[196:197]
	v_pk_mul_f32 v[190:191], v[190:191], v[198:199]
	v_pk_mul_f32 v[188:189], v[188:189], v[192:193]
	v_pk_mul_f32 v[190:191], v[190:191], v[194:195]
	v_cvt_pk_bf16_f32 v202, v188, v189
	v_cvt_pk_bf16_f32 v203, v190, v191
	s_mov_b64 exec, vcc
	global_store_dwordx4 v215, v[200:203], s[96:97]
	s_mov_b64 exec, -1
	v_pk_fma_f32 v[188:189], v[52:53], v[134:135], v[130:131]
	v_pk_fma_f32 v[190:191], v[54:55], v[136:137], v[132:133]
	v_pk_fma_f32 v[192:193], v[44:45], v[204:205], v[208:209]
	v_pk_fma_f32 v[194:195], v[46:47], v[206:207], v[210:211]
	v_fmac_f32_dpp v188, v52, v142 row_shr:1 row_mask:0xf bank_mask:0xf
	v_fmac_f32_dpp v189, v53, v143 row_shr:1 row_mask:0xf bank_mask:0xf
	v_fmac_f32_dpp v190, v54, v144 row_shr:1 row_mask:0xf bank_mask:0xf
	v_fmac_f32_dpp v191, v55, v145 row_shr:1 row_mask:0xf bank_mask:0xf
	v_fmac_f32_dpp v192, v44, v110 row_shr:1 row_mask:0xf bank_mask:0xf
	v_fmac_f32_dpp v193, v45, v111 row_shr:1 row_mask:0xf bank_mask:0xf
	v_fmac_f32_dpp v194, v46, v112 row_shr:1 row_mask:0xf bank_mask:0xf
	v_fmac_f32_dpp v195, v47, v113 row_shr:1 row_mask:0xf bank_mask:0xf
	v_fmac_f32_dpp v188, v52, v154 row_shr:2 row_mask:0xf bank_mask:0xf
	v_fmac_f32_dpp v189, v53, v155 row_shr:2 row_mask:0xf bank_mask:0xf
	v_fmac_f32_dpp v190, v54, v156 row_shr:2 row_mask:0xf bank_mask:0xf
	v_fmac_f32_dpp v191, v55, v157 row_shr:2 row_mask:0xf bank_mask:0xf
	v_fmac_f32_dpp v192, v44, v118 row_shr:2 row_mask:0xf bank_mask:0xf
	v_fmac_f32_dpp v193, v45, v119 row_shr:2 row_mask:0xf bank_mask:0xf
	v_fmac_f32_dpp v194, v46, v120 row_shr:2 row_mask:0xf bank_mask:0xf
	v_fmac_f32_dpp v195, v47, v121 row_shr:2 row_mask:0xf bank_mask:0xf
	v_fmac_f32_dpp v188, v60, v142 row_shl:15 row_mask:0xf bank_mask:0xf
	v_fmac_f32_dpp v189, v61, v143 row_shl:15 row_mask:0xf bank_mask:0xf
	v_fmac_f32_dpp v190, v62, v144 row_shl:15 row_mask:0xf bank_mask:0xf
	v_fmac_f32_dpp v191, v63, v145 row_shl:15 row_mask:0xf bank_mask:0xf
	v_fmac_f32_dpp v192, v56, v110 row_shl:15 row_mask:0xf bank_mask:0xf
	v_fmac_f32_dpp v193, v57, v111 row_shl:15 row_mask:0xf bank_mask:0xf
	v_fmac_f32_dpp v194, v58, v112 row_shl:15 row_mask:0xf bank_mask:0xf
	v_fmac_f32_dpp v195, v59, v113 row_shl:15 row_mask:0xf bank_mask:0xf
	v_fmac_f32_dpp v188, v60, v154 row_shl:14 row_mask:0xf bank_mask:0xf
	v_fmac_f32_dpp v189, v61, v155 row_shl:14 row_mask:0xf bank_mask:0xf
	v_fmac_f32_dpp v190, v62, v156 row_shl:14 row_mask:0xf bank_mask:0xf
	v_fmac_f32_dpp v191, v63, v157 row_shl:14 row_mask:0xf bank_mask:0xf
	v_fmac_f32_dpp v192, v56, v118 row_shl:14 row_mask:0xf bank_mask:0xf
	v_fmac_f32_dpp v193, v57, v119 row_shl:14 row_mask:0xf bank_mask:0xf
	v_fmac_f32_dpp v194, v58, v120 row_shl:14 row_mask:0xf bank_mask:0xf
	v_fmac_f32_dpp v195, v59, v121 row_shl:14 row_mask:0xf bank_mask:0xf
	v_pk_mul_f32 v[196:197], v[188:189], v[216:217] op_sel_hi:[1,0]
	v_pk_mul_f32 v[198:199], v[190:191], v[216:217] op_sel_hi:[1,0]
	v_exp_f32_e32 v196, v196
	v_exp_f32_e32 v197, v197
	v_exp_f32_e32 v198, v198
	v_exp_f32_e32 v199, v199
	v_pk_add_f32 v[196:197], v[196:197], v[214:215] op_sel_hi:[1,0]
	v_pk_add_f32 v[198:199], v[198:199], v[214:215] op_sel_hi:[1,0]
	v_rcp_f32_e32 v196, v196
	v_rcp_f32_e32 v197, v197
	v_rcp_f32_e32 v198, v198
	v_rcp_f32_e32 v199, v199
	v_pk_mul_f32 v[188:189], v[188:189], v[196:197]
	v_pk_mul_f32 v[190:191], v[190:191], v[198:199]
	v_pk_mul_f32 v[188:189], v[188:189], v[192:193]
	v_pk_mul_f32 v[190:191], v[190:191], v[194:195]
	v_cvt_pk_bf16_f32 v160, v188, v189
	v_cvt_pk_bf16_f32 v161, v190, v191
	v_add_u32_e32 v213, 0x2c000, v215
	global_store_dwordx4 v213, v[158:161], s[96:97]
	v_pk_fma_f32 v[188:189], v[48:49], v[134:135], v[130:131]
	v_pk_fma_f32 v[190:191], v[50:51], v[136:137], v[132:133]
	v_pk_fma_f32 v[192:193], v[36:37], v[204:205], v[208:209]
	v_pk_fma_f32 v[194:195], v[38:39], v[206:207], v[210:211]
	v_fmac_f32_dpp v188, v48, v142 row_shr:1 row_mask:0xf bank_mask:0xf
	v_fmac_f32_dpp v189, v49, v143 row_shr:1 row_mask:0xf bank_mask:0xf
	v_fmac_f32_dpp v190, v50, v144 row_shr:1 row_mask:0xf bank_mask:0xf
	v_fmac_f32_dpp v191, v51, v145 row_shr:1 row_mask:0xf bank_mask:0xf
	v_fmac_f32_dpp v192, v36, v110 row_shr:1 row_mask:0xf bank_mask:0xf
	v_fmac_f32_dpp v193, v37, v111 row_shr:1 row_mask:0xf bank_mask:0xf
	v_fmac_f32_dpp v194, v38, v112 row_shr:1 row_mask:0xf bank_mask:0xf
	v_fmac_f32_dpp v195, v39, v113 row_shr:1 row_mask:0xf bank_mask:0xf
	v_fmac_f32_dpp v188, v48, v154 row_shr:2 row_mask:0xf bank_mask:0xf
	v_fmac_f32_dpp v189, v49, v155 row_shr:2 row_mask:0xf bank_mask:0xf
	v_fmac_f32_dpp v190, v50, v156 row_shr:2 row_mask:0xf bank_mask:0xf
	v_fmac_f32_dpp v191, v51, v157 row_shr:2 row_mask:0xf bank_mask:0xf
	v_fmac_f32_dpp v192, v36, v118 row_shr:2 row_mask:0xf bank_mask:0xf
	v_fmac_f32_dpp v193, v37, v119 row_shr:2 row_mask:0xf bank_mask:0xf
	v_fmac_f32_dpp v194, v38, v120 row_shr:2 row_mask:0xf bank_mask:0xf
	v_fmac_f32_dpp v195, v39, v121 row_shr:2 row_mask:0xf bank_mask:0xf
	v_fmac_f32_dpp v188, v52, v142 row_shl:15 row_mask:0xf bank_mask:0xf
	v_fmac_f32_dpp v189, v53, v143 row_shl:15 row_mask:0xf bank_mask:0xf
	v_fmac_f32_dpp v190, v54, v144 row_shl:15 row_mask:0xf bank_mask:0xf
	v_fmac_f32_dpp v191, v55, v145 row_shl:15 row_mask:0xf bank_mask:0xf
	v_fmac_f32_dpp v192, v44, v110 row_shl:15 row_mask:0xf bank_mask:0xf
	v_fmac_f32_dpp v193, v45, v111 row_shl:15 row_mask:0xf bank_mask:0xf
	v_fmac_f32_dpp v194, v46, v112 row_shl:15 row_mask:0xf bank_mask:0xf
	v_fmac_f32_dpp v195, v47, v113 row_shl:15 row_mask:0xf bank_mask:0xf
	v_fmac_f32_dpp v188, v52, v154 row_shl:14 row_mask:0xf bank_mask:0xf
	v_fmac_f32_dpp v189, v53, v155 row_shl:14 row_mask:0xf bank_mask:0xf
	v_fmac_f32_dpp v190, v54, v156 row_shl:14 row_mask:0xf bank_mask:0xf
	v_fmac_f32_dpp v191, v55, v157 row_shl:14 row_mask:0xf bank_mask:0xf
	v_fmac_f32_dpp v192, v44, v118 row_shl:14 row_mask:0xf bank_mask:0xf
	v_fmac_f32_dpp v193, v45, v119 row_shl:14 row_mask:0xf bank_mask:0xf
	v_fmac_f32_dpp v194, v46, v120 row_shl:14 row_mask:0xf bank_mask:0xf
	v_fmac_f32_dpp v195, v47, v121 row_shl:14 row_mask:0xf bank_mask:0xf
	v_pk_mul_f32 v[196:197], v[188:189], v[216:217] op_sel_hi:[1,0]
	v_pk_mul_f32 v[198:199], v[190:191], v[216:217] op_sel_hi:[1,0]
	v_exp_f32_e32 v196, v196
	v_exp_f32_e32 v197, v197
	v_exp_f32_e32 v198, v198
	v_exp_f32_e32 v199, v199
	v_pk_add_f32 v[196:197], v[196:197], v[214:215] op_sel_hi:[1,0]
	v_pk_add_f32 v[198:199], v[198:199], v[214:215] op_sel_hi:[1,0]
	v_rcp_f32_e32 v196, v196
	v_rcp_f32_e32 v197, v197
	v_rcp_f32_e32 v198, v198
	v_rcp_f32_e32 v199, v199
	v_pk_mul_f32 v[188:189], v[188:189], v[196:197]
	v_pk_mul_f32 v[190:191], v[190:191], v[198:199]
	v_pk_mul_f32 v[188:189], v[188:189], v[192:193]
	v_pk_mul_f32 v[190:191], v[190:191], v[194:195]
	v_cvt_pk_bf16_f32 v152, v188, v189
	v_cvt_pk_bf16_f32 v153, v190, v191
	v_add_u32_e32 v213, 0x58000, v215
	global_store_dwordx4 v213, v[150:153], s[96:97]
	v_pk_fma_f32 v[188:189], v[40:41], v[134:135], v[130:131]
	v_pk_fma_f32 v[190:191], v[42:43], v[136:137], v[132:133]
	v_pk_fma_f32 v[192:193], v[32:33], v[204:205], v[208:209]
	v_pk_fma_f32 v[194:195], v[34:35], v[206:207], v[210:211]
	v_fmac_f32_dpp v188, v40, v142 row_shr:1 row_mask:0xf bank_mask:0xf
	v_fmac_f32_dpp v189, v41, v143 row_shr:1 row_mask:0xf bank_mask:0xf
	v_fmac_f32_dpp v190, v42, v144 row_shr:1 row_mask:0xf bank_mask:0xf
	v_fmac_f32_dpp v191, v43, v145 row_shr:1 row_mask:0xf bank_mask:0xf
	v_fmac_f32_dpp v192, v32, v110 row_shr:1 row_mask:0xf bank_mask:0xf
	v_fmac_f32_dpp v193, v33, v111 row_shr:1 row_mask:0xf bank_mask:0xf
	v_fmac_f32_dpp v194, v34, v112 row_shr:1 row_mask:0xf bank_mask:0xf
	v_fmac_f32_dpp v195, v35, v113 row_shr:1 row_mask:0xf bank_mask:0xf
	v_fmac_f32_dpp v188, v40, v154 row_shr:2 row_mask:0xf bank_mask:0xf
	v_fmac_f32_dpp v189, v41, v155 row_shr:2 row_mask:0xf bank_mask:0xf
	v_fmac_f32_dpp v190, v42, v156 row_shr:2 row_mask:0xf bank_mask:0xf
	v_fmac_f32_dpp v191, v43, v157 row_shr:2 row_mask:0xf bank_mask:0xf
	v_fmac_f32_dpp v192, v32, v118 row_shr:2 row_mask:0xf bank_mask:0xf
	v_fmac_f32_dpp v193, v33, v119 row_shr:2 row_mask:0xf bank_mask:0xf
	v_fmac_f32_dpp v194, v34, v120 row_shr:2 row_mask:0xf bank_mask:0xf
	v_fmac_f32_dpp v195, v35, v121 row_shr:2 row_mask:0xf bank_mask:0xf
	v_fmac_f32_dpp v188, v48, v142 row_shl:15 row_mask:0xf bank_mask:0xf
	v_fmac_f32_dpp v189, v49, v143 row_shl:15 row_mask:0xf bank_mask:0xf
	v_fmac_f32_dpp v190, v50, v144 row_shl:15 row_mask:0xf bank_mask:0xf
	v_fmac_f32_dpp v191, v51, v145 row_shl:15 row_mask:0xf bank_mask:0xf
	v_fmac_f32_dpp v192, v36, v110 row_shl:15 row_mask:0xf bank_mask:0xf
	v_fmac_f32_dpp v193, v37, v111 row_shl:15 row_mask:0xf bank_mask:0xf
	v_fmac_f32_dpp v194, v38, v112 row_shl:15 row_mask:0xf bank_mask:0xf
	v_fmac_f32_dpp v195, v39, v113 row_shl:15 row_mask:0xf bank_mask:0xf
	v_fmac_f32_dpp v188, v48, v154 row_shl:14 row_mask:0xf bank_mask:0xf
	v_fmac_f32_dpp v189, v49, v155 row_shl:14 row_mask:0xf bank_mask:0xf
	v_fmac_f32_dpp v190, v50, v156 row_shl:14 row_mask:0xf bank_mask:0xf
	v_fmac_f32_dpp v191, v51, v157 row_shl:14 row_mask:0xf bank_mask:0xf
	v_fmac_f32_dpp v192, v36, v118 row_shl:14 row_mask:0xf bank_mask:0xf
	v_fmac_f32_dpp v193, v37, v119 row_shl:14 row_mask:0xf bank_mask:0xf
	v_fmac_f32_dpp v194, v38, v120 row_shl:14 row_mask:0xf bank_mask:0xf
	v_fmac_f32_dpp v195, v39, v121 row_shl:14 row_mask:0xf bank_mask:0xf
	v_pk_mul_f32 v[196:197], v[188:189], v[216:217] op_sel_hi:[1,0]
	v_pk_mul_f32 v[198:199], v[190:191], v[216:217] op_sel_hi:[1,0]
	v_exp_f32_e32 v196, v196
	v_exp_f32_e32 v197, v197
	v_exp_f32_e32 v198, v198
	v_exp_f32_e32 v199, v199
	v_pk_add_f32 v[196:197], v[196:197], v[214:215] op_sel_hi:[1,0]
	v_pk_add_f32 v[198:199], v[198:199], v[214:215] op_sel_hi:[1,0]
	v_rcp_f32_e32 v196, v196
	v_rcp_f32_e32 v197, v197
	v_rcp_f32_e32 v198, v198
	v_rcp_f32_e32 v199, v199
	v_pk_mul_f32 v[188:189], v[188:189], v[196:197]
	v_pk_mul_f32 v[190:191], v[190:191], v[198:199]
	v_pk_mul_f32 v[188:189], v[188:189], v[192:193]
	v_pk_mul_f32 v[190:191], v[190:191], v[194:195]
	v_cvt_pk_bf16_f32 v148, v188, v189
	v_cvt_pk_bf16_f32 v149, v190, v191
	v_add_u32_e32 v213, 0x84000, v215
	global_store_dwordx4 v213, v[146:149], s[96:97]
	v_pk_fma_f32 v[188:189], v[28:29], v[134:135], v[130:131]
	v_pk_fma_f32 v[190:191], v[30:31], v[136:137], v[132:133]
	v_pk_fma_f32 v[192:193], v[16:17], v[204:205], v[208:209]
	v_pk_fma_f32 v[194:195], v[18:19], v[206:207], v[210:211]
	v_fmac_f32_dpp v188, v28, v142 row_shr:1 row_mask:0xf bank_mask:0xf
	v_fmac_f32_dpp v189, v29, v143 row_shr:1 row_mask:0xf bank_mask:0xf
	v_fmac_f32_dpp v190, v30, v144 row_shr:1 row_mask:0xf bank_mask:0xf
	v_fmac_f32_dpp v191, v31, v145 row_shr:1 row_mask:0xf bank_mask:0xf
	v_fmac_f32_dpp v192, v16, v110 row_shr:1 row_mask:0xf bank_mask:0xf
	v_fmac_f32_dpp v193, v17, v111 row_shr:1 row_mask:0xf bank_mask:0xf
	v_fmac_f32_dpp v194, v18, v112 row_shr:1 row_mask:0xf bank_mask:0xf
	v_fmac_f32_dpp v195, v19, v113 row_shr:1 row_mask:0xf bank_mask:0xf
	v_fmac_f32_dpp v188, v28, v154 row_shr:2 row_mask:0xf bank_mask:0xf
	v_fmac_f32_dpp v189, v29, v155 row_shr:2 row_mask:0xf bank_mask:0xf
	v_fmac_f32_dpp v190, v30, v156 row_shr:2 row_mask:0xf bank_mask:0xf
	v_fmac_f32_dpp v191, v31, v157 row_shr:2 row_mask:0xf bank_mask:0xf
	v_fmac_f32_dpp v192, v16, v118 row_shr:2 row_mask:0xf bank_mask:0xf
	v_fmac_f32_dpp v193, v17, v119 row_shr:2 row_mask:0xf bank_mask:0xf
	v_fmac_f32_dpp v194, v18, v120 row_shr:2 row_mask:0xf bank_mask:0xf
	v_fmac_f32_dpp v195, v19, v121 row_shr:2 row_mask:0xf bank_mask:0xf
	v_fmac_f32_dpp v188, v40, v142 row_shl:15 row_mask:0xf bank_mask:0xf
	v_fmac_f32_dpp v189, v41, v143 row_shl:15 row_mask:0xf bank_mask:0xf
	v_fmac_f32_dpp v190, v42, v144 row_shl:15 row_mask:0xf bank_mask:0xf
	v_fmac_f32_dpp v191, v43, v145 row_shl:15 row_mask:0xf bank_mask:0xf
	v_fmac_f32_dpp v192, v32, v110 row_shl:15 row_mask:0xf bank_mask:0xf
	v_fmac_f32_dpp v193, v33, v111 row_shl:15 row_mask:0xf bank_mask:0xf
	v_fmac_f32_dpp v194, v34, v112 row_shl:15 row_mask:0xf bank_mask:0xf
	v_fmac_f32_dpp v195, v35, v113 row_shl:15 row_mask:0xf bank_mask:0xf
	v_fmac_f32_dpp v188, v40, v154 row_shl:14 row_mask:0xf bank_mask:0xf
	v_fmac_f32_dpp v189, v41, v155 row_shl:14 row_mask:0xf bank_mask:0xf
	v_fmac_f32_dpp v190, v42, v156 row_shl:14 row_mask:0xf bank_mask:0xf
	v_fmac_f32_dpp v191, v43, v157 row_shl:14 row_mask:0xf bank_mask:0xf
	v_fmac_f32_dpp v192, v32, v118 row_shl:14 row_mask:0xf bank_mask:0xf
	v_fmac_f32_dpp v193, v33, v119 row_shl:14 row_mask:0xf bank_mask:0xf
	v_fmac_f32_dpp v194, v34, v120 row_shl:14 row_mask:0xf bank_mask:0xf
	v_fmac_f32_dpp v195, v35, v121 row_shl:14 row_mask:0xf bank_mask:0xf
	v_pk_mul_f32 v[196:197], v[188:189], v[216:217] op_sel_hi:[1,0]
	v_pk_mul_f32 v[198:199], v[190:191], v[216:217] op_sel_hi:[1,0]
	v_exp_f32_e32 v196, v196
	v_exp_f32_e32 v197, v197
	v_exp_f32_e32 v198, v198
	v_exp_f32_e32 v199, v199
	v_pk_add_f32 v[196:197], v[196:197], v[214:215] op_sel_hi:[1,0]
	v_pk_add_f32 v[198:199], v[198:199], v[214:215] op_sel_hi:[1,0]
	v_rcp_f32_e32 v196, v196
	v_rcp_f32_e32 v197, v197
	v_rcp_f32_e32 v198, v198
	v_rcp_f32_e32 v199, v199
	v_pk_mul_f32 v[188:189], v[188:189], v[196:197]
	v_pk_mul_f32 v[190:191], v[190:191], v[198:199]
	v_pk_mul_f32 v[188:189], v[188:189], v[192:193]
	v_pk_mul_f32 v[190:191], v[190:191], v[194:195]
	v_cvt_pk_bf16_f32 v140, v188, v189
	v_cvt_pk_bf16_f32 v141, v190, v191
	v_add_u32_e32 v213, 0xb0000, v215
	global_store_dwordx4 v213, v[138:141], s[96:97]
	v_pk_fma_f32 v[188:189], v[24:25], v[134:135], v[130:131]
	v_pk_fma_f32 v[190:191], v[26:27], v[136:137], v[132:133]
	v_pk_fma_f32 v[192:193], v[12:13], v[204:205], v[208:209]
	v_pk_fma_f32 v[194:195], v[14:15], v[206:207], v[210:211]
	v_fmac_f32_dpp v188, v24, v142 row_shr:1 row_mask:0xf bank_mask:0xf
	v_fmac_f32_dpp v189, v25, v143 row_shr:1 row_mask:0xf bank_mask:0xf
	v_fmac_f32_dpp v190, v26, v144 row_shr:1 row_mask:0xf bank_mask:0xf
	v_fmac_f32_dpp v191, v27, v145 row_shr:1 row_mask:0xf bank_mask:0xf
	v_fmac_f32_dpp v192, v12, v110 row_shr:1 row_mask:0xf bank_mask:0xf
	v_fmac_f32_dpp v193, v13, v111 row_shr:1 row_mask:0xf bank_mask:0xf
	v_fmac_f32_dpp v194, v14, v112 row_shr:1 row_mask:0xf bank_mask:0xf
	v_fmac_f32_dpp v195, v15, v113 row_shr:1 row_mask:0xf bank_mask:0xf
	v_fmac_f32_dpp v188, v24, v154 row_shr:2 row_mask:0xf bank_mask:0xf
	v_fmac_f32_dpp v189, v25, v155 row_shr:2 row_mask:0xf bank_mask:0xf
	v_fmac_f32_dpp v190, v26, v156 row_shr:2 row_mask:0xf bank_mask:0xf
	v_fmac_f32_dpp v191, v27, v157 row_shr:2 row_mask:0xf bank_mask:0xf
	v_fmac_f32_dpp v192, v12, v118 row_shr:2 row_mask:0xf bank_mask:0xf
	v_fmac_f32_dpp v193, v13, v119 row_shr:2 row_mask:0xf bank_mask:0xf
	v_fmac_f32_dpp v194, v14, v120 row_shr:2 row_mask:0xf bank_mask:0xf
	v_fmac_f32_dpp v195, v15, v121 row_shr:2 row_mask:0xf bank_mask:0xf
	v_fmac_f32_dpp v188, v28, v142 row_shl:15 row_mask:0xf bank_mask:0xf
	v_fmac_f32_dpp v189, v29, v143 row_shl:15 row_mask:0xf bank_mask:0xf
	v_fmac_f32_dpp v190, v30, v144 row_shl:15 row_mask:0xf bank_mask:0xf
	v_fmac_f32_dpp v191, v31, v145 row_shl:15 row_mask:0xf bank_mask:0xf
	v_fmac_f32_dpp v192, v16, v110 row_shl:15 row_mask:0xf bank_mask:0xf
	v_fmac_f32_dpp v193, v17, v111 row_shl:15 row_mask:0xf bank_mask:0xf
	v_fmac_f32_dpp v194, v18, v112 row_shl:15 row_mask:0xf bank_mask:0xf
	v_fmac_f32_dpp v195, v19, v113 row_shl:15 row_mask:0xf bank_mask:0xf
	v_fmac_f32_dpp v188, v28, v154 row_shl:14 row_mask:0xf bank_mask:0xf
	v_fmac_f32_dpp v189, v29, v155 row_shl:14 row_mask:0xf bank_mask:0xf
	v_fmac_f32_dpp v190, v30, v156 row_shl:14 row_mask:0xf bank_mask:0xf
	v_fmac_f32_dpp v191, v31, v157 row_shl:14 row_mask:0xf bank_mask:0xf
	v_fmac_f32_dpp v192, v16, v118 row_shl:14 row_mask:0xf bank_mask:0xf
	v_fmac_f32_dpp v193, v17, v119 row_shl:14 row_mask:0xf bank_mask:0xf
	v_fmac_f32_dpp v194, v18, v120 row_shl:14 row_mask:0xf bank_mask:0xf
	v_fmac_f32_dpp v195, v19, v121 row_shl:14 row_mask:0xf bank_mask:0xf
	v_pk_mul_f32 v[196:197], v[188:189], v[216:217] op_sel_hi:[1,0]
	v_pk_mul_f32 v[198:199], v[190:191], v[216:217] op_sel_hi:[1,0]
	v_exp_f32_e32 v196, v196
	v_exp_f32_e32 v197, v197
	v_exp_f32_e32 v198, v198
	v_exp_f32_e32 v199, v199
	v_pk_add_f32 v[196:197], v[196:197], v[214:215] op_sel_hi:[1,0]
	v_pk_add_f32 v[198:199], v[198:199], v[214:215] op_sel_hi:[1,0]
	v_rcp_f32_e32 v196, v196
	v_rcp_f32_e32 v197, v197
	v_rcp_f32_e32 v198, v198
	v_rcp_f32_e32 v199, v199
	v_pk_mul_f32 v[188:189], v[188:189], v[196:197]
	v_pk_mul_f32 v[190:191], v[190:191], v[198:199]
	v_pk_mul_f32 v[188:189], v[188:189], v[192:193]
	v_pk_mul_f32 v[190:191], v[190:191], v[194:195]
	v_cvt_pk_bf16_f32 v128, v188, v189
	v_cvt_pk_bf16_f32 v129, v190, v191
	v_add_u32_e32 v213, 0xdc000, v215
	global_store_dwordx4 v213, v[126:129], s[96:97]
	v_pk_fma_f32 v[188:189], v[20:21], v[134:135], v[130:131]
	v_pk_fma_f32 v[190:191], v[22:23], v[136:137], v[132:133]
	v_pk_fma_f32 v[192:193], v[8:9], v[204:205], v[208:209]
	v_pk_fma_f32 v[194:195], v[10:11], v[206:207], v[210:211]
	v_fmac_f32_dpp v188, v20, v142 row_shr:1 row_mask:0xf bank_mask:0xf
	v_fmac_f32_dpp v189, v21, v143 row_shr:1 row_mask:0xf bank_mask:0xf
	v_fmac_f32_dpp v190, v22, v144 row_shr:1 row_mask:0xf bank_mask:0xf
	v_fmac_f32_dpp v191, v23, v145 row_shr:1 row_mask:0xf bank_mask:0xf
	v_fmac_f32_dpp v192, v8, v110 row_shr:1 row_mask:0xf bank_mask:0xf
	v_fmac_f32_dpp v193, v9, v111 row_shr:1 row_mask:0xf bank_mask:0xf
	v_fmac_f32_dpp v194, v10, v112 row_shr:1 row_mask:0xf bank_mask:0xf
	v_fmac_f32_dpp v195, v11, v113 row_shr:1 row_mask:0xf bank_mask:0xf
	v_fmac_f32_dpp v188, v20, v154 row_shr:2 row_mask:0xf bank_mask:0xf
	v_fmac_f32_dpp v189, v21, v155 row_shr:2 row_mask:0xf bank_mask:0xf
	v_fmac_f32_dpp v190, v22, v156 row_shr:2 row_mask:0xf bank_mask:0xf
	v_fmac_f32_dpp v191, v23, v157 row_shr:2 row_mask:0xf bank_mask:0xf
	v_fmac_f32_dpp v192, v8, v118 row_shr:2 row_mask:0xf bank_mask:0xf
	v_fmac_f32_dpp v193, v9, v119 row_shr:2 row_mask:0xf bank_mask:0xf
	v_fmac_f32_dpp v194, v10, v120 row_shr:2 row_mask:0xf bank_mask:0xf
	v_fmac_f32_dpp v195, v11, v121 row_shr:2 row_mask:0xf bank_mask:0xf
	v_fmac_f32_dpp v188, v24, v142 row_shl:15 row_mask:0xf bank_mask:0xf
	v_fmac_f32_dpp v189, v25, v143 row_shl:15 row_mask:0xf bank_mask:0xf
	v_fmac_f32_dpp v190, v26, v144 row_shl:15 row_mask:0xf bank_mask:0xf
	v_fmac_f32_dpp v191, v27, v145 row_shl:15 row_mask:0xf bank_mask:0xf
	v_fmac_f32_dpp v192, v12, v110 row_shl:15 row_mask:0xf bank_mask:0xf
	v_fmac_f32_dpp v193, v13, v111 row_shl:15 row_mask:0xf bank_mask:0xf
	v_fmac_f32_dpp v194, v14, v112 row_shl:15 row_mask:0xf bank_mask:0xf
	v_fmac_f32_dpp v195, v15, v113 row_shl:15 row_mask:0xf bank_mask:0xf
	v_fmac_f32_dpp v188, v24, v154 row_shl:14 row_mask:0xf bank_mask:0xf
	v_fmac_f32_dpp v189, v25, v155 row_shl:14 row_mask:0xf bank_mask:0xf
	v_fmac_f32_dpp v190, v26, v156 row_shl:14 row_mask:0xf bank_mask:0xf
	v_fmac_f32_dpp v191, v27, v157 row_shl:14 row_mask:0xf bank_mask:0xf
	v_fmac_f32_dpp v192, v12, v118 row_shl:14 row_mask:0xf bank_mask:0xf
	v_fmac_f32_dpp v193, v13, v119 row_shl:14 row_mask:0xf bank_mask:0xf
	v_fmac_f32_dpp v194, v14, v120 row_shl:14 row_mask:0xf bank_mask:0xf
	v_fmac_f32_dpp v195, v15, v121 row_shl:14 row_mask:0xf bank_mask:0xf
	v_pk_mul_f32 v[196:197], v[188:189], v[216:217] op_sel_hi:[1,0]
	v_pk_mul_f32 v[198:199], v[190:191], v[216:217] op_sel_hi:[1,0]
	v_exp_f32_e32 v196, v196
	v_exp_f32_e32 v197, v197
	v_exp_f32_e32 v198, v198
	v_exp_f32_e32 v199, v199
	v_pk_add_f32 v[196:197], v[196:197], v[214:215] op_sel_hi:[1,0]
	v_pk_add_f32 v[198:199], v[198:199], v[214:215] op_sel_hi:[1,0]
	v_rcp_f32_e32 v196, v196
	v_rcp_f32_e32 v197, v197
	v_rcp_f32_e32 v198, v198
	v_rcp_f32_e32 v199, v199
	v_pk_mul_f32 v[188:189], v[188:189], v[196:197]
	v_pk_mul_f32 v[190:191], v[190:191], v[198:199]
	v_pk_mul_f32 v[188:189], v[188:189], v[192:193]
	v_pk_mul_f32 v[190:191], v[190:191], v[194:195]
	v_cvt_pk_bf16_f32 v124, v188, v189
	v_cvt_pk_bf16_f32 v125, v190, v191
	v_add_u32_e32 v213, 0x108000, v215
	global_store_dwordx4 v213, v[122:125], s[96:97]
	v_pk_fma_f32 v[188:189], v[4:5], v[134:135], v[130:131]
	v_pk_fma_f32 v[190:191], v[6:7], v[136:137], v[132:133]
	v_pk_fma_f32 v[192:193], v[0:1], v[204:205], v[208:209]
	v_pk_fma_f32 v[194:195], v[2:3], v[206:207], v[210:211]
	v_fmac_f32_dpp v188, v4, v142 row_shr:1 row_mask:0xf bank_mask:0xf
	v_fmac_f32_dpp v189, v5, v143 row_shr:1 row_mask:0xf bank_mask:0xf
	v_fmac_f32_dpp v190, v6, v144 row_shr:1 row_mask:0xf bank_mask:0xf
	v_fmac_f32_dpp v191, v7, v145 row_shr:1 row_mask:0xf bank_mask:0xf
	v_fmac_f32_dpp v192, v0, v110 row_shr:1 row_mask:0xf bank_mask:0xf
	v_fmac_f32_dpp v193, v1, v111 row_shr:1 row_mask:0xf bank_mask:0xf
	v_fmac_f32_dpp v194, v2, v112 row_shr:1 row_mask:0xf bank_mask:0xf
	v_fmac_f32_dpp v195, v3, v113 row_shr:1 row_mask:0xf bank_mask:0xf
	v_fmac_f32_dpp v188, v4, v154 row_shr:2 row_mask:0xf bank_mask:0xf
	v_fmac_f32_dpp v189, v5, v155 row_shr:2 row_mask:0xf bank_mask:0xf
	v_fmac_f32_dpp v190, v6, v156 row_shr:2 row_mask:0xf bank_mask:0xf
	v_fmac_f32_dpp v191, v7, v157 row_shr:2 row_mask:0xf bank_mask:0xf
	v_fmac_f32_dpp v192, v0, v118 row_shr:2 row_mask:0xf bank_mask:0xf
	v_fmac_f32_dpp v193, v1, v119 row_shr:2 row_mask:0xf bank_mask:0xf
	v_fmac_f32_dpp v194, v2, v120 row_shr:2 row_mask:0xf bank_mask:0xf
	v_fmac_f32_dpp v195, v3, v121 row_shr:2 row_mask:0xf bank_mask:0xf
	v_fmac_f32_dpp v188, v20, v142 row_shl:15 row_mask:0xf bank_mask:0xf
	v_fmac_f32_dpp v189, v21, v143 row_shl:15 row_mask:0xf bank_mask:0xf
	v_fmac_f32_dpp v190, v22, v144 row_shl:15 row_mask:0xf bank_mask:0xf
	v_fmac_f32_dpp v191, v23, v145 row_shl:15 row_mask:0xf bank_mask:0xf
	v_fmac_f32_dpp v192, v8, v110 row_shl:15 row_mask:0xf bank_mask:0xf
	v_fmac_f32_dpp v193, v9, v111 row_shl:15 row_mask:0xf bank_mask:0xf
	v_fmac_f32_dpp v194, v10, v112 row_shl:15 row_mask:0xf bank_mask:0xf
	v_fmac_f32_dpp v195, v11, v113 row_shl:15 row_mask:0xf bank_mask:0xf
	v_fmac_f32_dpp v188, v20, v154 row_shl:14 row_mask:0xf bank_mask:0xf
	v_fmac_f32_dpp v189, v21, v155 row_shl:14 row_mask:0xf bank_mask:0xf
	v_fmac_f32_dpp v190, v22, v156 row_shl:14 row_mask:0xf bank_mask:0xf
	v_fmac_f32_dpp v191, v23, v157 row_shl:14 row_mask:0xf bank_mask:0xf
	v_fmac_f32_dpp v192, v8, v118 row_shl:14 row_mask:0xf bank_mask:0xf
	v_fmac_f32_dpp v193, v9, v119 row_shl:14 row_mask:0xf bank_mask:0xf
	v_fmac_f32_dpp v194, v10, v120 row_shl:14 row_mask:0xf bank_mask:0xf
	v_fmac_f32_dpp v195, v11, v121 row_shl:14 row_mask:0xf bank_mask:0xf
	v_pk_mul_f32 v[196:197], v[188:189], v[216:217] op_sel_hi:[1,0]
	v_pk_mul_f32 v[198:199], v[190:191], v[216:217] op_sel_hi:[1,0]
	v_exp_f32_e32 v196, v196
	v_exp_f32_e32 v197, v197
	v_exp_f32_e32 v198, v198
	v_exp_f32_e32 v199, v199
	v_pk_add_f32 v[196:197], v[196:197], v[214:215] op_sel_hi:[1,0]
	v_pk_add_f32 v[198:199], v[198:199], v[214:215] op_sel_hi:[1,0]
	v_rcp_f32_e32 v196, v196
	v_rcp_f32_e32 v197, v197
	v_rcp_f32_e32 v198, v198
	v_rcp_f32_e32 v199, v199
	v_pk_mul_f32 v[188:189], v[188:189], v[196:197]
	v_pk_mul_f32 v[190:191], v[190:191], v[198:199]
	v_pk_mul_f32 v[188:189], v[188:189], v[192:193]
	v_pk_mul_f32 v[190:191], v[190:191], v[194:195]
	v_cvt_pk_bf16_f32 v116, v188, v189
	v_cvt_pk_bf16_f32 v117, v190, v191
	v_add_u32_e32 v213, 0x134000, v215
	global_store_dwordx4 v213, v[114:117], s[96:97]
	s_add_i32 s98, s98, 1
	s_branch .LBB0_836
